# v17 + LRU-A/B: each gate group's four weight ds_read_b128 issued right after the previous group's last MFMA (one transcendental block ahead) instead of 3-20 instructions before use
# speedup vs baseline: 1.0124x; 1.0016x over previous
; #define LAS __attribute__((address_space(3)))
; __device__ __forceinline__ unsigned pk2(float lo, float hi) { return f2bf(lo) | (f2bf(hi) << 16); }
; template <bool PHASE_B>
; __device__ __forceinline__ void lru_item(const Params& p, LAS unsigned char* lds, int ci, int ci_next, int jb, const int tid, v4u (&xvn)[3]) {
;     ...
;     const LAS float* CW = (const LAS float*)(lds + LR_CW); const LAS float* CB = (const LAS float*)(lds + LR_CB); const LAS float* GC = (const LAS float*)(lds + LR_GC);
;     bf16x8 af[2];
; #pragma unroll
;     for (int ks = 0; ks < 2; ++ks) { const int cb0 = 32 * ks + 8 * fq;
;         f32x4 s0 = *(const LAS f32x4*)(CB + cb0), s1 = *(const LAS f32x4*)(CB + cb0 + 4);
; #pragma unroll
;         for (int tap = 0; tap < 4; ++tap) { const v4u v = *(const LAS v4u*)(lds + LR_XR + (16 * rt + fr + tap) * 144 + cb0 * 2);
;             const f32x4 w0 = *(const LAS f32x4*)(CW + tap * 64 + cb0), w1 = *(const LAS f32x4*)(CW + tap * 64 + cb0 + 4);
;             s0 += (f32x4){bflo(v.x), bfhi(v.x), bflo(v.y), bfhi(v.y)} * w0; s1 += (f32x4){bflo(v.z), bfhi(v.z), bflo(v.w), bfhi(v.w)} * w1; }
;         v4u o; o.x = pk2(s0[0], s0[1]); o.y = pk2(s0[2], s0[3]); o.z = pk2(s1[0], s1[1]); o.w = pk2(s1[2], s1[3]);
;         af[ks] = __builtin_bit_cast(bf16x8, o); }
.LBB0_339:
	v_add_u32_e32 v1, v167, v157
	ds_read_b128 v[14:17], v165 offset:56832
	ds_read_b128 v[18:21], v165 offset:56848
	ds_read_b128 v[22:25], v1
	v_add_u32_e32 v31, v167, v166
	ds_read_b128 v[26:29], v31 offset:55808
	ds_read_b128 v[36:39], v31 offset:55824
	v_add_u32_e32 v50, 0xd800, v170
	v_add_u32_e32 v51, 0xdc00, v170
	s_waitcnt lgkmcnt(2)
	v_lshlrev_b32_e32 v40, 16, v22
	v_and_b32_e32 v41, 0xffff0000, v22
	v_lshlrev_b32_e32 v22, 16, v23
	v_and_b32_e32 v23, 0xffff0000, v23
	s_waitcnt lgkmcnt(1)
	v_pk_fma_f32 v[28:29], v[28:29], v[22:23], v[16:17]
	v_pk_fma_f32 v[26:27], v[26:27], v[40:41], v[14:15]
	v_lshlrev_b32_e32 v14, 16, v24
	v_and_b32_e32 v15, 0xffff0000, v24
	v_lshlrev_b32_e32 v16, 16, v25
	v_and_b32_e32 v17, 0xffff0000, v25
	s_waitcnt lgkmcnt(0)
	v_pk_fma_f32 v[38:39], v[38:39], v[16:17], v[20:21]
	v_pk_fma_f32 v[36:37], v[36:37], v[14:15], v[18:19]
	ds_read_b128 v[14:17], v1 offset:144
	ds_read_b128 v[18:21], v31 offset:56064
	ds_read_b128 v[22:25], v31 offset:56080
	v_add_u32_e32 v132, v173, v166
	s_and_b64 vcc, exec, s[6:7]
	s_waitcnt lgkmcnt(2)
	v_lshlrev_b32_e32 v40, 16, v14
	v_and_b32_e32 v41, 0xffff0000, v14
	v_lshlrev_b32_e32 v14, 16, v15
	v_and_b32_e32 v15, 0xffff0000, v15
	s_waitcnt lgkmcnt(1)
	v_pk_fma_f32 v[28:29], v[20:21], v[14:15], v[28:29]
	v_lshlrev_b32_e32 v14, 16, v16
	v_and_b32_e32 v15, 0xffff0000, v16
	v_lshlrev_b32_e32 v16, 16, v17
	v_and_b32_e32 v17, 0xffff0000, v17
	v_pk_fma_f32 v[26:27], v[18:19], v[40:41], v[26:27]
	s_waitcnt lgkmcnt(0)
	v_pk_fma_f32 v[38:39], v[24:25], v[16:17], v[38:39]
	v_pk_fma_f32 v[36:37], v[22:23], v[14:15], v[36:37]
	ds_read_b128 v[14:17], v1 offset:288
	ds_read_b128 v[18:21], v31 offset:56320
	ds_read_b128 v[22:25], v31 offset:56336
	s_waitcnt lgkmcnt(2)
	v_lshlrev_b32_e32 v40, 16, v14
	v_and_b32_e32 v41, 0xffff0000, v14
	v_lshlrev_b32_e32 v14, 16, v15
	v_and_b32_e32 v15, 0xffff0000, v15
	s_waitcnt lgkmcnt(1)
	v_pk_fma_f32 v[28:29], v[20:21], v[14:15], v[28:29]
	v_lshlrev_b32_e32 v14, 16, v16
	v_and_b32_e32 v15, 0xffff0000, v16
	v_lshlrev_b32_e32 v16, 16, v17
	v_and_b32_e32 v17, 0xffff0000, v17
	v_pk_fma_f32 v[26:27], v[18:19], v[40:41], v[26:27]
	s_waitcnt lgkmcnt(0)
	v_pk_fma_f32 v[36:37], v[22:23], v[14:15], v[36:37]
	v_pk_fma_f32 v[38:39], v[24:25], v[16:17], v[38:39]
	ds_read_b128 v[14:17], v1 offset:432
	ds_read_b128 v[18:21], v31 offset:56576
	ds_read_b128 v[22:25], v31 offset:56592
	s_waitcnt lgkmcnt(2)
	v_lshlrev_b32_e32 v40, 16, v14
	v_and_b32_e32 v41, 0xffff0000, v14
	v_lshlrev_b32_e32 v14, 16, v15
	v_and_b32_e32 v15, 0xffff0000, v15
	s_waitcnt lgkmcnt(1)
	v_pk_fma_f32 v[20:21], v[20:21], v[14:15], v[28:29]
	v_pk_fma_f32 v[14:15], v[18:19], v[40:41], v[26:27]
	v_lshlrev_b32_e32 v18, 16, v16
	v_bfe_u32 v1, v14, 16, 1
	v_add3_u32 v1, v14, v1, s33
	v_bfe_u32 v14, v15, 16, 1
	v_lshrrev_b32_e32 v1, 16, v1
	v_add3_u32 v14, v15, v14, s33
	v_and_or_b32 v14, v14, s11, v1
	v_and_b32_e32 v19, 0xffff0000, v16
	v_lshlrev_b32_e32 v16, 16, v17
	v_and_b32_e32 v17, 0xffff0000, v17
	s_waitcnt lgkmcnt(0)
	v_pk_fma_f32 v[24:25], v[24:25], v[16:17], v[38:39]
	v_pk_fma_f32 v[16:17], v[22:23], v[18:19], v[36:37]
	v_cvt_pk_bf16_f32 v15, v20, v21
	v_bfe_u32 v1, v16, 16, 1
	v_add3_u32 v1, v16, v1, s33
	v_bfe_u32 v16, v17, 16, 1
	v_lshrrev_b32_e32 v1, 16, v1
	v_add3_u32 v16, v17, v16, s33
	v_and_or_b32 v16, v16, s11, v1
	v_bfe_u32 v1, v24, 16, 1
	v_bfe_u32 v17, v25, 16, 1
	v_add3_u32 v1, v24, v1, s33
	v_add3_u32 v17, v25, v17, s33
	ds_read_b128 v[18:21], v31 offset:56960
	ds_read_b128 v[22:25], v31 offset:56976
	ds_read_b128 v[26:29], v198
	ds_read_b128 v[36:39], v31 offset:55936
	ds_read_b128 v[40:43], v31 offset:55952
	v_lshrrev_b32_e32 v1, 16, v1
	v_and_or_b32 v17, v17, s11, v1
	s_waitcnt lgkmcnt(2)
	v_lshlrev_b32_e32 v44, 16, v26
	v_and_b32_e32 v45, 0xffff0000, v26
	v_lshlrev_b32_e32 v26, 16, v27
	v_and_b32_e32 v27, 0xffff0000, v27
	s_waitcnt lgkmcnt(1)
	v_pk_fma_f32 v[38:39], v[38:39], v[26:27], v[20:21]
	v_pk_fma_f32 v[36:37], v[36:37], v[44:45], v[18:19]
	v_lshlrev_b32_e32 v18, 16, v28
	v_and_b32_e32 v19, 0xffff0000, v28
	v_lshlrev_b32_e32 v20, 16, v29
	v_and_b32_e32 v21, 0xffff0000, v29
	s_waitcnt lgkmcnt(0)
	v_pk_fma_f32 v[42:43], v[42:43], v[20:21], v[24:25]
	v_pk_fma_f32 v[40:41], v[40:41], v[18:19], v[22:23]
	ds_read_b128 v[18:21], v198 offset:144
	ds_read_b128 v[22:25], v31 offset:56192
	ds_read_b128 v[26:29], v31 offset:56208
	s_waitcnt lgkmcnt(2)
	v_lshlrev_b32_e32 v44, 16, v18
	v_and_b32_e32 v45, 0xffff0000, v18
	v_lshlrev_b32_e32 v18, 16, v19
	v_and_b32_e32 v19, 0xffff0000, v19
	s_waitcnt lgkmcnt(1)
	v_pk_fma_f32 v[38:39], v[24:25], v[18:19], v[38:39]
	v_lshlrev_b32_e32 v18, 16, v20
	v_and_b32_e32 v19, 0xffff0000, v20
	v_lshlrev_b32_e32 v20, 16, v21
	v_and_b32_e32 v21, 0xffff0000, v21
	v_pk_fma_f32 v[36:37], v[22:23], v[44:45], v[36:37]
	s_waitcnt lgkmcnt(0)
	v_pk_fma_f32 v[42:43], v[28:29], v[20:21], v[42:43]
	v_pk_fma_f32 v[40:41], v[26:27], v[18:19], v[40:41]
	ds_read_b128 v[18:21], v198 offset:288
	ds_read_b128 v[22:25], v31 offset:56448
	ds_read_b128 v[26:29], v31 offset:56464
	s_waitcnt lgkmcnt(2)
	v_lshlrev_b32_e32 v44, 16, v18
	v_and_b32_e32 v45, 0xffff0000, v18
	v_lshlrev_b32_e32 v18, 16, v19
	v_and_b32_e32 v19, 0xffff0000, v19
	s_waitcnt lgkmcnt(1)
	v_pk_fma_f32 v[38:39], v[24:25], v[18:19], v[38:39]
	v_lshlrev_b32_e32 v18, 16, v20
	v_and_b32_e32 v19, 0xffff0000, v20
	v_lshlrev_b32_e32 v20, 16, v21
	v_and_b32_e32 v21, 0xffff0000, v21
	v_pk_fma_f32 v[36:37], v[22:23], v[44:45], v[36:37]
	s_waitcnt lgkmcnt(0)
	v_pk_fma_f32 v[42:43], v[28:29], v[20:21], v[42:43]
	v_pk_fma_f32 v[40:41], v[26:27], v[18:19], v[40:41]
	ds_read_b128 v[18:21], v198 offset:432
	ds_read_b128 v[22:25], v31 offset:56704
	ds_read_b128 v[26:29], v31 offset:56720
	s_waitcnt lgkmcnt(2)
; #define LAS __attribute__((address_space(3)))
; template <bool PHASE_B>
; __device__ __forceinline__ void lru_item(const Params& p, LAS unsigned char* lds, int ci, int ci_next, int jb, const int tid, v4u (&xvn)[3]) {
;     ...
;     float xc[4][4];
; #pragma unroll
;     for (int ct = 0; ct < 4; ++ct) { const int ch = 16 * ct + fr; float xr7[7];
; #pragma unroll
;         for (int j = 0; j < 7; ++j) xr7[j] = __builtin_bit_cast(float, (unsigned)(*(const LAS bf16*)(lds + LR_XR + (16 * rt + 4 * fq + j) * 144 + ch * 2)) << 16);
;         const float w0 = CW[ch], w1 = CW[64 + ch], w2 = CW[128 + ch], w3 = CW[192 + ch], b = CB[ch];
; #pragma unroll
;         for (int e = 0; e < 4; ++e) xc[ct][e] = b + xr7[e] * w0 + xr7[e + 1] * w1 + xr7[e + 2] * w2 + xr7[e + 3] * w3; }
	v_lshlrev_b32_e32 v44, 16, v18
	v_and_b32_e32 v45, 0xffff0000, v18
	v_lshlrev_b32_e32 v18, 16, v19
	v_and_b32_e32 v19, 0xffff0000, v19
	s_waitcnt lgkmcnt(1)
	v_pk_fma_f32 v[24:25], v[24:25], v[18:19], v[38:39]
	v_pk_fma_f32 v[18:19], v[22:23], v[44:45], v[36:37]
	v_lshlrev_b32_e32 v22, 16, v20
	v_bfe_u32 v1, v18, 16, 1
	v_add3_u32 v1, v18, v1, s33
	v_bfe_u32 v18, v19, 16, 1
	v_lshrrev_b32_e32 v1, 16, v1
	v_add3_u32 v18, v19, v18, s33
	v_and_or_b32 v18, v18, s11, v1
	v_and_b32_e32 v23, 0xffff0000, v20
	v_lshlrev_b32_e32 v20, 16, v21
	v_and_b32_e32 v21, 0xffff0000, v21
	s_waitcnt lgkmcnt(0)
	v_pk_fma_f32 v[28:29], v[28:29], v[20:21], v[42:43]
	v_pk_fma_f32 v[20:21], v[26:27], v[22:23], v[40:41]
	v_cvt_pk_bf16_f32 v19, v24, v25
	v_bfe_u32 v1, v20, 16, 1
	v_add3_u32 v1, v20, v1, s33
	v_bfe_u32 v20, v21, 16, 1
	v_lshrrev_b32_e32 v1, 16, v1
	v_add3_u32 v20, v21, v20, s33
	v_and_or_b32 v20, v20, s11, v1
	v_cvt_pk_bf16_f32 v21, v28, v29
	v_add_u32_e32 v1, v168, v169
	ds_read_u16 v22, v1
	s_waitcnt lgkmcnt(0)
	v_lshlrev_b32_e32 v23, 16, v22
	ds_read_u16 v22, v1 offset:144
	ds_read_u16 v31, v1 offset:288
	ds_read_u16 v38, v1 offset:432
	ds_read_u16 v39, v1 offset:576
	ds_read_u16 v46, v1 offset:720
	ds_read_u16 v1, v1 offset:864
	ds_read2_b32 v[24:25], v50 offset0:128 offset1:144
	ds_read2_b32 v[26:27], v50 offset0:192 offset1:208
	ds_read2_b32 v[28:29], v51 offset1:16
	ds_read2_b32 v[36:37], v51 offset0:64 offset1:80
	ds_read2_b32 v[40:41], v51 offset0:128 offset1:144
	s_waitcnt lgkmcnt(10)
	v_lshlrev_b32_e32 v45, 16, v22
	s_waitcnt lgkmcnt(8)
	v_lshlrev_b32_e32 v43, 16, v38
	s_waitcnt lgkmcnt(7)
	v_lshlrev_b32_e32 v42, 16, v39
	s_waitcnt lgkmcnt(3)
	v_mov_b32_e32 v38, v26
	v_mov_b32_e32 v39, v24
	v_mov_b32_e32 v22, v45
	v_pk_mul_f32 v[22:23], v[38:39], v[22:23]
	v_lshlrev_b32_e32 v44, 16, v31
	s_waitcnt lgkmcnt(0)
	v_add_f32_e32 v23, v23, v40
	v_add_f32_e32 v24, v22, v23
	v_pk_mul_f32 v[22:23], v[38:39], v[44:45]
	v_mov_b32_e32 v47, v28
	v_add_f32_e32 v23, v23, v40
	v_add_f32_e32 v26, v22, v23
	v_pk_mov_b32 v[22:23], v[42:43], v[44:45] op_sel:[1,0]
	s_nop 0
	v_pk_mul_f32 v[44:45], v[38:39], v[22:23]
	v_pk_mul_f32 v[38:39], v[38:39], v[42:43]
	v_add_f32_e32 v31, v45, v40
	v_lshlrev_b32_e32 v45, 16, v46
	v_mov_b32_e32 v46, v36
	v_pk_mul_f32 v[48:49], v[46:47], v[22:23]
	v_pk_mul_f32 v[22:23], v[46:47], v[42:43]
	v_add_f32_e32 v31, v44, v31
	v_lshlrev_b32_e32 v44, 16, v1
	v_add_f32_e32 v1, v23, v26
	v_add_f32_e32 v108, v22, v1
	v_pk_mov_b32 v[22:23], v[44:45], v[42:43] op_sel:[1,0]
	v_add_f32_e32 v39, v39, v40
	v_pk_mul_f32 v[22:23], v[46:47], v[22:23]
	v_add_f32_e32 v38, v38, v39
	v_add_f32_e32 v1, v23, v31
	v_add_f32_e32 v106, v22, v1
	v_pk_mul_f32 v[22:23], v[46:47], v[44:45]
	v_add_f32_e32 v39, v49, v24
	v_add_f32_e32 v1, v23, v38
	v_add_f32_e32 v101, v22, v1
	ds_read_u16 v1, v199
	v_add_f32_e32 v110, v48, v39
	s_waitcnt lgkmcnt(0)
	v_lshlrev_b32_e32 v23, 16, v1
	ds_read_u16 v1, v199 offset:144
	ds_read_u16 v22, v199 offset:288
	ds_read_u16 v24, v199 offset:432
	ds_read_u16 v26, v199 offset:576
	ds_read_u16 v28, v199 offset:720
	ds_read_u16 v31, v199 offset:864
	s_waitcnt lgkmcnt(3)
	v_lshlrev_b32_e32 v43, 16, v24
	v_mov_b32_e32 v24, v27
	v_lshlrev_b32_e32 v27, 16, v1
	s_waitcnt lgkmcnt(2)
	v_lshlrev_b32_e32 v42, 16, v26
	v_lshlrev_b32_e32 v26, 16, v22
	v_mov_b32_e32 v22, v27
	v_pk_mul_f32 v[22:23], v[24:25], v[22:23]
	s_nop 0
	v_add_f32_e32 v1, v23, v41
	v_add_f32_e32 v1, v22, v1
	v_pk_mul_f32 v[22:23], v[24:25], v[26:27]
	s_nop 0
	v_add_f32_e32 v23, v23, v41
	v_add_f32_e32 v36, v22, v23
	v_pk_mov_b32 v[22:23], v[42:43], v[26:27] op_sel:[1,0]
	s_nop 0
	v_pk_mul_f32 v[26:27], v[24:25], v[22:23]
	v_pk_mul_f32 v[24:25], v[24:25], v[42:43]
	v_add_f32_e32 v27, v27, v41
	v_add_f32_e32 v25, v25, v41
	v_add_f32_e32 v26, v26, v27
	v_add_f32_e32 v27, v24, v25
	s_waitcnt lgkmcnt(1)
	v_lshlrev_b32_e32 v25, 16, v28
	v_mov_b32_e32 v28, v37
	v_pk_mul_f32 v[64:65], v[28:29], v[22:23]
	v_pk_mul_f32 v[22:23], v[28:29], v[42:43]
	s_waitcnt lgkmcnt(0)
	v_lshlrev_b32_e32 v24, 16, v31
	v_add_f32_e32 v57, v65, v1
	v_add_f32_e32 v1, v23, v36
	v_add_f32_e32 v120, v22, v1
	v_pk_mov_b32 v[22:23], v[24:25], v[42:43] op_sel:[1,0]
	v_add_f32_e32 v122, v64, v57
	v_pk_mul_f32 v[22:23], v[28:29], v[22:23]
	s_nop 0
	v_add_f32_e32 v1, v23, v26
	v_add_f32_e32 v118, v22, v1
	v_pk_mul_f32 v[22:23], v[28:29], v[24:25]
	s_nop 0
	v_add_f32_e32 v1, v23, v27
	v_add_f32_e32 v113, v22, v1
	ds_read_u16 v1, v200
	s_waitcnt lgkmcnt(0)
	v_lshlrev_b32_e32 v23, 16, v1
	ds_read_u16 v1, v200 offset:144
	ds_read_u16 v22, v200 offset:288
	ds_read_u16 v31, v200 offset:432
	ds_read_u16 v38, v200 offset:576
	ds_read_u16 v49, v200 offset:720
	ds_read_u16 v52, v200 offset:864
	ds_read2_b32 v[24:25], v50 offset0:160 offset1:176
	ds_read2_b32 v[26:27], v50 offset0:224 offset1:240
	ds_read2_b32 v[28:29], v51 offset0:32 offset1:48
	ds_read2_b32 v[36:37], v51 offset0:96 offset1:112
	ds_read2_b32 v[40:41], v51 offset0:160 offset1:176
	s_waitcnt lgkmcnt(10)
	v_lshlrev_b32_e32 v47, 16, v1
	s_waitcnt lgkmcnt(3)
	v_mov_b32_e32 v44, v26
	v_mov_b32_e32 v45, v24
	v_lshlrev_b32_e32 v46, 16, v22
	v_mov_b32_e32 v22, v47
	v_pk_mul_f32 v[22:23], v[44:45], v[22:23]
	v_lshlrev_b32_e32 v43, 16, v31
	s_waitcnt lgkmcnt(0)
; #define LAS __attribute__((address_space(3)))
; #define MFMA16(a, b, c) __builtin_amdgcn_mfma_f32_16x16x32_bf16(a, b, c, 0, 0, 0)
; template <bool PHASE_B>
; __device__ __forceinline__ void lru_item(const Params& p, LAS unsigned char* lds, int ci, int ci_next, int jb, const int tid, v4u (&xvn)[3]) {
;     ...
;     for (int dir = 0; dir < 2; ++dir) {
; #pragma unroll
;         for (int ct = 0; ct < 4; ++ct) {
;             f32x4 ga = (f32x4){0.f, 0.f, 0.f, 0.f}, gx = (f32x4){0.f, 0.f, 0.f, 0.f};
; #pragma unroll
;             for (int ks = 0; ks < 2; ++ks) {
;                 const bf16x8 wa = *(const LAS bf16x8*)(lds + LR_WG + ((dir * 2 + 0) * 64 + 16 * ct + fr) * 144 + (32 * ks + 8 * fq) * 2);
;                 const bf16x8 wx = *(const LAS bf16x8*)(lds + LR_WG + ((dir * 2 + 1) * 64 + 16 * ct + fr) * 144 + (32 * ks + 8 * fq) * 2);
;                 ga = MFMA16(af[ks], wa, ga); gx = MFMA16(af[ks], wx, gx); }
;             const int ch = 16 * ct + fr; const float bav = GC[(dir * 3 + 0) * 64 + ch], bxv = GC[(dir * 3 + 1) * 64 + ch], c8 = GC[(dir * 3 + 2) * 64 + ch];
;             float Al = 1.f, Hl = 0.f;
; #pragma unroll
;             for (int ee = 0; ee < 4; ++ee) { const int e = dir ? 3 - ee : ee;
;                 const float r = __builtin_amdgcn_rcpf(1.f + __expf(-(ga[e] + bav))), ig = __builtin_amdgcn_rcpf(1.f + __expf(-(gx[e] + bxv)));
;                 const float la = -c8 * r; const float a = __expf(la); const float u = __builtin_amdgcn_sqrtf((1.f - a) * (1.f + a)) * (ig * xc[ct][e]);
;                 av[dir][ct][e] = a; uv[dir][ct][e] = u; Hl = a * Hl + u; Al *= a; }
	v_add_f32_e32 v1, v23, v40
	v_add_f32_e32 v1, v22, v1
	v_pk_mul_f32 v[22:23], v[44:45], v[46:47]
	v_lshlrev_b32_e32 v42, 16, v38
	v_add_f32_e32 v23, v23, v40
	v_add_f32_e32 v24, v22, v23
	v_pk_mov_b32 v[22:23], v[42:43], v[46:47] op_sel:[1,0]
	v_mov_b32_e32 v50, v36
	v_pk_mul_f32 v[46:47], v[44:45], v[22:23]
	v_pk_mul_f32 v[44:45], v[44:45], v[42:43]
	v_mov_b32_e32 v51, v28
	v_add_f32_e32 v31, v45, v40
	v_add_f32_e32 v26, v47, v40
	v_add_f32_e32 v31, v44, v31
	v_pk_mul_f32 v[44:45], v[50:51], v[22:23]
	v_pk_mul_f32 v[22:23], v[50:51], v[42:43]
	v_add_f32_e32 v26, v46, v26
	v_lshlrev_b32_e32 v47, 16, v49
	v_lshlrev_b32_e32 v46, 16, v52
	v_add_f32_e32 v45, v45, v1
	v_add_f32_e32 v1, v23, v24
	v_add_f32_e32 v130, v22, v1
	v_pk_mov_b32 v[22:23], v[46:47], v[42:43] op_sel:[1,0]
	s_nop 0
	v_pk_mul_f32 v[22:23], v[50:51], v[22:23]
	s_nop 0
	v_add_f32_e32 v1, v23, v26
	v_add_f32_e32 v128, v22, v1
	v_pk_mul_f32 v[22:23], v[50:51], v[46:47]
	s_nop 0
	v_add_f32_e32 v1, v23, v31
	v_add_f32_e32 v125, v22, v1
	ds_read_u16 v1, v201
	s_waitcnt lgkmcnt(0)
	v_lshlrev_b32_e32 v23, 16, v1
	ds_read_u16 v1, v201 offset:144
	ds_read_u16 v22, v201 offset:288
	ds_read_u16 v24, v201 offset:432
	ds_read_u16 v26, v201 offset:576
	ds_read_u16 v28, v201 offset:720
	ds_read_u16 v31, v201 offset:864
	s_waitcnt lgkmcnt(3)
	v_lshlrev_b32_e32 v43, 16, v24
	v_mov_b32_e32 v24, v27
	v_lshlrev_b32_e32 v27, 16, v1
	s_waitcnt lgkmcnt(2)
	v_lshlrev_b32_e32 v42, 16, v26
	v_lshlrev_b32_e32 v26, 16, v22
	v_mov_b32_e32 v22, v27
	v_pk_mul_f32 v[22:23], v[24:25], v[22:23]
	s_nop 0
	v_add_f32_e32 v1, v23, v41
	v_add_f32_e32 v1, v22, v1
	v_pk_mul_f32 v[22:23], v[24:25], v[26:27]
	s_nop 0
	v_add_f32_e32 v23, v23, v41
	v_add_f32_e32 v38, v22, v23
	v_pk_mov_b32 v[22:23], v[42:43], v[26:27] op_sel:[1,0]
	s_nop 0
	v_pk_mul_f32 v[26:27], v[24:25], v[22:23]
	v_pk_mul_f32 v[24:25], v[24:25], v[42:43]
	v_add_f32_e32 v27, v27, v41
	v_add_f32_e32 v25, v25, v41
	v_add_f32_e32 v26, v26, v27
	v_add_f32_e32 v27, v24, v25
	s_waitcnt lgkmcnt(1)
	v_lshlrev_b32_e32 v25, 16, v28
	v_mov_b32_e32 v28, v37
	v_pk_mul_f32 v[36:37], v[28:29], v[22:23]
	v_pk_mul_f32 v[22:23], v[28:29], v[42:43]
	s_waitcnt lgkmcnt(0)
	v_lshlrev_b32_e32 v24, 16, v31
	v_add_f32_e32 v37, v37, v1
	v_add_f32_e32 v1, v23, v38
	v_add_f32_e32 v31, v22, v1
	v_pk_mov_b32 v[22:23], v[24:25], v[42:43] op_sel:[1,0]
	s_nop 0
	v_pk_mul_f32 v[22:23], v[28:29], v[22:23]
	s_nop 0
	v_add_f32_e32 v1, v23, v26
	v_add_f32_e32 v136, v22, v1
	v_pk_mul_f32 v[22:23], v[28:29], v[24:25]
	s_nop 0
	v_add_f32_e32 v1, v23, v27
	v_add_f32_e32 v133, v22, v1
	ds_read_b128 v[22:25], v132 offset:18944
	ds_read_b128 v[26:29], v132 offset:28160
	s_waitcnt lgkmcnt(1)
	v_mfma_f32_16x16x32_bf16 v[22:25], v[14:17], v[22:25], 0
	s_waitcnt lgkmcnt(0)
	v_mfma_f32_16x16x32_bf16 v[40:43], v[14:17], v[26:29], 0
	ds_read_b128 v[26:29], v132 offset:19008
	ds_read_b128 v[50:53], v132 offset:28224
	ds_read_b32 v49, v174 offset:57088
	ds_read_b32 v47, v174 offset:57344
	ds_read_b32 v46, v174 offset:57600
	s_waitcnt lgkmcnt(4)
	v_mfma_f32_16x16x32_bf16 v[26:29], v[18:21], v[26:29], v[22:25]
	s_waitcnt lgkmcnt(3)
	v_mfma_f32_16x16x32_bf16 v[22:25], v[18:21], v[50:53], v[40:43]
	ds_read_b128 v[208:211], v132 offset:21248
	ds_read_b128 v[212:215], v132 offset:30464
	ds_read_b128 v[216:219], v132 offset:21312
	ds_read_b128 v[220:223], v132 offset:30528
	s_waitcnt lgkmcnt(2)
	s_nop 4
	v_add_f32_e32 v1, v26, v49
	v_mul_f32_e32 v1, 0xbfb8aa3b, v1
	v_exp_f32_e32 v1, v1
	s_nop 0
	v_add_f32_e32 v1, 1.0, v1
	v_rcp_f32_e32 v1, v1
	s_waitcnt lgkmcnt(1)
	v_add_f32_e32 v22, v22, v47
	v_mul_f32_e32 v22, 0xbfb8aa3b, v22
	v_exp_f32_e32 v22, v22
	s_waitcnt lgkmcnt(0)
	v_mul_f32_e32 v1, v1, v46
	v_mul_f32_e32 v1, 0xbfb8aa3b, v1
	v_exp_f32_e32 v38, v1
	v_add_f32_e32 v22, 1.0, v22
	v_rcp_f32_e32 v50, v22
	v_add_f32_e32 v23, v23, v47
	v_sub_f32_e32 v1, 1.0, v38
	v_add_f32_e32 v22, 1.0, v38
	v_mul_f32_e32 v1, v1, v22
	v_add_f32_e32 v22, v27, v49
	v_mul_f32_e32 v22, 0xbfb8aa3b, v22
	v_exp_f32_e32 v22, v22
	v_mul_f32_e32 v23, 0xbfb8aa3b, v23
	v_exp_f32_e32 v23, v23
	v_add_f32_e32 v24, v24, v47
	v_add_f32_e32 v22, 1.0, v22
	v_rcp_f32_e32 v22, v22
	v_add_f32_e32 v23, 1.0, v23
	v_rcp_f32_e32 v23, v23
	v_add_f32_e32 v25, v25, v47
	v_mul_f32_e32 v22, v22, v46
	v_mul_f32_e32 v22, 0xbfb8aa3b, v22
	v_exp_f32_e32 v41, v22
	v_mul_f32_e32 v24, 0xbfb8aa3b, v24
	v_mul_f32_e32 v25, 0xbfb8aa3b, v25
	v_sqrt_f32_e32 v1, v1
	v_sub_f32_e32 v22, 1.0, v41
	v_add_f32_e32 v26, 1.0, v41
	v_mul_f32_e32 v22, v22, v26
	v_add_f32_e32 v26, v28, v49
	v_mul_f32_e32 v26, 0xbfb8aa3b, v26
	v_exp_f32_e32 v26, v26
	v_sqrt_f32_e32 v40, v22
	v_mul_f32_e32 v22, v108, v23
	v_mul_f32_e32 v23, v38, v41
	v_add_f32_e32 v26, 1.0, v26
	v_rcp_f32_e32 v26, v26
	v_exp_f32_e32 v24, v24
	v_exp_f32_e32 v25, v25
	v_mul_f32_e32 v39, v110, v50
	v_mul_f32_e32 v26, v26, v46
	v_mul_f32_e32 v26, 0xbfb8aa3b, v26
	v_exp_f32_e32 v43, v26
	v_add_f32_e32 v24, 1.0, v24
	v_add_f32_e32 v25, 1.0, v25
	v_rcp_f32_e32 v24, v24
	v_sub_f32_e32 v26, 1.0, v43
	v_add_f32_e32 v27, 1.0, v43
	v_mul_f32_e32 v26, v26, v27
	v_sqrt_f32_e32 v42, v26
	v_add_f32_e32 v26, v29, v49
	v_mul_f32_e32 v26, 0xbfb8aa3b, v26
	v_exp_f32_e32 v26, v26
	v_mul_f32_e32 v23, v43, v23
	v_pk_mul_f32 v[48:49], v[38:39], v[0:1]
	v_rcp_f32_e32 v25, v25
	v_add_f32_e32 v26, 1.0, v26
	v_rcp_f32_e32 v26, v26
	v_pk_fma_f32 v[50:51], v[38:39], v[0:1], v[48:49] op_sel_hi:[1,1,0]
	v_mul_f32_e32 v24, v106, v24
	v_mul_f32_e32 v26, v26, v46
	v_mul_f32_e32 v26, 0xbfb8aa3b, v26
	v_exp_f32_e32 v47, v26
	s_nop 0
	v_mul_f32_e32 v29, v47, v23
	ds_bpermute_b32 v56, v171, v29
	v_sub_f32_e32 v26, 1.0, v47
	v_add_f32_e32 v27, 1.0, v47
	v_mul_f32_e32 v26, v26, v27
	v_sqrt_f32_e32 v46, v26
	s_waitcnt lgkmcnt(0)
; #define LAS __attribute__((address_space(3)))
; #define MFMA16(a, b, c) __builtin_amdgcn_mfma_f32_16x16x32_bf16(a, b, c, 0, 0, 0)
; template <bool PHASE_B>
; __device__ __forceinline__ void lru_item(const Params& p, LAS unsigned char* lds, int ci, int ci_next, int jb, const int tid, v4u (&xvn)[3]) {
;     ...
;         for (int ct = 0; ct < 4; ++ct) {
;             f32x4 ga = (f32x4){0.f, 0.f, 0.f, 0.f}, gx = (f32x4){0.f, 0.f, 0.f, 0.f};
; #pragma unroll
;             for (int ks = 0; ks < 2; ++ks) {
;                 const bf16x8 wa = *(const LAS bf16x8*)(lds + LR_WG + ((dir * 2 + 0) * 64 + 16 * ct + fr) * 144 + (32 * ks + 8 * fq) * 2);
;                 const bf16x8 wx = *(const LAS bf16x8*)(lds + LR_WG + ((dir * 2 + 1) * 64 + 16 * ct + fr) * 144 + (32 * ks + 8 * fq) * 2);
;                 ga = MFMA16(af[ks], wa, ga); gx = MFMA16(af[ks], wx, gx); }
;             const int ch = 16 * ct + fr; const float bav = GC[(dir * 3 + 0) * 64 + ch], bxv = GC[(dir * 3 + 1) * 64 + ch], c8 = GC[(dir * 3 + 2) * 64 + ch];
;             float Al = 1.f, Hl = 0.f;
; #pragma unroll
;             for (int ee = 0; ee < 4; ++ee) { const int e = dir ? 3 - ee : ee;
;                 const float r = __builtin_amdgcn_rcpf(1.f + __expf(-(ga[e] + bav))), ig = __builtin_amdgcn_rcpf(1.f + __expf(-(gx[e] + bxv)));
;                 const float la = -c8 * r; const float a = __expf(la); const float u = __builtin_amdgcn_sqrtf((1.f - a) * (1.f + a)) * (ig * xc[ct][e]);
;                 av[dir][ct][e] = a; uv[dir][ct][e] = u; Hl = a * Hl + u; Al *= a; }
;             const int o = dir ? 3 - fq : fq; const bool odd = (o & 1) != 0, hi2 = (o & 2) != 0;
;             const float A1 = __shfl_xor(Al, 16), H1 = __shfl_xor(Hl, 16);
;             const float pxA = odd ? A1 : 1.f, pxH = odd ? H1 : 0.f;
;             const float gA = Al * A1, gH = odd ? (Al * H1 + Hl) : (A1 * Hl + H1);
;             const float A2 = __shfl_xor(gA, 32), H2 = __shfl_xor(gH, 32);
;             const float PA = hi2 ? pxA * A2 : pxA, PH = hi2 ? (pxA * H2 + pxH) : pxH;
;             const float TA = gA * A2, TH = hi2 ? (gA * H2 + gH) : (A2 * gH + H2);
;             pA[dir][ct] = PA; pH[dir][ct] = PH;
;             ((LAS f32x2*)(lds + LR_SEG))[(dir * 8 + rt) * 64 + ch] = (f32x2){TA, TH};
	v_mul_f32_e32 v59, v29, v56
	ds_bpermute_b32 v60, v172, v59
	v_cndmask_b32_e64 v58, v56, 1.0, s[50:51]
	v_mul_f32_e32 v26, v101, v25
	s_waitcnt lgkmcnt(0)
	v_mul_f32_e32 v23, v58, v60
	v_cndmask_b32_e64 v206, v23, v58, s[52:53]
	v_mov_b32_e32 v23, v51
	v_pk_mul_f32 v[50:51], v[22:23], v[40:41]
	v_mul_f32_e32 v28, v59, v60
	v_pk_fma_f32 v[22:23], v[22:23], v[40:41], v[50:51] op_sel_hi:[1,1,0]
	s_nop 0
	v_mov_b32_e32 v25, v23
	v_pk_mul_f32 v[52:53], v[24:25], v[42:43]
	s_nop 0
	v_pk_fma_f32 v[22:23], v[24:25], v[42:43], v[52:53] op_sel_hi:[1,1,0]
	s_nop 0
	v_mov_b32_e32 v27, v23
	v_pk_mul_f32 v[54:55], v[26:27], v[46:47]
	s_nop 0
	v_add_f32_e32 v1, v54, v55
	ds_bpermute_b32 v22, v171, v1
	s_waitcnt lgkmcnt(0)
	v_cndmask_b32_e64 v23, v22, 0, s[50:51]
	v_fma_f32 v24, v29, v22, v1
	v_fmac_f32_e32 v22, v1, v56
	v_cndmask_b32_e64 v1, v24, v22, s[50:51]
	ds_bpermute_b32 v22, v172, v1
	s_waitcnt lgkmcnt(0)
	v_fma_f32 v24, v58, v22, v23
	v_cndmask_b32_e64 v39, v24, v23, s[52:53]
	v_fma_f32 v23, v59, v22, v1
	v_fmac_f32_e32 v22, v1, v60
	v_cndmask_b32_e64 v29, v23, v22, s[52:53]
	ds_write_b64 v175, v[28:29] offset:58624
	s_waitcnt lgkmcnt(1)
	v_mfma_f32_16x16x32_bf16 v[22:25], v[14:17], v[208:211], 0
	s_waitcnt lgkmcnt(0)
	v_mfma_f32_16x16x32_bf16 v[58:61], v[14:17], v[212:215], 0
	ds_read_b32 v40, v174 offset:57152
	ds_read_b32 v42, v174 offset:57408
	ds_read_b32 v46, v174 offset:57664
	s_waitcnt lgkmcnt(4)
	v_mfma_f32_16x16x32_bf16 v[26:29], v[18:21], v[216:219], v[22:25]
	s_waitcnt lgkmcnt(3)
	v_mfma_f32_16x16x32_bf16 v[22:25], v[18:21], v[220:223], v[58:61]
	ds_read_b128 v[208:211], v132 offset:23552
	ds_read_b128 v[212:215], v132 offset:32768
	ds_read_b128 v[216:219], v132 offset:23616
	ds_read_b128 v[220:223], v132 offset:32832
	s_waitcnt lgkmcnt(2)
	s_nop 4
	v_add_f32_e32 v1, v26, v40
	v_mul_f32_e32 v1, 0xbfb8aa3b, v1
	v_exp_f32_e32 v1, v1
	s_nop 0
	v_add_f32_e32 v1, 1.0, v1
	v_rcp_f32_e32 v1, v1
	s_waitcnt lgkmcnt(1)
	v_add_f32_e32 v22, v22, v42
	v_mul_f32_e32 v22, 0xbfb8aa3b, v22
	v_exp_f32_e32 v22, v22
	s_waitcnt lgkmcnt(0)
	v_mul_f32_e32 v1, v1, v46
	v_mul_f32_e32 v1, 0xbfb8aa3b, v1
	v_exp_f32_e32 v56, v1
	v_add_f32_e32 v22, 1.0, v22
	v_rcp_f32_e32 v48, v22
	v_add_f32_e32 v23, v23, v42
	v_sub_f32_e32 v1, 1.0, v56
	v_add_f32_e32 v22, 1.0, v56
	v_mul_f32_e32 v1, v1, v22
	v_add_f32_e32 v22, v27, v40
	v_mul_f32_e32 v22, 0xbfb8aa3b, v22
	v_exp_f32_e32 v22, v22
	v_mul_f32_e32 v23, 0xbfb8aa3b, v23
	v_exp_f32_e32 v23, v23
	v_add_f32_e32 v24, v24, v42
	v_add_f32_e32 v22, 1.0, v22
	v_rcp_f32_e32 v22, v22
	v_add_f32_e32 v23, 1.0, v23
	v_rcp_f32_e32 v23, v23
	v_add_f32_e32 v25, v25, v42
	v_mul_f32_e32 v22, v22, v46
	v_mul_f32_e32 v22, 0xbfb8aa3b, v22
	v_exp_f32_e32 v59, v22
	v_mul_f32_e32 v24, 0xbfb8aa3b, v24
	v_mul_f32_e32 v25, 0xbfb8aa3b, v25
	v_sqrt_f32_e32 v1, v1
	v_sub_f32_e32 v22, 1.0, v59
	v_add_f32_e32 v26, 1.0, v59
	v_mul_f32_e32 v22, v22, v26
	v_add_f32_e32 v26, v28, v40
	v_mul_f32_e32 v26, 0xbfb8aa3b, v26
	v_exp_f32_e32 v26, v26
	v_sqrt_f32_e32 v58, v22
	v_mul_f32_e32 v22, v120, v23
	v_mul_f32_e32 v23, v56, v59
	v_add_f32_e32 v26, 1.0, v26
	v_rcp_f32_e32 v26, v26
	v_exp_f32_e32 v24, v24
	v_exp_f32_e32 v25, v25
	v_mul_f32_e32 v57, v122, v48
	v_mul_f32_e32 v26, v26, v46
	v_mul_f32_e32 v26, 0xbfb8aa3b, v26
	v_exp_f32_e32 v61, v26
	v_add_f32_e32 v24, 1.0, v24
	v_add_f32_e32 v25, 1.0, v25
	v_pk_mul_f32 v[64:65], v[56:57], v[0:1]
	v_sub_f32_e32 v26, 1.0, v61
	v_add_f32_e32 v27, 1.0, v61
	v_mul_f32_e32 v26, v26, v27
	v_sqrt_f32_e32 v60, v26
	v_add_f32_e32 v26, v29, v40
	v_mul_f32_e32 v26, 0xbfb8aa3b, v26
	v_exp_f32_e32 v26, v26
	v_mul_f32_e32 v23, v61, v23
	v_rcp_f32_e32 v24, v24
	v_rcp_f32_e32 v25, v25
	v_add_f32_e32 v26, 1.0, v26
	v_rcp_f32_e32 v26, v26
	v_pk_fma_f32 v[66:67], v[56:57], v[0:1], v[64:65] op_sel_hi:[1,1,0]
	v_mul_f32_e32 v24, v118, v24
	v_mul_f32_e32 v26, v26, v46
	v_mul_f32_e32 v26, 0xbfb8aa3b, v26
	v_exp_f32_e32 v63, v26
	s_nop 0
	v_mul_f32_e32 v29, v63, v23
	ds_bpermute_b32 v42, v171, v29
	v_sub_f32_e32 v26, 1.0, v63
	v_add_f32_e32 v27, 1.0, v63
	v_mul_f32_e32 v26, v26, v27
	v_sqrt_f32_e32 v62, v26
	s_waitcnt lgkmcnt(0)
	v_mul_f32_e32 v51, v29, v42
	ds_bpermute_b32 v53, v172, v51
	v_cndmask_b32_e64 v46, v42, 1.0, s[50:51]
	v_mul_f32_e32 v26, v113, v25
	s_waitcnt lgkmcnt(0)
	v_mul_f32_e32 v23, v46, v53
	v_cndmask_b32_e64 v40, v23, v46, s[52:53]
	v_mov_b32_e32 v23, v67
	v_pk_mul_f32 v[66:67], v[22:23], v[58:59]
	v_mul_f32_e32 v28, v51, v53
	v_pk_fma_f32 v[22:23], v[22:23], v[58:59], v[66:67] op_sel_hi:[1,1,0]
	s_nop 0
	v_mov_b32_e32 v25, v23
	v_pk_mul_f32 v[68:69], v[24:25], v[60:61]
	s_nop 0
	v_pk_fma_f32 v[22:23], v[24:25], v[60:61], v[68:69] op_sel_hi:[1,1,0]
	v_add_f32_e32 v69, v44, v45
	v_mov_b32_e32 v27, v23
	v_pk_mul_f32 v[70:71], v[26:27], v[62:63]
	s_nop 0
	v_add_f32_e32 v1, v70, v71
	ds_bpermute_b32 v22, v171, v1
	v_add_f32_e32 v71, v36, v37
	s_waitcnt lgkmcnt(0)
	v_cndmask_b32_e64 v23, v22, 0, s[50:51]
	v_fma_f32 v24, v29, v22, v1
	v_fmac_f32_e32 v22, v1, v42
	v_cndmask_b32_e64 v1, v24, v22, s[50:51]
	ds_bpermute_b32 v22, v172, v1
	s_waitcnt lgkmcnt(0)
	v_fma_f32 v24, v46, v22, v23
	v_cndmask_b32_e64 v42, v24, v23, s[52:53]
	v_fma_f32 v23, v51, v22, v1
	v_fmac_f32_e32 v22, v1, v53
	v_cndmask_b32_e64 v29, v23, v22, s[52:53]
	ds_write_b64 v175, v[28:29] offset:58752
	s_waitcnt lgkmcnt(1)
	v_mfma_f32_16x16x32_bf16 v[22:25], v[14:17], v[208:211], 0
	s_waitcnt lgkmcnt(2)
	v_mfma_f32_16x16x32_bf16 v[26:29], v[14:17], v[212:215], 0
	s_waitcnt lgkmcnt(1)
	v_mfma_f32_16x16x32_bf16 v[80:83], v[18:21], v[216:219], v[22:25]
	s_waitcnt lgkmcnt(0)
; #define LAS __attribute__((address_space(3)))
; #define MFMA16(a, b, c) __builtin_amdgcn_mfma_f32_16x16x32_bf16(a, b, c, 0, 0, 0)
; template <bool PHASE_B>
; __device__ __forceinline__ void lru_item(const Params& p, LAS unsigned char* lds, int ci, int ci_next, int jb, const int tid, v4u (&xvn)[3]) {
;     ...
;         for (int ct = 0; ct < 4; ++ct) {
;             f32x4 ga = (f32x4){0.f, 0.f, 0.f, 0.f}, gx = (f32x4){0.f, 0.f, 0.f, 0.f};
; #pragma unroll
;             for (int ks = 0; ks < 2; ++ks) {
;                 const bf16x8 wa = *(const LAS bf16x8*)(lds + LR_WG + ((dir * 2 + 0) * 64 + 16 * ct + fr) * 144 + (32 * ks + 8 * fq) * 2);
;                 const bf16x8 wx = *(const LAS bf16x8*)(lds + LR_WG + ((dir * 2 + 1) * 64 + 16 * ct + fr) * 144 + (32 * ks + 8 * fq) * 2);
;                 ga = MFMA16(af[ks], wa, ga); gx = MFMA16(af[ks], wx, gx); }
;             const int ch = 16 * ct + fr; const float bav = GC[(dir * 3 + 0) * 64 + ch], bxv = GC[(dir * 3 + 1) * 64 + ch], c8 = GC[(dir * 3 + 2) * 64 + ch];
;             float Al = 1.f, Hl = 0.f;
; #pragma unroll
;             for (int ee = 0; ee < 4; ++ee) { const int e = dir ? 3 - ee : ee;
;                 const float r = __builtin_amdgcn_rcpf(1.f + __expf(-(ga[e] + bav))), ig = __builtin_amdgcn_rcpf(1.f + __expf(-(gx[e] + bxv)));
;                 const float la = -c8 * r; const float a = __expf(la); const float u = __builtin_amdgcn_sqrtf((1.f - a) * (1.f + a)) * (ig * xc[ct][e]);
;                 av[dir][ct][e] = a; uv[dir][ct][e] = u; Hl = a * Hl + u; Al *= a; }
;             const int o = dir ? 3 - fq : fq; const bool odd = (o & 1) != 0, hi2 = (o & 2) != 0;
;             const float A1 = __shfl_xor(Al, 16), H1 = __shfl_xor(Hl, 16);
;             const float pxA = odd ? A1 : 1.f, pxH = odd ? H1 : 0.f;
;             const float gA = Al * A1, gH = odd ? (Al * H1 + Hl) : (A1 * Hl + H1);
;             const float A2 = __shfl_xor(gA, 32), H2 = __shfl_xor(gH, 32);
;             const float PA = hi2 ? pxA * A2 : pxA, PH = hi2 ? (pxA * H2 + pxH) : pxH;
;             const float TA = gA * A2, TH = hi2 ? (gA * H2 + gH) : (A2 * gH + H2);
;             pA[dir][ct] = PA; pH[dir][ct] = PH;
;             ((LAS f32x2*)(lds + LR_SEG))[(dir * 8 + rt) * 64 + ch] = (f32x2){TA, TH};
	v_mfma_f32_16x16x32_bf16 v[22:25], v[18:21], v[220:223], v[26:29]
	ds_read_b128 v[208:211], v132 offset:25856
	ds_read_b128 v[212:215], v132 offset:35072
	ds_read_b128 v[216:219], v132 offset:25920
	ds_read_b128 v[220:223], v132 offset:35136
	s_nop 3
	ds_read_b32 v26, v174 offset:57216
	ds_read_b32 v27, v174 offset:57472
	ds_read_b32 v28, v174 offset:57728
	s_waitcnt lgkmcnt(2)
	v_add_f32_e32 v1, v80, v26
	v_mul_f32_e32 v1, 0xbfb8aa3b, v1
	v_exp_f32_e32 v1, v1
	s_waitcnt lgkmcnt(1)
	v_add_f32_e32 v22, v22, v27
	v_mul_f32_e32 v22, 0xbfb8aa3b, v22
	v_exp_f32_e32 v22, v22
	v_add_f32_e32 v1, 1.0, v1
	v_rcp_f32_e32 v1, v1
	v_add_f32_e32 v23, v23, v27
	v_add_f32_e32 v22, 1.0, v22
	v_rcp_f32_e32 v29, v22
	s_waitcnt lgkmcnt(0)
	v_mul_f32_e32 v1, v1, v28
	v_mul_f32_e32 v1, 0xbfb8aa3b, v1
	v_exp_f32_e32 v72, v1
	v_mul_f32_e32 v23, 0xbfb8aa3b, v23
	v_exp_f32_e32 v23, v23
	v_add_f32_e32 v24, v24, v27
	v_sub_f32_e32 v1, 1.0, v72
	v_add_f32_e32 v22, 1.0, v72
	v_mul_f32_e32 v1, v1, v22
	v_add_f32_e32 v22, v81, v26
	v_mul_f32_e32 v22, 0xbfb8aa3b, v22
	v_exp_f32_e32 v22, v22
	v_add_f32_e32 v23, 1.0, v23
	v_rcp_f32_e32 v23, v23
	v_add_f32_e32 v25, v25, v27
	v_add_f32_e32 v22, 1.0, v22
	v_rcp_f32_e32 v22, v22
	v_mul_f32_e32 v24, 0xbfb8aa3b, v24
	v_mul_f32_e32 v25, 0xbfb8aa3b, v25
	v_sqrt_f32_e32 v1, v1
	v_mul_f32_e32 v22, v22, v28
	v_mul_f32_e32 v22, 0xbfb8aa3b, v22
	v_exp_f32_e32 v75, v22
	v_exp_f32_e32 v24, v24
	v_exp_f32_e32 v25, v25
	v_mul_f32_e32 v73, v69, v29
	v_sub_f32_e32 v22, 1.0, v75
	v_add_f32_e32 v46, 1.0, v75
	v_mul_f32_e32 v22, v22, v46
	v_add_f32_e32 v46, v82, v26
	v_mul_f32_e32 v46, 0xbfb8aa3b, v46
	v_add_f32_e32 v26, v83, v26
	v_exp_f32_e32 v46, v46
	v_mul_f32_e32 v26, 0xbfb8aa3b, v26
	v_exp_f32_e32 v26, v26
	v_sqrt_f32_e32 v74, v22
	v_add_f32_e32 v46, 1.0, v46
	v_rcp_f32_e32 v46, v46
	v_add_f32_e32 v26, 1.0, v26
	v_rcp_f32_e32 v26, v26
	v_mul_f32_e32 v22, v130, v23
	v_mul_f32_e32 v46, v46, v28
	v_mul_f32_e32 v46, 0xbfb8aa3b, v46
	v_mul_f32_e32 v26, v26, v28
	v_exp_f32_e32 v77, v46
	v_mul_f32_e32 v26, 0xbfb8aa3b, v26
	v_exp_f32_e32 v79, v26
	v_mul_f32_e32 v23, v72, v75
	v_sub_f32_e32 v46, 1.0, v77
	v_add_f32_e32 v48, 1.0, v77
	v_mul_f32_e32 v23, v77, v23
	v_mul_f32_e32 v46, v46, v48
	v_mul_f32_e32 v48, v79, v23
	ds_bpermute_b32 v51, v171, v48
	v_add_f32_e32 v24, 1.0, v24
	v_add_f32_e32 v25, 1.0, v25
	v_pk_mul_f32 v[44:45], v[72:73], v[0:1]
	v_rcp_f32_e32 v24, v24
	s_waitcnt lgkmcnt(0)
	v_mul_f32_e32 v55, v48, v51
	ds_bpermute_b32 v57, v172, v55
	v_cndmask_b32_e64 v53, v51, 1.0, s[50:51]
	v_rcp_f32_e32 v25, v25
	v_pk_fma_f32 v[80:81], v[72:73], v[0:1], v[44:45] op_sel_hi:[1,1,0]
	v_sqrt_f32_e32 v76, v46
	s_waitcnt lgkmcnt(0)
	v_mul_f32_e32 v23, v53, v57
	v_cndmask_b32_e64 v46, v23, v53, s[52:53]
	v_mov_b32_e32 v23, v81
	v_sub_f32_e32 v26, 1.0, v79
	v_add_f32_e32 v27, 1.0, v79
	v_pk_mul_f32 v[80:81], v[22:23], v[74:75]
	v_mul_f32_e32 v26, v26, v27
	v_pk_fma_f32 v[22:23], v[22:23], v[74:75], v[80:81] op_sel_hi:[1,1,0]
	v_mul_f32_e32 v24, v128, v24
	v_sqrt_f32_e32 v78, v26
	v_mul_f32_e32 v26, v125, v25
	v_mov_b32_e32 v25, v23
	v_pk_mul_f32 v[82:83], v[24:25], v[76:77]
	v_mul_f32_e32 v28, v55, v57
	v_pk_fma_f32 v[22:23], v[24:25], v[76:77], v[82:83] op_sel_hi:[1,1,0]
	s_nop 0
	v_mov_b32_e32 v27, v23
	v_pk_mul_f32 v[84:85], v[26:27], v[78:79]
	s_nop 0
	v_add_f32_e32 v1, v84, v85
	ds_bpermute_b32 v22, v171, v1
	s_waitcnt lgkmcnt(0)
	v_cndmask_b32_e64 v23, v22, 0, s[50:51]
	v_fma_f32 v24, v48, v22, v1
	v_fmac_f32_e32 v22, v1, v51
	v_cndmask_b32_e64 v1, v24, v22, s[50:51]
	ds_bpermute_b32 v22, v172, v1
	s_waitcnt lgkmcnt(0)
	v_fma_f32 v24, v53, v22, v23
	v_cndmask_b32_e64 v44, v24, v23, s[52:53]
	v_fma_f32 v23, v55, v22, v1
	v_fmac_f32_e32 v22, v1, v57
	v_cndmask_b32_e64 v29, v23, v22, s[52:53]
	ds_write_b64 v175, v[28:29] offset:58880
	s_waitcnt lgkmcnt(1)
	v_mfma_f32_16x16x32_bf16 v[22:25], v[14:17], v[208:211], 0
	s_waitcnt lgkmcnt(2)
	v_mfma_f32_16x16x32_bf16 v[26:29], v[14:17], v[212:215], 0
	s_waitcnt lgkmcnt(1)
	v_mfma_f32_16x16x32_bf16 v[94:97], v[18:21], v[216:219], v[22:25]
	s_waitcnt lgkmcnt(0)
	v_mfma_f32_16x16x32_bf16 v[22:25], v[18:21], v[220:223], v[26:29]
	ds_read_b128 v[208:211], v132 offset:37376
	ds_read_b128 v[212:215], v132 offset:46592
	ds_read_b128 v[216:219], v132 offset:37440
	ds_read_b128 v[220:223], v132 offset:46656
	s_nop 3
	ds_read_b32 v26, v174 offset:57280
	ds_read_b32 v27, v174 offset:57536
	ds_read_b32 v28, v174 offset:57792
	s_waitcnt lgkmcnt(2)
	v_add_f32_e32 v1, v94, v26
	v_mul_f32_e32 v1, 0xbfb8aa3b, v1
	v_exp_f32_e32 v1, v1
	s_waitcnt lgkmcnt(1)
	v_add_f32_e32 v22, v22, v27
	v_mul_f32_e32 v22, 0xbfb8aa3b, v22
	v_exp_f32_e32 v22, v22
	v_add_f32_e32 v1, 1.0, v1
	v_rcp_f32_e32 v1, v1
	v_add_f32_e32 v23, v23, v27
	v_add_f32_e32 v22, 1.0, v22
	v_rcp_f32_e32 v29, v22
	s_waitcnt lgkmcnt(0)
; #define LAS __attribute__((address_space(3)))
; #define MFMA16(a, b, c) __builtin_amdgcn_mfma_f32_16x16x32_bf16(a, b, c, 0, 0, 0)
; template <bool PHASE_B>
; __device__ __forceinline__ void lru_item(const Params& p, LAS unsigned char* lds, int ci, int ci_next, int jb, const int tid, v4u (&xvn)[3]) {
;     ...
;         for (int ct = 0; ct < 4; ++ct) {
;             f32x4 ga = (f32x4){0.f, 0.f, 0.f, 0.f}, gx = (f32x4){0.f, 0.f, 0.f, 0.f};
; #pragma unroll
;             for (int ks = 0; ks < 2; ++ks) {
;                 const bf16x8 wa = *(const LAS bf16x8*)(lds + LR_WG + ((dir * 2 + 0) * 64 + 16 * ct + fr) * 144 + (32 * ks + 8 * fq) * 2);
;                 const bf16x8 wx = *(const LAS bf16x8*)(lds + LR_WG + ((dir * 2 + 1) * 64 + 16 * ct + fr) * 144 + (32 * ks + 8 * fq) * 2);
;                 ga = MFMA16(af[ks], wa, ga); gx = MFMA16(af[ks], wx, gx); }
;             const int ch = 16 * ct + fr; const float bav = GC[(dir * 3 + 0) * 64 + ch], bxv = GC[(dir * 3 + 1) * 64 + ch], c8 = GC[(dir * 3 + 2) * 64 + ch];
;             float Al = 1.f, Hl = 0.f;
; #pragma unroll
;             for (int ee = 0; ee < 4; ++ee) { const int e = dir ? 3 - ee : ee;
;                 const float r = __builtin_amdgcn_rcpf(1.f + __expf(-(ga[e] + bav))), ig = __builtin_amdgcn_rcpf(1.f + __expf(-(gx[e] + bxv)));
;                 const float la = -c8 * r; const float a = __expf(la); const float u = __builtin_amdgcn_sqrtf((1.f - a) * (1.f + a)) * (ig * xc[ct][e]);
;                 av[dir][ct][e] = a; uv[dir][ct][e] = u; Hl = a * Hl + u; Al *= a; }
;             const int o = dir ? 3 - fq : fq; const bool odd = (o & 1) != 0, hi2 = (o & 2) != 0;
;             const float A1 = __shfl_xor(Al, 16), H1 = __shfl_xor(Hl, 16);
;             const float pxA = odd ? A1 : 1.f, pxH = odd ? H1 : 0.f;
;             const float gA = Al * A1, gH = odd ? (Al * H1 + Hl) : (A1 * Hl + H1);
;             const float A2 = __shfl_xor(gA, 32), H2 = __shfl_xor(gH, 32);
;             const float PA = hi2 ? pxA * A2 : pxA, PH = hi2 ? (pxA * H2 + pxH) : pxH;
;             const float TA = gA * A2, TH = hi2 ? (gA * H2 + gH) : (A2 * gH + H2);
;             pA[dir][ct] = PA; pH[dir][ct] = PH;
;             ((LAS f32x2*)(lds + LR_SEG))[(dir * 8 + rt) * 64 + ch] = (f32x2){TA, TH};
	v_mul_f32_e32 v1, v1, v28
	v_mul_f32_e32 v1, 0xbfb8aa3b, v1
	v_exp_f32_e32 v86, v1
	v_mul_f32_e32 v23, 0xbfb8aa3b, v23
	v_exp_f32_e32 v23, v23
	v_add_f32_e32 v24, v24, v27
	v_sub_f32_e32 v1, 1.0, v86
	v_add_f32_e32 v22, 1.0, v86
	v_mul_f32_e32 v1, v1, v22
	v_add_f32_e32 v22, v95, v26
	v_mul_f32_e32 v22, 0xbfb8aa3b, v22
	v_exp_f32_e32 v22, v22
	v_add_f32_e32 v23, 1.0, v23
	v_rcp_f32_e32 v23, v23
	v_add_f32_e32 v25, v25, v27
	v_add_f32_e32 v22, 1.0, v22
	v_rcp_f32_e32 v22, v22
	v_mul_f32_e32 v24, 0xbfb8aa3b, v24
	v_mul_f32_e32 v25, 0xbfb8aa3b, v25
	v_sqrt_f32_e32 v1, v1
	v_mul_f32_e32 v22, v22, v28
	v_mul_f32_e32 v22, 0xbfb8aa3b, v22
	v_exp_f32_e32 v89, v22
	v_exp_f32_e32 v24, v24
	v_exp_f32_e32 v25, v25
	v_mul_f32_e32 v87, v71, v29
	v_sub_f32_e32 v22, 1.0, v89
	v_add_f32_e32 v48, 1.0, v89
	v_mul_f32_e32 v22, v22, v48
	v_add_f32_e32 v48, v96, v26
	v_mul_f32_e32 v48, 0xbfb8aa3b, v48
	v_add_f32_e32 v26, v97, v26
	v_exp_f32_e32 v48, v48
	v_mul_f32_e32 v26, 0xbfb8aa3b, v26
	v_exp_f32_e32 v26, v26
	v_sqrt_f32_e32 v88, v22
	v_add_f32_e32 v48, 1.0, v48
	v_rcp_f32_e32 v48, v48
	v_add_f32_e32 v26, 1.0, v26
	v_rcp_f32_e32 v26, v26
	v_mul_f32_e32 v22, v31, v23
	v_mul_f32_e32 v48, v48, v28
	v_mul_f32_e32 v48, 0xbfb8aa3b, v48
	v_mul_f32_e32 v26, v26, v28
	v_exp_f32_e32 v91, v48
	v_mul_f32_e32 v26, 0xbfb8aa3b, v26
	v_exp_f32_e32 v93, v26
	v_mul_f32_e32 v23, v86, v89
	v_sub_f32_e32 v48, 1.0, v91
	v_add_f32_e32 v51, 1.0, v91
	v_mul_f32_e32 v23, v91, v23
	v_mul_f32_e32 v48, v48, v51
	v_mul_f32_e32 v51, v93, v23
	ds_bpermute_b32 v53, v171, v51
	v_add_f32_e32 v24, 1.0, v24
	v_add_f32_e32 v25, 1.0, v25
	v_pk_mul_f32 v[36:37], v[86:87], v[0:1]
	v_rcp_f32_e32 v24, v24
	s_waitcnt lgkmcnt(0)
	v_mul_f32_e32 v57, v51, v53
	ds_bpermute_b32 v58, v172, v57
	v_cndmask_b32_e64 v55, v53, 1.0, s[50:51]
	v_rcp_f32_e32 v25, v25
	v_pk_fma_f32 v[94:95], v[86:87], v[0:1], v[36:37] op_sel_hi:[1,1,0]
	v_sqrt_f32_e32 v90, v48
	s_waitcnt lgkmcnt(0)
	v_mul_f32_e32 v23, v55, v58
	v_cndmask_b32_e64 v48, v23, v55, s[52:53]
	v_mov_b32_e32 v23, v95
	v_sub_f32_e32 v26, 1.0, v93
	v_add_f32_e32 v27, 1.0, v93
	v_pk_mul_f32 v[94:95], v[22:23], v[88:89]
	v_mul_f32_e32 v26, v26, v27
	v_pk_fma_f32 v[22:23], v[22:23], v[88:89], v[94:95] op_sel_hi:[1,1,0]
	v_mul_f32_e32 v24, v136, v24
	v_sqrt_f32_e32 v92, v26
	v_mul_f32_e32 v26, v133, v25
	v_mov_b32_e32 v25, v23
	v_pk_mul_f32 v[96:97], v[24:25], v[90:91]
	v_mul_f32_e32 v28, v57, v58
	v_pk_fma_f32 v[22:23], v[24:25], v[90:91], v[96:97] op_sel_hi:[1,1,0]
	s_nop 0
	v_mov_b32_e32 v27, v23
	v_pk_mul_f32 v[98:99], v[26:27], v[92:93]
	s_nop 0
	v_add_f32_e32 v1, v98, v99
	ds_bpermute_b32 v22, v171, v1
	s_waitcnt lgkmcnt(0)
	v_cndmask_b32_e64 v23, v22, 0, s[50:51]
	v_fma_f32 v24, v51, v22, v1
	v_fmac_f32_e32 v22, v1, v53
	v_cndmask_b32_e64 v1, v24, v22, s[50:51]
	ds_bpermute_b32 v22, v172, v1
	s_waitcnt lgkmcnt(0)
	v_fma_f32 v24, v55, v22, v23
	v_cndmask_b32_e64 v36, v24, v23, s[52:53]
	v_fma_f32 v23, v57, v22, v1
	v_fmac_f32_e32 v22, v1, v58
	v_cndmask_b32_e64 v29, v23, v22, s[52:53]
	ds_write_b64 v175, v[28:29] offset:59008
	s_waitcnt lgkmcnt(1)
	v_mfma_f32_16x16x32_bf16 v[22:25], v[14:17], v[208:211], 0
	s_waitcnt lgkmcnt(0)
	v_mfma_f32_16x16x32_bf16 v[102:105], v[14:17], v[212:215], 0
	ds_read_b32 v55, v174 offset:57856
	ds_read_b32 v57, v174 offset:58112
	ds_read_b32 v58, v174 offset:58368
	s_waitcnt lgkmcnt(4)
	v_mfma_f32_16x16x32_bf16 v[26:29], v[18:21], v[216:219], v[22:25]
	s_waitcnt lgkmcnt(3)
	v_mfma_f32_16x16x32_bf16 v[22:25], v[18:21], v[220:223], v[102:105]
	ds_read_b128 v[208:211], v132 offset:39680
	ds_read_b128 v[212:215], v132 offset:48896
	ds_read_b128 v[216:219], v132 offset:39744
	ds_read_b128 v[220:223], v132 offset:48960
	s_waitcnt lgkmcnt(2)
	s_nop 4
	v_add_f32_e32 v1, v29, v55
	v_mul_f32_e32 v1, 0xbfb8aa3b, v1
	v_exp_f32_e32 v1, v1
	s_nop 0
	v_add_f32_e32 v1, 1.0, v1
	v_rcp_f32_e32 v1, v1
	s_waitcnt lgkmcnt(1)
	v_add_f32_e32 v25, v25, v57
	v_mul_f32_e32 v25, 0xbfb8aa3b, v25
	v_exp_f32_e32 v25, v25
	s_waitcnt lgkmcnt(0)
	v_mul_f32_e32 v1, v1, v58
	v_mul_f32_e32 v1, 0xbfb8aa3b, v1
	v_exp_f32_e32 v100, v1
	v_add_f32_e32 v25, 1.0, v25
	v_rcp_f32_e32 v25, v25
	v_add_f32_e32 v23, v23, v57
	v_sub_f32_e32 v1, 1.0, v100
	v_add_f32_e32 v29, 1.0, v100
	v_mul_f32_e32 v1, v1, v29
	v_sqrt_f32_e32 v1, v1
	v_mul_f32_e32 v101, v101, v25
	v_mul_f32_e32 v23, 0xbfb8aa3b, v23
	v_exp_f32_e32 v23, v23
	v_pk_mul_f32 v[102:103], v[100:101], v[0:1]
	v_add_f32_e32 v24, v24, v57
	v_pk_fma_f32 v[114:115], v[100:101], v[0:1], v[102:103] op_sel_hi:[1,1,0]
	v_add_f32_e32 v1, v28, v55
	v_mul_f32_e32 v1, 0xbfb8aa3b, v1
	v_exp_f32_e32 v1, v1
	v_add_f32_e32 v23, 1.0, v23
	v_rcp_f32_e32 v23, v23
	v_mul_f32_e32 v24, 0xbfb8aa3b, v24
	v_add_f32_e32 v1, 1.0, v1
	v_rcp_f32_e32 v1, v1
	v_mul_f32_e32 v23, v108, v23
	v_exp_f32_e32 v24, v24
	v_add_f32_e32 v22, v22, v57
	v_mul_f32_e32 v1, v1, v58
	v_mul_f32_e32 v1, 0xbfb8aa3b, v1
	v_exp_f32_e32 v105, v1
	v_mul_f32_e32 v22, 0xbfb8aa3b, v22
	v_add_f32_e32 v24, 1.0, v24
	v_exp_f32_e32 v22, v22
	v_sub_f32_e32 v1, 1.0, v105
	v_add_f32_e32 v25, 1.0, v105
	v_mul_f32_e32 v1, v1, v25
	v_add_f32_e32 v25, v27, v55
	v_mul_f32_e32 v25, 0xbfb8aa3b, v25
	v_exp_f32_e32 v25, v25
	v_rcp_f32_e32 v24, v24
	v_sqrt_f32_e32 v104, v1
	v_add_f32_e32 v22, 1.0, v22
	v_add_f32_e32 v25, 1.0, v25
	v_rcp_f32_e32 v25, v25
	v_mul_f32_e32 v114, v106, v24
	v_rcp_f32_e32 v22, v22
	v_pk_mul_f32 v[106:107], v[114:115], v[104:105]
	v_mul_f32_e32 v25, v25, v58
	v_mul_f32_e32 v25, 0xbfb8aa3b, v25
	v_exp_f32_e32 v51, v25
	v_add_f32_e32 v1, v106, v107
	v_mul_f32_e32 v24, v100, v105
	v_mul_f32_e32 v22, v110, v22
	v_sub_f32_e32 v25, 1.0, v51
	v_add_f32_e32 v27, 1.0, v51
	v_mul_f32_e32 v25, v25, v27
	v_sqrt_f32_e32 v25, v25
	v_mul_f32_e32 v1, v51, v1
	v_mul_f32_e32 v24, v51, v24
	v_mul_f32_e32 v53, v23, v25
	v_add_f32_e32 v23, v26, v55
	v_mul_f32_e32 v23, 0xbfb8aa3b, v23
	v_exp_f32_e32 v23, v23
	s_nop 0
	v_add_f32_e32 v23, 1.0, v23
	v_rcp_f32_e32 v23, v23
	s_nop 0
	v_mul_f32_e32 v23, v23, v58
	v_mul_f32_e32 v23, 0xbfb8aa3b, v23
	v_exp_f32_e32 v109, v23
	s_nop 0
	v_sub_f32_e32 v23, 1.0, v109
	v_add_f32_e32 v25, 1.0, v109
	v_mul_f32_e32 v23, v23, v25
	v_sqrt_f32_e32 v108, v23
	v_add_f32_e32 v23, v1, v53
	v_pk_mul_f32 v[110:111], v[22:23], v[108:109]
	s_nop 0
	v_add_f32_e32 v1, v110, v111
	v_mul_f32_e32 v22, v109, v24
	ds_bpermute_b32 v23, v171, v22
	ds_bpermute_b32 v24, v171, v1
	s_waitcnt lgkmcnt(1)
; #define LAS __attribute__((address_space(3)))
; #define MFMA16(a, b, c) __builtin_amdgcn_mfma_f32_16x16x32_bf16(a, b, c, 0, 0, 0)
; template <bool PHASE_B>
; __device__ __forceinline__ void lru_item(const Params& p, LAS unsigned char* lds, int ci, int ci_next, int jb, const int tid, v4u (&xvn)[3]) {
;     ...
;         for (int ct = 0; ct < 4; ++ct) {
;             f32x4 ga = (f32x4){0.f, 0.f, 0.f, 0.f}, gx = (f32x4){0.f, 0.f, 0.f, 0.f};
; #pragma unroll
;             for (int ks = 0; ks < 2; ++ks) {
;                 const bf16x8 wa = *(const LAS bf16x8*)(lds + LR_WG + ((dir * 2 + 0) * 64 + 16 * ct + fr) * 144 + (32 * ks + 8 * fq) * 2);
;                 const bf16x8 wx = *(const LAS bf16x8*)(lds + LR_WG + ((dir * 2 + 1) * 64 + 16 * ct + fr) * 144 + (32 * ks + 8 * fq) * 2);
;                 ga = MFMA16(af[ks], wa, ga); gx = MFMA16(af[ks], wx, gx); }
;             const int ch = 16 * ct + fr; const float bav = GC[(dir * 3 + 0) * 64 + ch], bxv = GC[(dir * 3 + 1) * 64 + ch], c8 = GC[(dir * 3 + 2) * 64 + ch];
;             float Al = 1.f, Hl = 0.f;
; #pragma unroll
;             for (int ee = 0; ee < 4; ++ee) { const int e = dir ? 3 - ee : ee;
;                 const float r = __builtin_amdgcn_rcpf(1.f + __expf(-(ga[e] + bav))), ig = __builtin_amdgcn_rcpf(1.f + __expf(-(gx[e] + bxv)));
;                 const float la = -c8 * r; const float a = __expf(la); const float u = __builtin_amdgcn_sqrtf((1.f - a) * (1.f + a)) * (ig * xc[ct][e]);
;                 av[dir][ct][e] = a; uv[dir][ct][e] = u; Hl = a * Hl + u; Al *= a; }
;             const int o = dir ? 3 - fq : fq; const bool odd = (o & 1) != 0, hi2 = (o & 2) != 0;
;             const float A1 = __shfl_xor(Al, 16), H1 = __shfl_xor(Hl, 16);
;             const float pxA = odd ? A1 : 1.f, pxH = odd ? H1 : 0.f;
;             const float gA = Al * A1, gH = odd ? (Al * H1 + Hl) : (A1 * Hl + H1);
;             const float A2 = __shfl_xor(gA, 32), H2 = __shfl_xor(gH, 32);
;             const float PA = hi2 ? pxA * A2 : pxA, PH = hi2 ? (pxA * H2 + pxH) : pxH;
;             const float TA = gA * A2, TH = hi2 ? (gA * H2 + gH) : (A2 * gH + H2);
;             pA[dir][ct] = PA; pH[dir][ct] = PH;
;             ((LAS f32x2*)(lds + LR_SEG))[(dir * 8 + rt) * 64 + ch] = (f32x2){TA, TH};
	v_mul_f32_e32 v27, v22, v23
	s_waitcnt lgkmcnt(0)
	v_cndmask_b32_e64 v26, v24, 0, s[54:55]
	v_fma_f32 v22, v22, v24, v1
	v_fmac_f32_e32 v24, v1, v23
	v_cndmask_b32_e64 v25, v23, 1.0, s[54:55]
	v_cndmask_b32_e64 v1, v22, v24, s[54:55]
	ds_bpermute_b32 v23, v172, v27
	ds_bpermute_b32 v24, v172, v1
	s_waitcnt lgkmcnt(1)
	v_mul_f32_e32 v22, v25, v23
	v_cndmask_b32_e64 v55, v22, v25, s[56:57]
	s_waitcnt lgkmcnt(0)
	v_fma_f32 v22, v25, v24, v26
	v_fma_f32 v25, v27, v24, v1
	v_fmac_f32_e32 v24, v1, v23
	v_cndmask_b32_e64 v57, v22, v26, s[56:57]
	v_mul_f32_e32 v22, v27, v23
	v_cndmask_b32_e64 v23, v25, v24, s[56:57]
	ds_write_b64 v175, v[22:23] offset:62720
	s_waitcnt lgkmcnt(1)
	v_mfma_f32_16x16x32_bf16 v[22:25], v[14:17], v[208:211], 0
	s_waitcnt lgkmcnt(0)
	v_mfma_f32_16x16x32_bf16 v[114:117], v[14:17], v[212:215], 0
	ds_read_b32 v62, v174 offset:57920
	ds_read_b32 v64, v174 offset:58176
	ds_read_b32 v67, v174 offset:58432
	s_waitcnt lgkmcnt(4)
	v_mfma_f32_16x16x32_bf16 v[26:29], v[18:21], v[216:219], v[22:25]
	s_waitcnt lgkmcnt(3)
	v_mfma_f32_16x16x32_bf16 v[22:25], v[18:21], v[220:223], v[114:117]
	ds_read_b128 v[208:211], v132 offset:41984
	ds_read_b128 v[212:215], v132 offset:51200
	ds_read_b128 v[216:219], v132 offset:42048
	ds_read_b128 v[220:223], v132 offset:51264
	s_waitcnt lgkmcnt(2)
	s_nop 4
	v_add_f32_e32 v1, v29, v62
	v_mul_f32_e32 v1, 0xbfb8aa3b, v1
	v_exp_f32_e32 v1, v1
	s_nop 0
	v_add_f32_e32 v1, 1.0, v1
	v_rcp_f32_e32 v1, v1
	s_waitcnt lgkmcnt(1)
	v_add_f32_e32 v25, v25, v64
	v_mul_f32_e32 v25, 0xbfb8aa3b, v25
	v_exp_f32_e32 v25, v25
	s_waitcnt lgkmcnt(0)
	v_mul_f32_e32 v1, v1, v67
	v_mul_f32_e32 v1, 0xbfb8aa3b, v1
	v_exp_f32_e32 v112, v1
	v_add_f32_e32 v25, 1.0, v25
	v_rcp_f32_e32 v25, v25
	v_add_f32_e32 v23, v23, v64
	v_sub_f32_e32 v1, 1.0, v112
	v_add_f32_e32 v29, 1.0, v112
	v_mul_f32_e32 v1, v1, v29
	v_sqrt_f32_e32 v1, v1
	v_mul_f32_e32 v113, v113, v25
	v_mul_f32_e32 v23, 0xbfb8aa3b, v23
	v_exp_f32_e32 v23, v23
	v_pk_mul_f32 v[114:115], v[112:113], v[0:1]
	v_add_f32_e32 v24, v24, v64
	v_pk_fma_f32 v[126:127], v[112:113], v[0:1], v[114:115] op_sel_hi:[1,1,0]
	v_add_f32_e32 v1, v28, v62
	v_mul_f32_e32 v1, 0xbfb8aa3b, v1
	v_exp_f32_e32 v1, v1
	v_add_f32_e32 v23, 1.0, v23
	v_rcp_f32_e32 v23, v23
	v_mul_f32_e32 v24, 0xbfb8aa3b, v24
	v_add_f32_e32 v1, 1.0, v1
	v_rcp_f32_e32 v1, v1
	v_mul_f32_e32 v23, v120, v23
	v_exp_f32_e32 v24, v24
	v_add_f32_e32 v22, v22, v64
	v_mul_f32_e32 v1, v1, v67
	v_mul_f32_e32 v1, 0xbfb8aa3b, v1
	v_exp_f32_e32 v117, v1
	v_mul_f32_e32 v22, 0xbfb8aa3b, v22
	v_add_f32_e32 v24, 1.0, v24
	v_exp_f32_e32 v22, v22
	v_sub_f32_e32 v1, 1.0, v117
	v_add_f32_e32 v25, 1.0, v117
	v_mul_f32_e32 v1, v1, v25
	v_add_f32_e32 v25, v27, v62
	v_mul_f32_e32 v25, 0xbfb8aa3b, v25
	v_exp_f32_e32 v25, v25
	v_rcp_f32_e32 v24, v24
	v_sqrt_f32_e32 v116, v1
	v_add_f32_e32 v22, 1.0, v22
	v_add_f32_e32 v25, 1.0, v25
	v_rcp_f32_e32 v25, v25
	v_mul_f32_e32 v126, v118, v24
	v_rcp_f32_e32 v22, v22
	v_pk_mul_f32 v[118:119], v[126:127], v[116:117]
	v_mul_f32_e32 v25, v25, v67
	v_mul_f32_e32 v25, 0xbfb8aa3b, v25
	v_exp_f32_e32 v58, v25
	v_add_f32_e32 v1, v118, v119
	v_mul_f32_e32 v24, v112, v117
	v_mul_f32_e32 v22, v122, v22
	v_sub_f32_e32 v25, 1.0, v58
	v_add_f32_e32 v27, 1.0, v58
	v_mul_f32_e32 v25, v25, v27
	v_sqrt_f32_e32 v25, v25
	v_mul_f32_e32 v1, v58, v1
	v_mul_f32_e32 v24, v58, v24
	v_mul_f32_e32 v60, v23, v25
	v_add_f32_e32 v23, v26, v62
	v_mul_f32_e32 v23, 0xbfb8aa3b, v23
	v_exp_f32_e32 v23, v23
	s_nop 0
	v_add_f32_e32 v23, 1.0, v23
	v_rcp_f32_e32 v23, v23
	s_nop 0
	v_mul_f32_e32 v23, v23, v67
	v_mul_f32_e32 v23, 0xbfb8aa3b, v23
	v_exp_f32_e32 v121, v23
	s_nop 0
	v_sub_f32_e32 v23, 1.0, v121
	v_add_f32_e32 v25, 1.0, v121
	v_mul_f32_e32 v23, v23, v25
	v_sqrt_f32_e32 v120, v23
	v_add_f32_e32 v23, v1, v60
	v_pk_mul_f32 v[122:123], v[22:23], v[120:121]
	s_nop 0
	v_add_f32_e32 v1, v122, v123
	v_mul_f32_e32 v22, v121, v24
	ds_bpermute_b32 v23, v171, v22
	ds_bpermute_b32 v24, v171, v1
	s_waitcnt lgkmcnt(1)
	v_mul_f32_e32 v27, v22, v23
	s_waitcnt lgkmcnt(0)
	v_cndmask_b32_e64 v26, v24, 0, s[54:55]
	v_fma_f32 v22, v22, v24, v1
	v_fmac_f32_e32 v24, v1, v23
	v_cndmask_b32_e64 v25, v23, 1.0, s[54:55]
	v_cndmask_b32_e64 v1, v22, v24, s[54:55]
	ds_bpermute_b32 v23, v172, v27
	ds_bpermute_b32 v24, v172, v1
	s_waitcnt lgkmcnt(1)
	v_mul_f32_e32 v22, v25, v23
	v_cndmask_b32_e64 v62, v22, v25, s[56:57]
	s_waitcnt lgkmcnt(0)
	v_fma_f32 v22, v25, v24, v26
	v_fma_f32 v25, v27, v24, v1
	v_fmac_f32_e32 v24, v1, v23
	v_cndmask_b32_e64 v64, v22, v26, s[56:57]
	v_mul_f32_e32 v22, v27, v23
	v_cndmask_b32_e64 v23, v25, v24, s[56:57]
	ds_write_b64 v175, v[22:23] offset:62848
	s_waitcnt lgkmcnt(1)
	v_mfma_f32_16x16x32_bf16 v[22:25], v[14:17], v[208:211], 0
	s_waitcnt lgkmcnt(0)
	v_mfma_f32_16x16x32_bf16 v[138:141], v[14:17], v[212:215], 0
	ds_read_b32 v73, v174 offset:57984
	ds_read_b32 v74, v174 offset:58240
	ds_read_b32 v76, v174 offset:58496
	s_waitcnt lgkmcnt(4)
	v_mfma_f32_16x16x32_bf16 v[26:29], v[18:21], v[216:219], v[22:25]
	s_waitcnt lgkmcnt(3)
	v_mfma_f32_16x16x32_bf16 v[22:25], v[18:21], v[220:223], v[138:141]
	ds_read_b128 v[208:211], v132 offset:44288
	ds_read_b128 v[212:215], v132 offset:53504
	ds_read_b128 v[216:219], v132 offset:44352
	ds_read_b128 v[220:223], v132 offset:53568
	s_waitcnt lgkmcnt(2)
	s_nop 4
	v_add_f32_e32 v1, v29, v73
	v_mul_f32_e32 v1, 0xbfb8aa3b, v1
	v_exp_f32_e32 v1, v1
	s_nop 0
	v_add_f32_e32 v1, 1.0, v1
	v_rcp_f32_e32 v1, v1
	s_waitcnt lgkmcnt(1)
	v_add_f32_e32 v25, v25, v74
	v_mul_f32_e32 v25, 0xbfb8aa3b, v25
	v_exp_f32_e32 v25, v25
	s_waitcnt lgkmcnt(0)
; #define LAS __attribute__((address_space(3)))
; #define MFMA16(a, b, c) __builtin_amdgcn_mfma_f32_16x16x32_bf16(a, b, c, 0, 0, 0)
; template <bool PHASE_B>
; __device__ __forceinline__ void lru_item(const Params& p, LAS unsigned char* lds, int ci, int ci_next, int jb, const int tid, v4u (&xvn)[3]) {
;     ...
;         for (int ct = 0; ct < 4; ++ct) {
;             f32x4 ga = (f32x4){0.f, 0.f, 0.f, 0.f}, gx = (f32x4){0.f, 0.f, 0.f, 0.f};
; #pragma unroll
;             for (int ks = 0; ks < 2; ++ks) {
;                 const bf16x8 wa = *(const LAS bf16x8*)(lds + LR_WG + ((dir * 2 + 0) * 64 + 16 * ct + fr) * 144 + (32 * ks + 8 * fq) * 2);
;                 const bf16x8 wx = *(const LAS bf16x8*)(lds + LR_WG + ((dir * 2 + 1) * 64 + 16 * ct + fr) * 144 + (32 * ks + 8 * fq) * 2);
;                 ga = MFMA16(af[ks], wa, ga); gx = MFMA16(af[ks], wx, gx); }
;             const int ch = 16 * ct + fr; const float bav = GC[(dir * 3 + 0) * 64 + ch], bxv = GC[(dir * 3 + 1) * 64 + ch], c8 = GC[(dir * 3 + 2) * 64 + ch];
;             float Al = 1.f, Hl = 0.f;
; #pragma unroll
;             for (int ee = 0; ee < 4; ++ee) { const int e = dir ? 3 - ee : ee;
;                 const float r = __builtin_amdgcn_rcpf(1.f + __expf(-(ga[e] + bav))), ig = __builtin_amdgcn_rcpf(1.f + __expf(-(gx[e] + bxv)));
;                 const float la = -c8 * r; const float a = __expf(la); const float u = __builtin_amdgcn_sqrtf((1.f - a) * (1.f + a)) * (ig * xc[ct][e]);
;                 av[dir][ct][e] = a; uv[dir][ct][e] = u; Hl = a * Hl + u; Al *= a; }
;             const int o = dir ? 3 - fq : fq; const bool odd = (o & 1) != 0, hi2 = (o & 2) != 0;
;             const float A1 = __shfl_xor(Al, 16), H1 = __shfl_xor(Hl, 16);
;             const float pxA = odd ? A1 : 1.f, pxH = odd ? H1 : 0.f;
;             const float gA = Al * A1, gH = odd ? (Al * H1 + Hl) : (A1 * Hl + H1);
;             const float A2 = __shfl_xor(gA, 32), H2 = __shfl_xor(gH, 32);
;             const float PA = hi2 ? pxA * A2 : pxA, PH = hi2 ? (pxA * H2 + pxH) : pxH;
;             const float TA = gA * A2, TH = hi2 ? (gA * H2 + gH) : (A2 * gH + H2);
;             pA[dir][ct] = PA; pH[dir][ct] = PH;
;             ((LAS f32x2*)(lds + LR_SEG))[(dir * 8 + rt) * 64 + ch] = (f32x2){TA, TH};
	v_mul_f32_e32 v1, v1, v76
	v_mul_f32_e32 v1, 0xbfb8aa3b, v1
	v_exp_f32_e32 v124, v1
	v_add_f32_e32 v25, 1.0, v25
	v_rcp_f32_e32 v25, v25
	v_add_f32_e32 v24, v24, v74
	v_sub_f32_e32 v1, 1.0, v124
	v_add_f32_e32 v29, 1.0, v124
	v_mul_f32_e32 v1, v1, v29
	v_sqrt_f32_e32 v1, v1
	v_mul_f32_e32 v125, v125, v25
	v_mul_f32_e32 v24, 0xbfb8aa3b, v24
	v_exp_f32_e32 v24, v24
	v_pk_mul_f32 v[126:127], v[124:125], v[0:1]
	v_add_f32_e32 v23, v23, v74
	v_pk_fma_f32 v[134:135], v[124:125], v[0:1], v[126:127] op_sel_hi:[1,1,0]
	v_add_f32_e32 v1, v28, v73
	v_mul_f32_e32 v1, 0xbfb8aa3b, v1
	v_exp_f32_e32 v1, v1
	v_add_f32_e32 v24, 1.0, v24
	v_rcp_f32_e32 v24, v24
	v_mul_f32_e32 v23, 0xbfb8aa3b, v23
	v_add_f32_e32 v1, 1.0, v1
	v_rcp_f32_e32 v1, v1
	v_mul_f32_e32 v134, v128, v24
	v_exp_f32_e32 v23, v23
	v_add_f32_e32 v22, v22, v74
	v_mul_f32_e32 v1, v1, v76
	v_mul_f32_e32 v1, 0xbfb8aa3b, v1
	v_exp_f32_e32 v29, v1
	v_add_f32_e32 v23, 1.0, v23
	v_rcp_f32_e32 v23, v23
	v_mul_f32_e32 v22, 0xbfb8aa3b, v22
	v_sub_f32_e32 v1, 1.0, v29
	v_add_f32_e32 v25, 1.0, v29
	v_mul_f32_e32 v1, v1, v25
	v_add_f32_e32 v25, v27, v73
	v_mul_f32_e32 v25, 0xbfb8aa3b, v25
	v_exp_f32_e32 v25, v25
	v_sqrt_f32_e32 v28, v1
	v_mul_f32_e32 v23, v130, v23
	v_exp_f32_e32 v22, v22
	v_add_f32_e32 v25, 1.0, v25
	v_rcp_f32_e32 v25, v25
	v_pk_mul_f32 v[128:129], v[134:135], v[28:29]
	v_add_f32_e32 v22, 1.0, v22
	v_rcp_f32_e32 v22, v22
	v_mul_f32_e32 v25, v25, v76
	v_mul_f32_e32 v25, 0xbfb8aa3b, v25
	v_exp_f32_e32 v28, v25
	v_add_f32_e32 v1, v128, v129
	v_mul_f32_e32 v24, v124, v29
	v_mul_f32_e32 v22, v69, v22
	v_sub_f32_e32 v25, 1.0, v28
	v_add_f32_e32 v27, 1.0, v28
	v_mul_f32_e32 v25, v25, v27
	v_sqrt_f32_e32 v25, v25
	v_mul_f32_e32 v1, v28, v1
	v_mul_f32_e32 v24, v28, v24
	v_mul_f32_e32 v67, v23, v25
	v_add_f32_e32 v23, v26, v73
	v_mul_f32_e32 v23, 0xbfb8aa3b, v23
	v_exp_f32_e32 v23, v23
	s_nop 0
	v_add_f32_e32 v23, 1.0, v23
	v_rcp_f32_e32 v23, v23
	s_nop 0
	v_mul_f32_e32 v23, v23, v76
	v_mul_f32_e32 v23, 0xbfb8aa3b, v23
	v_exp_f32_e32 v27, v23
	s_nop 0
	v_sub_f32_e32 v23, 1.0, v27
	v_add_f32_e32 v25, 1.0, v27
	v_mul_f32_e32 v23, v23, v25
	v_sqrt_f32_e32 v26, v23
	v_add_f32_e32 v23, v1, v67
	v_pk_mul_f32 v[130:131], v[22:23], v[26:27]
	s_nop 0
	v_add_f32_e32 v1, v130, v131
	v_mul_f32_e32 v22, v27, v24
	ds_bpermute_b32 v23, v171, v22
	ds_bpermute_b32 v24, v171, v1
	s_waitcnt lgkmcnt(1)
	v_mul_f32_e32 v73, v22, v23
	s_waitcnt lgkmcnt(0)
	v_cndmask_b32_e64 v69, v24, 0, s[54:55]
	v_fma_f32 v22, v22, v24, v1
	v_fmac_f32_e32 v24, v1, v23
	v_cndmask_b32_e64 v25, v23, 1.0, s[54:55]
	v_cndmask_b32_e64 v1, v22, v24, s[54:55]
	ds_bpermute_b32 v23, v172, v73
	ds_bpermute_b32 v24, v172, v1
	s_waitcnt lgkmcnt(1)
	v_mul_f32_e32 v22, v25, v23
	v_cndmask_b32_e64 v26, v22, v25, s[56:57]
	s_waitcnt lgkmcnt(0)
	v_fma_f32 v22, v25, v24, v69
	v_fma_f32 v25, v73, v24, v1
	v_fmac_f32_e32 v24, v1, v23
	v_cndmask_b32_e64 v69, v22, v69, s[56:57]
	v_mul_f32_e32 v22, v73, v23
	v_cndmask_b32_e64 v23, v25, v24, s[56:57]
	ds_write_b64 v175, v[22:23] offset:62976
	s_waitcnt lgkmcnt(1)
	v_mfma_f32_16x16x32_bf16 v[22:25], v[14:17], v[208:211], 0
	s_waitcnt lgkmcnt(0)
	v_mfma_f32_16x16x32_bf16 v[14:17], v[14:17], v[212:215], 0
	s_waitcnt lgkmcnt(1)
	v_mfma_f32_16x16x32_bf16 v[22:25], v[18:21], v[216:219], v[22:25]
	s_waitcnt lgkmcnt(0)
	v_mfma_f32_16x16x32_bf16 v[14:17], v[18:21], v[220:223], v[14:17]
	ds_read_b32 v20, v174 offset:58048
	ds_read_b32 v21, v174 offset:58304
	ds_read_b32 v73, v174 offset:58560
	s_waitcnt lgkmcnt(2)
	s_nop 1
	v_add_f32_e32 v1, v25, v20
	v_mul_f32_e32 v1, 0xbfb8aa3b, v1
	v_exp_f32_e32 v1, v1
	s_waitcnt lgkmcnt(1)
	v_add_f32_e32 v17, v17, v21
	v_mul_f32_e32 v17, 0xbfb8aa3b, v17
	v_exp_f32_e32 v17, v17
	v_add_f32_e32 v1, 1.0, v1
	v_rcp_f32_e32 v1, v1
	v_add_f32_e32 v16, v16, v21
	v_add_f32_e32 v17, 1.0, v17
	v_rcp_f32_e32 v17, v17
	s_waitcnt lgkmcnt(0)
	v_mul_f32_e32 v1, v1, v73
	v_mul_f32_e32 v1, 0xbfb8aa3b, v1
	v_exp_f32_e32 v132, v1
	v_mul_f32_e32 v133, v133, v17
	v_mul_f32_e32 v16, 0xbfb8aa3b, v16
	v_exp_f32_e32 v16, v16
	v_sub_f32_e32 v1, 1.0, v132
	v_add_f32_e32 v18, 1.0, v132
	v_mul_f32_e32 v1, v1, v18
	v_sqrt_f32_e32 v1, v1
	v_add_f32_e32 v16, 1.0, v16
	v_add_f32_e32 v15, v15, v21
	v_rcp_f32_e32 v16, v16
	v_pk_mul_f32 v[134:135], v[132:133], v[0:1]
	v_mul_f32_e32 v15, 0xbfb8aa3b, v15
	v_pk_fma_f32 v[18:19], v[132:133], v[0:1], v[134:135] op_sel_hi:[1,1,0]
	v_add_f32_e32 v1, v24, v20
	v_mul_f32_e32 v1, 0xbfb8aa3b, v1
	v_exp_f32_e32 v1, v1
	v_exp_f32_e32 v15, v15
	v_mul_f32_e32 v18, v136, v16
	v_add_f32_e32 v14, v14, v21
	v_add_f32_e32 v1, 1.0, v1
	v_rcp_f32_e32 v1, v1
	v_add_f32_e32 v15, 1.0, v15
	v_rcp_f32_e32 v15, v15
	v_mul_f32_e32 v14, 0xbfb8aa3b, v14
	v_mul_f32_e32 v1, v1, v73
	v_mul_f32_e32 v1, 0xbfb8aa3b, v1
	v_exp_f32_e32 v25, v1
	v_mul_f32_e32 v15, v31, v15
	v_exp_f32_e32 v14, v14
	v_sub_f32_e32 v1, 1.0, v25
	v_add_f32_e32 v17, 1.0, v25
	v_mul_f32_e32 v1, v1, v17
	v_sqrt_f32_e32 v24, v1
	v_add_f32_e32 v1, v23, v20
	v_mul_f32_e32 v1, 0xbfb8aa3b, v1
	v_exp_f32_e32 v1, v1
	v_pk_mul_f32 v[136:137], v[18:19], v[24:25]
	v_mul_f32_e32 v17, v132, v25
	v_add_f32_e32 v16, v136, v137
	v_add_f32_e32 v1, 1.0, v1
	v_rcp_f32_e32 v1, v1
	v_add_f32_e32 v14, 1.0, v14
	v_rcp_f32_e32 v14, v14
	v_mul_f32_e32 v1, v1, v73
	v_mul_f32_e32 v1, 0xbfb8aa3b, v1
	v_exp_f32_e32 v1, v1
	v_mul_f32_e32 v14, v71, v14
	v_sub_f32_e32 v18, 1.0, v1
	v_add_f32_e32 v19, 1.0, v1
	v_mul_f32_e32 v18, v18, v19
	v_sqrt_f32_e32 v18, v18
	s_nop 0
	v_mul_f32_e32 v24, v15, v18
	v_mul_f32_e32 v15, v1, v16
	v_mul_f32_e32 v16, v1, v17
	v_add_f32_e32 v17, v22, v20
	v_mul_f32_e32 v17, 0xbfb8aa3b, v17
	v_exp_f32_e32 v17, v17
	v_add_f32_e32 v15, v15, v24
	v_add_f32_e32 v17, 1.0, v17
	v_rcp_f32_e32 v17, v17
	s_nop 0
	v_mul_f32_e32 v17, v17, v73
	v_mul_f32_e32 v17, 0xbfb8aa3b, v17
	v_exp_f32_e32 v23, v17
	s_nop 0
	v_sub_f32_e32 v17, 1.0, v23
	v_add_f32_e32 v18, 1.0, v23
	v_mul_f32_e32 v17, v17, v18
	v_sqrt_f32_e32 v22, v17
	s_nop 0
	v_pk_mul_f32 v[138:139], v[14:15], v[22:23]
	s_nop 0
	v_add_f32_e32 v14, v138, v139
	v_mul_f32_e32 v15, v23, v16
	ds_bpermute_b32 v16, v171, v15
	ds_bpermute_b32 v17, v171, v14
	s_waitcnt lgkmcnt(1)
; #define LAS __attribute__((address_space(3)))
; template <bool PHASE_B>
; __device__ __forceinline__ void lru_item(const Params& p, LAS unsigned char* lds, int ci, int ci_next, int jb, const int tid, v4u (&xvn)[3]) {
;     ...
;             const int o = dir ? 3 - fq : fq; const bool odd = (o & 1) != 0, hi2 = (o & 2) != 0;
;             const float A1 = __shfl_xor(Al, 16), H1 = __shfl_xor(Hl, 16);
;             const float pxA = odd ? A1 : 1.f, pxH = odd ? H1 : 0.f;
;             const float gA = Al * A1, gH = odd ? (Al * H1 + Hl) : (A1 * Hl + H1);
;             const float A2 = __shfl_xor(gA, 32), H2 = __shfl_xor(gH, 32);
;             const float PA = hi2 ? pxA * A2 : pxA, PH = hi2 ? (pxA * H2 + pxH) : pxH;
;             const float TA = gA * A2, TH = hi2 ? (gA * H2 + gH) : (A2 * gH + H2);
;             pA[dir][ct] = PA; pH[dir][ct] = PH;
;             ((LAS f32x2*)(lds + LR_SEG))[(dir * 8 + rt) * 64 + ch] = (f32x2){TA, TH};
;         }
;     }
;     if constexpr (PHASE_B) {
; #pragma unroll
;         for (int dir = 0; dir < 2; ++dir)
; #pragma unroll
;             for (int ct = 0; ct < 4; ++ct) cin[dir][ct] = ((const float*)(p.ws + WS_CIN))[(size_t)(ci * 2 + dir) * 768 + jb * 64 + 16 * ct + fr];
;         const bf16* gp = (const bf16*)(p.ws + WS_GR) + (size_t)(t0 + (tid >> 2)) * 768 + jb * 64 + (tid & 3) * 16;
;         gv[0] = *(const v4u*)gp; gv[1] = *(const v4u*)(gp + 8);
;     }
;     __syncthreads();
;     if constexpr (!PHASE_B) {
;         if (tid < 128) { const int dir = tid >> 6, ch = tid & 63; float A = 1.f, H = 0.f;
; #pragma unroll
;             for (int q = 0; q < 8; ++q) { const f32x2 sh = ((const LAS f32x2*)(lds + LR_SEG))[(dir * 8 + (dir ? 7 - q : q)) * 64 + ch]; H = sh.x * H + sh.y; A *= sh.x; }
;             ((f32x2*)(p.ws + WS_CAR))[(size_t)(ci * 2 + dir) * 768 + jb * 64 + ch] = (f32x2){A, H}; }
;     } else {
; #pragma unroll
;         for (int dir = 0; dir < 2; ++dir) { const int ot = dir ? 7 - rt : rt;
; #pragma unroll
;             for (int ct = 0; ct < 4; ++ct) { const int ch = 16 * ct + fr; float h = cin[dir][ct];
; #pragma unroll
;                 for (int q = 0; q < 7; ++q) { const f32x2 sh = ((const LAS f32x2*)(lds + LR_SEG))[(dir * 8 + (dir ? 7 - q : q)) * 64 + ch]; const float nh = sh.x * h + sh.y; h = (q < ot) ? nh : h; }
;                 h = pA[dir][ct] * h + pH[dir][ct];
; #pragma unroll
	v_mul_f32_e32 v20, v15, v16
	s_waitcnt lgkmcnt(0)
	v_cndmask_b32_e64 v19, v17, 0, s[54:55]
	v_fma_f32 v15, v15, v17, v14
	v_fmac_f32_e32 v17, v14, v16
	v_cndmask_b32_e64 v18, v16, 1.0, s[54:55]
	v_cndmask_b32_e64 v15, v15, v17, s[54:55]
	ds_bpermute_b32 v16, v172, v20
	ds_bpermute_b32 v17, v172, v15
	s_waitcnt lgkmcnt(1)
	v_mul_f32_e32 v14, v18, v16
	v_cndmask_b32_e64 v22, v14, v18, s[56:57]
	s_waitcnt lgkmcnt(0)
	v_fma_f32 v14, v18, v17, v19
	v_fma_f32 v18, v20, v17, v15
	v_fmac_f32_e32 v17, v15, v16
	v_cndmask_b32_e64 v31, v14, v19, s[56:57]
	v_mul_f32_e32 v14, v20, v16
	v_cndmask_b32_e64 v15, v18, v17, s[56:57]
	ds_write_b64 v175, v[14:15] offset:63104
	v_mad_i64_i32 v[14:15], s[0:1], s13, v232, v[32:33]
	global_load_dword v78, v[14:15], off
	global_load_dword v81, v[14:15], off offset:64
	global_load_dword v83, v[14:15], off offset:128
	global_load_dword v85, v[14:15], off offset:192
	s_add_i32 s0, s13, 1
	v_mad_i64_i32 v[14:15], s[0:1], s0, v232, v[32:33]
	s_movk_i32 s0, 0x600
	s_nop 0
	v_mad_i64_i32 v[140:141], s[0:1], v196, s0, v[34:35]
	global_load_dword v76, v[14:15], off
	global_load_dword v74, v[14:15], off offset:64
	global_load_dword v73, v[14:15], off offset:128
	global_load_dword v71, v[14:15], off offset:192
	s_nop 0
	global_load_dwordx4 v[14:17], v[140:141], off offset:16
	global_load_dwordx4 v[18:21], v[140:141], off
	s_waitcnt lgkmcnt(0)
	s_barrier
	ds_read_b64 v[208:209], v176 offset:58624
	ds_read_b64 v[210:211], v176 offset:59136
	ds_read_b64 v[212:213], v176 offset:59648
	ds_read_b64 v[214:215], v176 offset:60160
	ds_read_b64 v[216:217], v176 offset:60672
	ds_read_b64 v[218:219], v176 offset:61184
	ds_read_b64 v[220:221], v176 offset:61696
	v_add_u32_e32 v196, s12, v196
	s_add_i32 s13, s13, s86
	s_waitcnt vmcnt(9) lgkmcnt(0)
	v_fmac_f32_e32 v209, v78, v208
	v_cndmask_b32_e64 v78, v78, v209, s[58:59]
	v_fmac_f32_e32 v211, v210, v78
	v_cndmask_b32_e64 v78, v78, v211, s[60:61]
	v_fmac_f32_e32 v213, v212, v78
	v_cndmask_b32_e64 v78, v78, v213, s[62:63]
	v_fmac_f32_e32 v215, v214, v78
	v_cndmask_b32_e64 v78, v78, v215, s[64:65]
	v_fmac_f32_e32 v217, v216, v78
	v_cndmask_b32_e64 v78, v78, v217, s[66:67]
	v_fmac_f32_e32 v219, v218, v78
	v_cndmask_b32_e64 v78, v78, v219, s[68:69]
	v_fmac_f32_e32 v221, v220, v78
	v_cndmask_b32_e64 v78, v78, v221, s[70:71]
	v_fmac_f32_e32 v39, v206, v78
	v_fmac_f32_e32 v49, v38, v39
	v_fmac_f32_e32 v50, v41, v49
	v_fmac_f32_e32 v52, v43, v50
	v_fmac_f32_e32 v54, v47, v52
	ds_write2_b32 v202, v49, v50 offset1:68
	ds_write2_b32 v202, v52, v54 offset0:136 offset1:204
	ds_read_b64 v[222:223], v176 offset:58752
	ds_read_b64 v[224:225], v176 offset:59264
	ds_read_b64 v[226:227], v176 offset:59776
	ds_read_b64 v[228:229], v176 offset:60288
	ds_read_b64 v[234:235], v176 offset:60800
	ds_read_b64 v[236:237], v176 offset:61312
	ds_read_b64 v[238:239], v176 offset:61824
	s_waitcnt vmcnt(0)
	v_lshlrev_b32_e32 v52, 16, v18
	v_and_b32_e32 v18, 0xffff0000, v18
	s_waitcnt lgkmcnt(0)
	v_fmac_f32_e32 v223, v81, v222
	v_cndmask_b32_e64 v41, v81, v223, s[58:59]
	v_fmac_f32_e32 v225, v224, v41
	v_cndmask_b32_e64 v41, v41, v225, s[60:61]
	v_fmac_f32_e32 v227, v226, v41
	v_cndmask_b32_e64 v41, v41, v227, s[62:63]
	v_fmac_f32_e32 v229, v228, v41
	v_cndmask_b32_e64 v41, v41, v229, s[64:65]
	v_fmac_f32_e32 v235, v234, v41
	v_cndmask_b32_e64 v41, v41, v235, s[66:67]
	v_fmac_f32_e32 v237, v236, v41
	v_cndmask_b32_e64 v41, v41, v237, s[68:69]
	v_fmac_f32_e32 v239, v238, v41
	v_cndmask_b32_e64 v38, v41, v239, s[70:71]
	v_fmac_f32_e32 v42, v40, v38
	v_fmac_f32_e32 v65, v56, v42
	v_fmac_f32_e32 v66, v59, v65
	v_fmac_f32_e32 v68, v61, v66
	v_fmac_f32_e32 v70, v63, v68
	ds_write_b32 v177, v65
	ds_write_b32 v178, v66
	ds_write_b32 v179, v68
	ds_write_b32 v180, v70
	ds_read_b64 v[208:209], v176 offset:58880
	ds_read_b64 v[210:211], v176 offset:59392
	ds_read_b64 v[212:213], v176 offset:59904
	ds_read_b64 v[214:215], v176 offset:60416
	ds_read_b64 v[216:217], v176 offset:60928
	ds_read_b64 v[218:219], v176 offset:61440
	ds_read_b64 v[220:221], v176 offset:61952
	s_waitcnt lgkmcnt(0)
	v_fmac_f32_e32 v209, v83, v208
	v_cndmask_b32_e64 v40, v83, v209, s[58:59]
	v_fmac_f32_e32 v211, v210, v40
	v_cndmask_b32_e64 v40, v40, v211, s[60:61]
	v_fmac_f32_e32 v213, v212, v40
	v_cndmask_b32_e64 v40, v40, v213, s[62:63]
	v_fmac_f32_e32 v215, v214, v40
	v_cndmask_b32_e64 v40, v40, v215, s[64:65]
	v_fmac_f32_e32 v217, v216, v40
	v_cndmask_b32_e64 v40, v40, v217, s[66:67]
	v_fmac_f32_e32 v219, v218, v40
	v_cndmask_b32_e64 v40, v40, v219, s[68:69]
	v_fmac_f32_e32 v221, v220, v40
	v_cndmask_b32_e64 v38, v40, v221, s[70:71]
	v_fmac_f32_e32 v44, v46, v38
	v_fmac_f32_e32 v45, v72, v44
	v_fmac_f32_e32 v80, v75, v45
	v_fmac_f32_e32 v82, v77, v80
	v_fmac_f32_e32 v84, v79, v82
	ds_write_b32 v181, v45
	ds_write_b32 v182, v80
	ds_write_b32 v183, v82
	ds_write_b32 v184, v84
	ds_read_b64 v[222:223], v176 offset:59008
	ds_read_b64 v[224:225], v176 offset:59520
	ds_read_b64 v[226:227], v176 offset:60032
	ds_read_b64 v[228:229], v176 offset:60544
	ds_read_b64 v[234:235], v176 offset:61056
	ds_read_b64 v[236:237], v176 offset:61568
	ds_read_b64 v[238:239], v176 offset:62080
	s_waitcnt lgkmcnt(0)
	v_fmac_f32_e32 v223, v85, v222
	v_cndmask_b32_e64 v40, v85, v223, s[58:59]
	v_fmac_f32_e32 v225, v224, v40
	v_cndmask_b32_e64 v40, v40, v225, s[60:61]
	v_fmac_f32_e32 v227, v226, v40
	v_cndmask_b32_e64 v40, v40, v227, s[62:63]
	v_fmac_f32_e32 v229, v228, v40
	v_cndmask_b32_e64 v40, v40, v229, s[64:65]
	v_fmac_f32_e32 v235, v234, v40
	v_cndmask_b32_e64 v40, v40, v235, s[66:67]
	v_fmac_f32_e32 v237, v236, v40
	v_cndmask_b32_e64 v40, v40, v237, s[68:69]
	v_fmac_f32_e32 v239, v238, v40
	v_cndmask_b32_e64 v38, v40, v239, s[70:71]
	v_fmac_f32_e32 v36, v48, v38
	v_fmac_f32_e32 v37, v86, v36
	v_fmac_f32_e32 v94, v89, v37
	v_fmac_f32_e32 v96, v91, v94
	v_fmac_f32_e32 v98, v93, v96
	ds_write_b32 v185, v37
	ds_write_b32 v186, v94
	ds_write_b32 v187, v96
	ds_write_b32 v188, v98
	ds_read2st64_b64 v[36:39], v190 offset0:6 offset1:7
	s_waitcnt lgkmcnt(0)
; #define LAS __attribute__((address_space(3)))
; template <bool PHASE_B>
; __device__ __forceinline__ void lru_item(const Params& p, LAS unsigned char* lds, int ci, int ci_next, int jb, const int tid, v4u (&xvn)[3]) {
;     ...
;         for (int dir = 0; dir < 2; ++dir) { const int ot = dir ? 7 - rt : rt;
; #pragma unroll
;             for (int ct = 0; ct < 4; ++ct) { const int ch = 16 * ct + fr; float h = cin[dir][ct];
; #pragma unroll
;                 for (int q = 0; q < 7; ++q) { const f32x2 sh = ((const LAS f32x2*)(lds + LR_SEG))[(dir * 8 + (dir ? 7 - q : q)) * 64 + ch]; const float nh = sh.x * h + sh.y; h = (q < ot) ? nh : h; }
;                 h = pA[dir][ct] * h + pH[dir][ct];
; #pragma unroll
;                 for (int ee = 0; ee < 4; ++ee) { const int e = dir ? 3 - ee : ee; h = av[dir][ct][e] * h + uv[dir][ct][e];
;                     ((LAS float*)(lds + LR_HB))[(dir * LCH + 16 * rt + 4 * fq + e) * 68 + ch] = h; } } }
;         __syncthreads();
	v_fma_f32 v38, v76, v38, v39
	v_cndmask_b32_e64 v38, v76, v38, s[72:73]
	v_fmac_f32_e32 v37, v36, v38
	v_cndmask_b32_e64 v38, v38, v37, s[74:75]
	ds_read_b64 v[208:209], v176 offset:65280
	ds_read_b64 v[210:211], v176 offset:64768
	ds_read_b64 v[212:213], v176 offset:64256
	ds_read_b64 v[214:215], v176 offset:63744
	ds_read_b64 v[216:217], v176 offset:63232
	s_waitcnt lgkmcnt(0)
	v_fmac_f32_e32 v209, v208, v38
	v_cndmask_b32_e64 v38, v38, v209, s[76:77]
	v_fmac_f32_e32 v211, v210, v38
	v_cndmask_b32_e64 v38, v38, v211, s[78:79]
	v_fmac_f32_e32 v213, v212, v38
	v_cndmask_b32_e64 v38, v38, v213, s[80:81]
	v_fmac_f32_e32 v215, v214, v38
	v_cndmask_b32_e64 v38, v38, v215, s[82:83]
	v_fmac_f32_e32 v217, v216, v38
	v_cndmask_b32_e64 v36, v38, v217, s[84:85]
	v_fmac_f32_e32 v57, v55, v36
	v_fmac_f32_e32 v103, v100, v57
	v_fmac_f32_e32 v106, v105, v103
	v_fmac_f32_e32 v53, v51, v106
	v_add_u32_e32 v36, 0x8800, v202
	v_fmac_f32_e32 v110, v109, v53
	ds_write2_b32 v36, v106, v103 offset0:136 offset1:204
	ds_write2_b32 v36, v110, v53 offset1:68
	ds_read2st64_b64 v[36:39], v191 offset0:6 offset1:7
	v_lshlrev_b32_e32 v53, 16, v19
	v_and_b32_e32 v19, 0xffff0000, v19
	s_waitcnt lgkmcnt(0)
	v_fma_f32 v38, v74, v38, v39
	v_cndmask_b32_e64 v38, v74, v38, s[72:73]
	v_fmac_f32_e32 v37, v36, v38
	v_cndmask_b32_e64 v38, v38, v37, s[74:75]
	ds_read_b64 v[222:223], v176 offset:65408
	ds_read_b64 v[224:225], v176 offset:64896
	ds_read_b64 v[226:227], v176 offset:64384
	ds_read_b64 v[228:229], v176 offset:63872
	ds_read_b64 v[234:235], v176 offset:63360
	s_waitcnt lgkmcnt(0)
	v_fmac_f32_e32 v223, v222, v38
	v_cndmask_b32_e64 v38, v38, v223, s[76:77]
	v_fmac_f32_e32 v225, v224, v38
	v_cndmask_b32_e64 v38, v38, v225, s[78:79]
	v_fmac_f32_e32 v227, v226, v38
	v_cndmask_b32_e64 v38, v38, v227, s[80:81]
	v_fmac_f32_e32 v229, v228, v38
	v_cndmask_b32_e64 v38, v38, v229, s[82:83]
	v_fmac_f32_e32 v235, v234, v38
	v_cndmask_b32_e64 v36, v38, v235, s[84:85]
	v_fmac_f32_e32 v64, v62, v36
	v_fmac_f32_e32 v115, v112, v64
	v_fmac_f32_e32 v118, v117, v115
	v_fmac_f32_e32 v60, v58, v118
	v_add_u32_e32 v36, 0x8800, v203
	v_fmac_f32_e32 v122, v121, v60
	ds_write2_b32 v36, v118, v115 offset0:136 offset1:204
	ds_write2_b32 v36, v122, v60 offset1:68
	ds_read_b64 v[36:37], v192 offset:3584
	s_waitcnt lgkmcnt(0)
	v_fmac_f32_e32 v37, v73, v36
	v_cndmask_b32_e64 v40, v73, v37, s[72:73]
	ds_read2st64_b64 v[36:39], v192 offset0:5 offset1:6
	s_waitcnt lgkmcnt(0)
	v_fma_f32 v38, v38, v40, v39
	v_cndmask_b32_e64 v38, v40, v38, s[74:75]
	v_fmac_f32_e32 v37, v36, v38
	v_cndmask_b32_e64 v38, v38, v37, s[76:77]
	ds_read_b64 v[208:209], v176 offset:65024
	ds_read_b64 v[210:211], v176 offset:64512
	ds_read_b64 v[212:213], v176 offset:64000
	ds_read_b64 v[214:215], v176 offset:63488
	s_waitcnt lgkmcnt(0)
	v_fmac_f32_e32 v209, v208, v38
	v_cndmask_b32_e64 v38, v38, v209, s[78:79]
	v_fmac_f32_e32 v211, v210, v38
	v_cndmask_b32_e64 v38, v38, v211, s[80:81]
	v_fmac_f32_e32 v213, v212, v38
	v_cndmask_b32_e64 v38, v38, v213, s[82:83]
	v_fmac_f32_e32 v215, v214, v38
	v_cndmask_b32_e64 v36, v38, v215, s[84:85]
	v_fmac_f32_e32 v69, v26, v36
	v_fmac_f32_e32 v127, v124, v69
	v_fmac_f32_e32 v128, v29, v127
	v_fmac_f32_e32 v67, v28, v128
	v_add_u32_e32 v26, 0x8800, v204
	v_fmac_f32_e32 v130, v27, v67
	ds_write2_b32 v26, v128, v127 offset0:136 offset1:204
	ds_write2_b32 v26, v130, v67 offset1:68
	ds_read_b64 v[26:27], v194 offset:3584
	s_waitcnt lgkmcnt(0)
	v_fmac_f32_e32 v27, v71, v26
	v_cndmask_b32_e64 v36, v71, v27, s[72:73]
	ds_read2st64_b64 v[26:29], v194 offset0:5 offset1:6
	s_waitcnt lgkmcnt(0)
	v_fma_f32 v28, v28, v36, v29
	v_cndmask_b32_e64 v28, v36, v28, s[74:75]
	v_fmac_f32_e32 v27, v26, v28
	v_cndmask_b32_e64 v28, v28, v27, s[76:77]
	ds_read_b64 v[222:223], v176 offset:65152
	ds_read_b64 v[224:225], v176 offset:64640
	ds_read_b64 v[226:227], v176 offset:64128
	ds_read_b64 v[228:229], v176 offset:63616
	s_waitcnt lgkmcnt(0)
	v_fmac_f32_e32 v223, v222, v28
	v_cndmask_b32_e64 v28, v28, v223, s[78:79]
	v_fmac_f32_e32 v225, v224, v28
	v_cndmask_b32_e64 v28, v28, v225, s[80:81]
	v_fmac_f32_e32 v227, v226, v28
	v_cndmask_b32_e64 v28, v28, v227, s[82:83]
	v_fmac_f32_e32 v229, v228, v28
	v_cndmask_b32_e64 v26, v28, v229, s[84:85]
	v_fmac_f32_e32 v31, v22, v26
	v_fmac_f32_e32 v135, v132, v31
	v_fmac_f32_e32 v136, v25, v135
	v_fmac_f32_e32 v24, v1, v136
	v_add_u32_e32 v22, 0x8800, v205
	v_fmac_f32_e32 v138, v23, v24
	ds_write2_b32 v22, v136, v135 offset0:136 offset1:204
	ds_write2_b32 v22, v138, v24 offset1:68
	s_waitcnt lgkmcnt(0)
	s_barrier
; #define LAS __attribute__((address_space(3)))
; __device__ __forceinline__ unsigned pk2(float lo, float hi) { return f2bf(lo) | (f2bf(hi) << 16); }
; template <bool PHASE_B>
; __device__ __forceinline__ void lru_item(const Params& p, LAS unsigned char* lds, int ci, int ci_next, int jb, const int tid, v4u (&xvn)[3]) {
;     ...
;         { const int t = tid >> 2, c0 = (tid & 3) * 16; bf16* gp = (bf16*)(p.ws + WS_GR) + (size_t)(t0 + t) * 768 + jb * 64 + c0;
;           const LAS float* H0 = (const LAS float*)(lds + LR_HB) + t * 68 + c0; const LAS float* H1 = H0 + LCH * 68;
; #pragma unroll
;           for (int hf = 0; hf < 2; ++hf) { const f32x4 a0 = *(const LAS f32x4*)(H0 + 8 * hf), a1 = *(const LAS f32x4*)(H0 + 8 * hf + 4), b0 = *(const LAS f32x4*)(H1 + 8 * hf), b1 = *(const LAS f32x4*)(H1 + 8 * hf + 4);
;               const v4u g = gv[hf]; v4u o;
;               o.x = pk2(bflo(g.x) * (a0[0] + b0[0]), bfhi(g.x) * (a0[1] + b0[1])); o.y = pk2(bflo(g.y) * (a0[2] + b0[2]), bfhi(g.y) * (a0[3] + b0[3]));
;               o.z = pk2(bflo(g.z) * (a1[0] + b1[0]), bfhi(g.z) * (a1[1] + b1[1])); o.w = pk2(bflo(g.w) * (a1[2] + b1[2]), bfhi(g.w) * (a1[3] + b1[3]));
;               *(v4u*)(gp + 8 * hf) = o; } }
	ds_read_b128 v[22:25], v195
	ds_read_b128 v[26:29], v195 offset:16
	ds_read_b128 v[36:39], v195 offset:32
	ds_read_b128 v[40:43], v195 offset:48
	ds_read_b128 v[44:47], v195 offset:34816
	ds_read_b128 v[48:51], v195 offset:34832
	s_waitcnt lgkmcnt(1)
	v_pk_add_f32 v[24:25], v[24:25], v[46:47]
	v_pk_add_f32 v[22:23], v[22:23], v[44:45]
	v_mov_b32_e32 v45, v24
	v_mov_b32_e32 v24, v23
	v_pk_mul_f32 v[18:19], v[24:25], v[18:19]
	s_waitcnt lgkmcnt(0)
	v_pk_add_f32 v[24:25], v[28:29], v[50:51]
	v_pk_add_f32 v[26:27], v[26:27], v[48:49]
	v_mov_b32_e32 v44, v22
	v_lshlrev_b32_e32 v23, 16, v21
	v_lshlrev_b32_e32 v22, 16, v20
	v_mov_b32_e32 v29, v24
	v_and_b32_e32 v21, 0xffff0000, v21
	v_and_b32_e32 v20, 0xffff0000, v20
	v_mov_b32_e32 v24, v27
	v_mov_b32_e32 v28, v26
	v_pk_mul_f32 v[20:21], v[24:25], v[20:21]
	v_pk_mul_f32 v[44:45], v[44:45], v[52:53]
	v_pk_mul_f32 v[22:23], v[28:29], v[22:23]
	v_bfe_u32 v1, v21, 16, 1
	v_add3_u32 v1, v21, v1, s33
	v_bfe_u32 v26, v23, 16, 1
	v_add3_u32 v23, v23, v26, s33
	v_lshrrev_b32_e32 v21, 16, v23
	v_and_or_b32 v21, v1, s11, v21
	v_cvt_pk_bf16_f32 v20, v22, v20
	v_cvt_pk_bf16_f32 v19, v45, v19
	v_cvt_pk_bf16_f32 v18, v44, v18
	global_store_dwordx4 v[140:141], v[18:21], off
	ds_read_b128 v[18:21], v195 offset:34848
	ds_read_b128 v[22:25], v195 offset:34864
	v_lshlrev_b32_e32 v27, 16, v15
	v_lshlrev_b32_e32 v26, 16, v14
	v_and_b32_e32 v15, 0xffff0000, v15
	s_waitcnt lgkmcnt(1)
	v_pk_add_f32 v[20:21], v[38:39], v[20:21]
	v_pk_add_f32 v[18:19], v[36:37], v[18:19]
	v_mov_b32_e32 v29, v20
	v_and_b32_e32 v14, 0xffff0000, v14
	v_mov_b32_e32 v20, v19
	v_pk_mul_f32 v[14:15], v[20:21], v[14:15]
	s_waitcnt lgkmcnt(0)
	v_pk_add_f32 v[20:21], v[42:43], v[24:25]
	v_pk_add_f32 v[22:23], v[40:41], v[22:23]
	v_mov_b32_e32 v28, v18
	v_lshlrev_b32_e32 v19, 16, v17
	v_lshlrev_b32_e32 v18, 16, v16
	v_mov_b32_e32 v25, v20
	v_and_b32_e32 v17, 0xffff0000, v17
	v_and_b32_e32 v16, 0xffff0000, v16
	v_mov_b32_e32 v20, v23
	v_mov_b32_e32 v24, v22
	v_pk_mul_f32 v[16:17], v[20:21], v[16:17]
	v_pk_mul_f32 v[26:27], v[28:29], v[26:27]
	v_pk_mul_f32 v[18:19], v[24:25], v[18:19]
	v_bfe_u32 v1, v17, 16, 1
	v_bfe_u32 v20, v16, 16, 1
	v_add3_u32 v16, v16, v20, s33
	v_add3_u32 v1, v17, v1, s33
	v_bfe_u32 v21, v18, 16, 1
	v_bfe_u32 v22, v19, 16, 1
	v_add3_u32 v19, v19, v22, s33
	v_add3_u32 v18, v18, v21, s33
	v_lshrrev_b32_e32 v21, 16, v17
	v_lshrrev_b32_e32 v20, 16, v20
	v_lshrrev_b32_e32 v18, 16, v18
	v_lshrrev_b32_e32 v17, 16, v19
	v_and_or_b32 v17, v1, s11, v17
	v_and_or_b32 v16, v16, s11, v18
	v_cvt_pk_bf16_f32 v15, v27, v15
	v_cvt_pk_bf16_f32 v14, v26, v14
	global_store_dwordx4 v[140:141], v[14:17], off offset:16
	s_cbranch_vccnz .LBB0_353

; #define LAS __attribute__((address_space(3)))
; __device__ __forceinline__ unsigned pk2(float lo, float hi) { return f2bf(lo) | (f2bf(hi) << 16); }
; template <bool PHASE_B>
; __device__ __forceinline__ void lru_item(const Params& p, LAS unsigned char* lds, int ci, int ci_next, int jb, const int tid, v4u (&xvn)[3]) {
;     ...
;     for (int ks = 0; ks < 2; ++ks) { const int cb0 = 32 * ks + 8 * fq;
;         f32x4 s0 = *(const LAS f32x4*)(CB + cb0), s1 = *(const LAS f32x4*)(CB + cb0 + 4);
; #pragma unroll
;         for (int tap = 0; tap < 4; ++tap) { const v4u v = *(const LAS v4u*)(lds + LR_XR + (16 * rt + fr + tap) * 144 + cb0 * 2);
;             const f32x4 w0 = *(const LAS f32x4*)(CW + tap * 64 + cb0), w1 = *(const LAS f32x4*)(CW + tap * 64 + cb0 + 4);
;             s0 += (f32x4){bflo(v.x), bfhi(v.x), bflo(v.y), bfhi(v.y)} * w0; s1 += (f32x4){bflo(v.z), bfhi(v.z), bflo(v.w), bfhi(v.w)} * w1; }
;         v4u o; o.x = pk2(s0[0], s0[1]); o.y = pk2(s0[2], s0[3]); o.z = pk2(s1[0], s1[1]); o.w = pk2(s1[2], s1[3]);
;         af[ks] = __builtin_bit_cast(bf16x8, o); }
.LBB0_541:
	ds_read_b128 v[14:17], v88
	ds_read_b128 v[18:21], v78 offset:56832
	ds_read_b128 v[26:29], v78 offset:56848
	ds_read_b128 v[30:33], v78 offset:55808
	ds_read_b128 v[34:37], v78 offset:55824
	ds_read_b128 v[38:41], v88 offset:144
	s_waitcnt lgkmcnt(5)
	v_lshlrev_b32_e32 v42, 16, v14
	v_and_b32_e32 v43, 0xffff0000, v14
	v_lshlrev_b32_e32 v14, 16, v15
	v_and_b32_e32 v15, 0xffff0000, v15
	s_waitcnt lgkmcnt(2)
	v_pk_fma_f32 v[32:33], v[32:33], v[14:15], v[20:21]
	v_lshlrev_b32_e32 v14, 16, v16
	v_and_b32_e32 v15, 0xffff0000, v16
	v_lshlrev_b32_e32 v16, 16, v17
	v_and_b32_e32 v17, 0xffff0000, v17
	v_pk_fma_f32 v[30:31], v[30:31], v[42:43], v[18:19]
	s_waitcnt lgkmcnt(1)
	v_pk_fma_f32 v[26:27], v[34:35], v[14:15], v[26:27]
	v_pk_fma_f32 v[28:29], v[36:37], v[16:17], v[28:29]
	ds_read_b128 v[14:17], v78 offset:56064
	ds_read_b128 v[18:21], v78 offset:56080
	s_waitcnt lgkmcnt(2)
	v_lshlrev_b32_e32 v34, 16, v38
	v_and_b32_e32 v35, 0xffff0000, v38
	v_lshlrev_b32_e32 v36, 16, v39
	v_and_b32_e32 v37, 0xffff0000, v39
	s_waitcnt lgkmcnt(1)
	v_pk_fma_f32 v[34:35], v[14:15], v[34:35], v[30:31]
	v_lshlrev_b32_e32 v14, 16, v41
	v_and_b32_e32 v15, 0xffff0000, v41
	v_pk_fma_f32 v[36:37], v[16:17], v[36:37], v[32:33]
	s_waitcnt lgkmcnt(0)
	v_pk_fma_f32 v[38:39], v[20:21], v[14:15], v[28:29]
	ds_read_b128 v[14:17], v88 offset:288
	v_lshlrev_b32_e32 v30, 16, v40
	v_and_b32_e32 v31, 0xffff0000, v40
	v_pk_fma_f32 v[40:41], v[18:19], v[30:31], v[26:27]
	ds_read_b128 v[18:21], v78 offset:56320
	ds_read_b128 v[26:29], v78 offset:56336
	ds_read_b128 v[30:33], v88 offset:432
	s_waitcnt lgkmcnt(3)
	v_lshlrev_b32_e32 v42, 16, v14
	v_and_b32_e32 v43, 0xffff0000, v14
	v_lshlrev_b32_e32 v14, 16, v15
	v_and_b32_e32 v15, 0xffff0000, v15
	s_waitcnt lgkmcnt(2)
	v_pk_fma_f32 v[36:37], v[20:21], v[14:15], v[36:37]
	v_lshlrev_b32_e32 v14, 16, v16
	v_and_b32_e32 v15, 0xffff0000, v16
	v_lshlrev_b32_e32 v16, 16, v17
	v_and_b32_e32 v17, 0xffff0000, v17
	v_pk_fma_f32 v[34:35], v[18:19], v[42:43], v[34:35]
	s_waitcnt lgkmcnt(1)
	v_pk_fma_f32 v[26:27], v[26:27], v[14:15], v[40:41]
	v_pk_fma_f32 v[28:29], v[28:29], v[16:17], v[38:39]
	ds_read_b128 v[14:17], v78 offset:56576
	ds_read_b128 v[18:21], v78 offset:56592
	s_waitcnt lgkmcnt(2)
	v_lshlrev_b32_e32 v38, 16, v30
	v_and_b32_e32 v39, 0xffff0000, v30
	v_lshlrev_b32_e32 v30, 16, v31
	s_waitcnt lgkmcnt(1)
	v_pk_fma_f32 v[14:15], v[14:15], v[38:39], v[34:35]
	v_and_b32_e32 v31, 0xffff0000, v31
	v_bfe_u32 v1, v14, 16, 1
	v_add3_u32 v1, v14, v1, s33
	v_bfe_u32 v14, v15, 16, 1
	v_pk_fma_f32 v[16:17], v[16:17], v[30:31], v[36:37]
	v_lshrrev_b32_e32 v1, 16, v1
	v_add3_u32 v14, v15, v14, s33
	v_and_or_b32 v14, v14, s11, v1
	v_lshlrev_b32_e32 v30, 16, v32
	v_and_b32_e32 v31, 0xffff0000, v32
	s_waitcnt lgkmcnt(0)
	v_pk_fma_f32 v[18:19], v[18:19], v[30:31], v[26:27]
	v_cvt_pk_bf16_f32 v15, v16, v17
	v_lshlrev_b32_e32 v32, 16, v33
	v_and_b32_e32 v33, 0xffff0000, v33
	v_pk_fma_f32 v[20:21], v[20:21], v[32:33], v[28:29]
	v_cvt_pk_bf16_f32 v16, v18, v19
	v_bfe_u32 v1, v20, 16, 1
	v_bfe_u32 v17, v21, 16, 1
	v_add3_u32 v1, v20, v1, s33
	v_add3_u32 v17, v21, v17, s33
	ds_read_b128 v[18:21], v89
	ds_read_b128 v[26:29], v78 offset:56960
	ds_read_b128 v[30:33], v78 offset:56976
	ds_read_b128 v[34:37], v78 offset:55936
	ds_read_b128 v[38:41], v78 offset:55952
	ds_read_b128 v[42:45], v89 offset:144
	s_waitcnt lgkmcnt(5)
	v_lshlrev_b32_e32 v46, 16, v18
	v_and_b32_e32 v47, 0xffff0000, v18
	v_lshlrev_b32_e32 v18, 16, v19
	v_and_b32_e32 v19, 0xffff0000, v19
	s_waitcnt lgkmcnt(2)
	v_pk_fma_f32 v[36:37], v[36:37], v[18:19], v[28:29]
	v_lshlrev_b32_e32 v18, 16, v20
	v_and_b32_e32 v19, 0xffff0000, v20
	v_lshlrev_b32_e32 v20, 16, v21
	v_and_b32_e32 v21, 0xffff0000, v21
	v_pk_fma_f32 v[34:35], v[34:35], v[46:47], v[26:27]
	s_waitcnt lgkmcnt(1)
	v_pk_fma_f32 v[30:31], v[38:39], v[18:19], v[30:31]
	v_pk_fma_f32 v[32:33], v[40:41], v[20:21], v[32:33]
	ds_read_b128 v[18:21], v78 offset:56192
	ds_read_b128 v[26:29], v78 offset:56208
	s_waitcnt lgkmcnt(2)
	v_lshlrev_b32_e32 v38, 16, v42
	v_and_b32_e32 v39, 0xffff0000, v42
	v_lshlrev_b32_e32 v40, 16, v43
	v_and_b32_e32 v41, 0xffff0000, v43
	s_waitcnt lgkmcnt(1)
	v_pk_fma_f32 v[38:39], v[18:19], v[38:39], v[34:35]
	v_lshlrev_b32_e32 v18, 16, v45
	v_and_b32_e32 v19, 0xffff0000, v45
	v_pk_fma_f32 v[40:41], v[20:21], v[40:41], v[36:37]
	s_waitcnt lgkmcnt(0)
	v_pk_fma_f32 v[42:43], v[28:29], v[18:19], v[32:33]
	ds_read_b128 v[18:21], v89 offset:288
	v_lshlrev_b32_e32 v34, 16, v44
	v_and_b32_e32 v35, 0xffff0000, v44
	v_pk_fma_f32 v[44:45], v[26:27], v[34:35], v[30:31]
	ds_read_b128 v[26:29], v78 offset:56448
	ds_read_b128 v[30:33], v78 offset:56464
	ds_read_b128 v[34:37], v89 offset:432
	s_waitcnt lgkmcnt(3)
	v_lshlrev_b32_e32 v46, 16, v18
	v_and_b32_e32 v47, 0xffff0000, v18
	v_lshlrev_b32_e32 v18, 16, v19
	v_and_b32_e32 v19, 0xffff0000, v19
	s_waitcnt lgkmcnt(2)
	v_pk_fma_f32 v[40:41], v[28:29], v[18:19], v[40:41]
	v_lshlrev_b32_e32 v18, 16, v20
	v_and_b32_e32 v19, 0xffff0000, v20
	v_lshlrev_b32_e32 v20, 16, v21
	v_and_b32_e32 v21, 0xffff0000, v21
	v_pk_fma_f32 v[38:39], v[26:27], v[46:47], v[38:39]
	s_waitcnt lgkmcnt(1)
	v_pk_fma_f32 v[30:31], v[30:31], v[18:19], v[44:45]
	v_pk_fma_f32 v[32:33], v[32:33], v[20:21], v[42:43]
	ds_read_b128 v[18:21], v78 offset:56704
	ds_read_b128 v[26:29], v78 offset:56720
	s_waitcnt lgkmcnt(2)
	v_lshlrev_b32_e32 v42, 16, v34
	v_and_b32_e32 v43, 0xffff0000, v34
	v_lshlrev_b32_e32 v34, 16, v35
	s_waitcnt lgkmcnt(1)
; #define LAS __attribute__((address_space(3)))
; #define MFMA16(a, b, c) __builtin_amdgcn_mfma_f32_16x16x32_bf16(a, b, c, 0, 0, 0)
; template <bool PHASE_B>
; __device__ __forceinline__ void lru_item(const Params& p, LAS unsigned char* lds, int ci, int ci_next, int jb, const int tid, v4u (&xvn)[3]) {
;     ...
;     float xc[4][4];
; #pragma unroll
;     for (int ct = 0; ct < 4; ++ct) { const int ch = 16 * ct + fr; float xr7[7];
; #pragma unroll
;         for (int j = 0; j < 7; ++j) xr7[j] = __builtin_bit_cast(float, (unsigned)(*(const LAS bf16*)(lds + LR_XR + (16 * rt + 4 * fq + j) * 144 + ch * 2)) << 16);
;         const float w0 = CW[ch], w1 = CW[64 + ch], w2 = CW[128 + ch], w3 = CW[192 + ch], b = CB[ch];
; #pragma unroll
;         for (int e = 0; e < 4; ++e) xc[ct][e] = b + xr7[e] * w0 + xr7[e + 1] * w1 + xr7[e + 2] * w2 + xr7[e + 3] * w3; }
;     float av[2][4][4], uv[2][4][4], pA[2][4], pH[2][4];
; #pragma unroll
;     for (int dir = 0; dir < 2; ++dir) {
; #pragma unroll
;         for (int ct = 0; ct < 4; ++ct) {
;             f32x4 ga = (f32x4){0.f, 0.f, 0.f, 0.f}, gx = (f32x4){0.f, 0.f, 0.f, 0.f};
; #pragma unroll
;             for (int ks = 0; ks < 2; ++ks) {
;                 const bf16x8 wa = *(const LAS bf16x8*)(lds + LR_WG + ((dir * 2 + 0) * 64 + 16 * ct + fr) * 144 + (32 * ks + 8 * fq) * 2);
;                 const bf16x8 wx = *(const LAS bf16x8*)(lds + LR_WG + ((dir * 2 + 1) * 64 + 16 * ct + fr) * 144 + (32 * ks + 8 * fq) * 2);
;                 ga = MFMA16(af[ks], wa, ga); gx = MFMA16(af[ks], wx, gx); }
;             const int ch = 16 * ct + fr; const float bav = GC[(dir * 3 + 0) * 64 + ch], bxv = GC[(dir * 3 + 1) * 64 + ch], c8 = GC[(dir * 3 + 2) * 64 + ch];
;             float Al = 1.f, Hl = 0.f;
; #pragma unroll
;             for (int ee = 0; ee < 4; ++ee) { const int e = dir ? 3 - ee : ee;
;                 const float r = __builtin_amdgcn_rcpf(1.f + __expf(-(ga[e] + bav))), ig = __builtin_amdgcn_rcpf(1.f + __expf(-(gx[e] + bxv)));
;                 const float la = -c8 * r; const float a = __expf(la); const float u = __builtin_amdgcn_sqrtf((1.f - a) * (1.f + a)) * (ig * xc[ct][e]);
;                 av[dir][ct][e] = a; uv[dir][ct][e] = u; Hl = a * Hl + u; Al *= a; }
	v_pk_fma_f32 v[18:19], v[18:19], v[42:43], v[38:39]
	v_and_b32_e32 v35, 0xffff0000, v35
	v_pk_fma_f32 v[20:21], v[20:21], v[34:35], v[40:41]
	v_cvt_pk_bf16_f32 v18, v18, v19
	v_bfe_u32 v19, v20, 16, 1
	v_lshlrev_b32_e32 v34, 16, v36
	v_and_b32_e32 v35, 0xffff0000, v36
	v_lshlrev_b32_e32 v36, 16, v37
	v_and_b32_e32 v37, 0xffff0000, v37
	v_add3_u32 v19, v20, v19, s33
	v_bfe_u32 v20, v21, 16, 1
	s_waitcnt lgkmcnt(0)
	v_pk_fma_f32 v[28:29], v[28:29], v[36:37], v[32:33]
	v_pk_fma_f32 v[26:27], v[26:27], v[34:35], v[30:31]
	v_lshrrev_b32_e32 v19, 16, v19
	v_add3_u32 v20, v21, v20, s33
	v_and_or_b32 v19, v20, s11, v19
	v_bfe_u32 v20, v26, 16, 1
	v_bfe_u32 v23, v29, 16, 1
	v_add3_u32 v20, v26, v20, s33
	v_bfe_u32 v21, v27, 16, 1
	v_add3_u32 v32, v29, v23, s33
	v_add_u32_e32 v23, v80, v81
	v_add_u32_e32 v30, 0xd800, v82
	v_add_u32_e32 v58, 0xdc00, v82
	v_lshrrev_b32_e32 v20, 16, v20
	v_add3_u32 v21, v27, v21, s33
	ds_read_u16 v49, v23
	ds_read_u16 v51, v23 offset:144
	ds_read_u16 v60, v23 offset:288
	ds_read_u16 v26, v23 offset:864
	ds_read_u16 v70, v23 offset:432
	ds_read_u16 v109, v23 offset:576
	ds_read_u16 v116, v90
	ds_read_u16 v110, v23 offset:720
	ds_read2_b32 v[46:47], v30 offset0:128 offset1:144
	ds_read2_b32 v[40:41], v30 offset0:192 offset1:208
	ds_read2_b32 v[52:53], v58 offset1:16
	ds_read2_b32 v[44:45], v58 offset0:64 offset1:80
	ds_read2_b32 v[34:35], v58 offset0:128 offset1:144
	ds_read_u16 v117, v90 offset:144
	ds_read_u16 v118, v90 offset:288
	ds_read_u16 v119, v90 offset:432
	ds_read_u16 v23, v90 offset:864
	ds_read_u16 v120, v90 offset:576
	ds_read_u16 v123, v91
	ds_read_u16 v122, v91 offset:144
	ds_read_u16 v121, v90 offset:720
	v_and_or_b32 v20, v21, s11, v20
	v_bfe_u32 v21, v28, 16, 1
	s_waitcnt lgkmcnt(4)
	v_lshlrev_b32_e32 v50, 16, v23
	v_add_u32_e32 v23, v85, v79
	v_add3_u32 v21, v28, v21, s33
	v_lshlrev_b32_e32 v48, 16, v26
	ds_read_u16 v124, v91 offset:288
	ds_read_u16 v125, v91 offset:432
	ds_read_u16 v126, v91 offset:576
	ds_read_u16 v127, v91 offset:720
	ds_read_u16 v31, v91 offset:864
	ds_read_u16 v43, v92
	ds_read_u16 v61, v92 offset:144
	ds_read_u16 v103, v92 offset:288
	ds_read_b128 v[26:29], v23 offset:18944
	v_perm_b32 v17, v17, v1, s65
	ds_read2_b32 v[38:39], v30 offset0:160 offset1:176
	ds_read_b128 v[54:57], v23 offset:28160
	ds_read_b128 v[62:65], v23 offset:19008
	v_perm_b32 v21, v32, v21, s65
	s_waitcnt lgkmcnt(3)
	v_mfma_f32_16x16x32_bf16 v[66:69], v[14:17], v[26:29], 0
	v_lshlrev_b32_e32 v42, 16, v31
	ds_read2_b32 v[30:31], v30 offset0:224 offset1:240
	ds_read_b128 v[104:107], v23 offset:28224
	ds_read2_b32 v[36:37], v58 offset0:32 offset1:48
	ds_read2_b32 v[32:33], v58 offset0:96 offset1:112
	ds_read2_b32 v[26:27], v58 offset0:160 offset1:176
	s_waitcnt lgkmcnt(6)
	v_mfma_f32_16x16x32_bf16 v[54:57], v[14:17], v[54:57], 0
	v_lshlrev_b32_e32 v71, 16, v49
	v_lshlrev_b32_e32 v122, 16, v122
	v_lshlrev_b32_e32 v123, 16, v123
	s_waitcnt lgkmcnt(5)
	v_mfma_f32_16x16x32_bf16 v[62:65], v[18:21], v[62:65], v[66:69]
	s_nop 2
	ds_read_b32 v66, v93 offset:57088
	ds_read_u16 v128, v92 offset:432
	ds_read_u16 v102, v92 offset:576
	ds_read_u16 v29, v92 offset:720
	ds_read_u16 v1, v92 offset:864
	v_mov_b32_e32 v67, v46
	s_waitcnt lgkmcnt(4)
	v_add_f32_e32 v28, v62, v66
	v_mfma_f32_16x16x32_bf16 v[56:59], v[18:21], v[104:107], v[54:57]
	ds_read_b128 v[198:201], v23 offset:21248
	ds_read_b128 v[202:205], v23 offset:21312
	ds_read_b128 v[206:209], v23 offset:30464
	ds_read_b128 v[210:213], v23 offset:30528
	s_nop 2
	ds_read_b32 v54, v93 offset:57344
	ds_read_b32 v55, v93 offset:57600
	v_mul_f32_e32 v28, 0xbfb8aa3b, v28
	v_exp_f32_e32 v28, v28
	s_waitcnt lgkmcnt(1)
	v_add_f32_e32 v56, v56, v54
	v_mul_f32_e32 v56, 0xbfb8aa3b, v56
	v_exp_f32_e32 v56, v56
	v_add_f32_e32 v28, 1.0, v28
	v_rcp_f32_e32 v62, v28
	v_lshlrev_b32_e32 v28, 16, v1
	v_add_f32_e32 v1, 1.0, v56
	v_rcp_f32_e32 v129, v1
	s_waitcnt lgkmcnt(0)
	v_mul_f32_e32 v1, v62, v55
	v_mul_f32_e32 v1, 0xbfb8aa3b, v1
	v_exp_f32_e32 v56, v1
	v_add_f32_e32 v1, v63, v66
	v_mul_f32_e32 v1, 0xbfb8aa3b, v1
	v_exp_f32_e32 v1, v1
	v_add_f32_e32 v57, v57, v54
	v_sub_f32_e32 v62, 1.0, v56
	v_add_f32_e32 v63, 1.0, v56
	v_add_f32_e32 v1, 1.0, v1
	v_rcp_f32_e32 v1, v1
	v_mul_f32_e32 v57, 0xbfb8aa3b, v57
	v_mul_f32_e32 v62, v62, v63
	v_exp_f32_e32 v57, v57
	v_mul_f32_e32 v1, v1, v55
	v_mul_f32_e32 v1, 0xbfb8aa3b, v1
	v_exp_f32_e32 v130, v1
	v_sqrt_f32_e32 v1, v62
	v_add_f32_e32 v62, v64, v66
	v_mul_f32_e32 v62, 0xbfb8aa3b, v62
	v_exp_f32_e32 v62, v62
	v_add_f32_e32 v57, 1.0, v57
	v_rcp_f32_e32 v131, v57
	v_sub_f32_e32 v57, 1.0, v130
	v_add_f32_e32 v63, 1.0, v130
	v_mul_f32_e32 v57, v57, v63
	v_sqrt_f32_e32 v63, v57
	v_add_f32_e32 v57, 1.0, v62
	v_rcp_f32_e32 v57, v57
	v_add_f32_e32 v58, v58, v54
	v_mul_f32_e32 v58, 0xbfb8aa3b, v58
	v_exp_f32_e32 v58, v58
	v_mul_f32_e32 v57, v57, v55
	v_mul_f32_e32 v57, 0xbfb8aa3b, v57
	v_exp_f32_e32 v105, v57
	v_add_f32_e32 v62, v65, v66
	v_mul_f32_e32 v62, 0xbfb8aa3b, v62
	v_exp_f32_e32 v62, v62
	v_add_f32_e32 v58, 1.0, v58
	v_rcp_f32_e32 v132, v58
	v_sub_f32_e32 v58, 1.0, v105
	v_add_f32_e32 v64, 1.0, v105
	v_mul_f32_e32 v58, v58, v64
	v_sqrt_f32_e32 v65, v58
	v_add_f32_e32 v58, 1.0, v62
	v_rcp_f32_e32 v58, v58
	v_add_f32_e32 v54, v59, v54
	v_mul_f32_e32 v54, 0xbfb8aa3b, v54
	v_exp_f32_e32 v54, v54
	v_mul_f32_e32 v55, v58, v55
	v_mul_f32_e32 v55, 0xbfb8aa3b, v55
	v_exp_f32_e32 v59, v55
	v_add_f32_e32 v54, 1.0, v54
	v_rcp_f32_e32 v58, v54
	v_mov_b32_e32 v66, v40
	v_sub_f32_e32 v54, 1.0, v59
	v_add_f32_e32 v55, 1.0, v59
	v_mul_f32_e32 v54, v54, v55
	v_sqrt_f32_e32 v133, v54
	v_lshlrev_b32_e32 v55, 16, v60
	v_lshlrev_b32_e32 v54, 16, v70
; #define LAS __attribute__((address_space(3)))
; template <bool PHASE_B>
; __device__ __forceinline__ void lru_item(const Params& p, LAS unsigned char* lds, int ci, int ci_next, int jb, const int tid, v4u (&xvn)[3]) {
;     ...
;         for (int j = 0; j < 7; ++j) xr7[j] = __builtin_bit_cast(float, (unsigned)(*(const LAS bf16*)(lds + LR_XR + (16 * rt + 4 * fq + j) * 144 + ch * 2)) << 16);
;         const float w0 = CW[ch], w1 = CW[64 + ch], w2 = CW[128 + ch], w3 = CW[192 + ch], b = CB[ch];
; #pragma unroll
;         for (int e = 0; e < 4; ++e) xc[ct][e] = b + xr7[e] * w0 + xr7[e + 1] * w1 + xr7[e + 2] * w2 + xr7[e + 3] * w3; }
;     float av[2][4][4], uv[2][4][4], pA[2][4], pH[2][4];
; #pragma unroll
;     for (int dir = 0; dir < 2; ++dir) {
; #pragma unroll
;         for (int ct = 0; ct < 4; ++ct) {
;             f32x4 ga = (f32x4){0.f, 0.f, 0.f, 0.f}, gx = (f32x4){0.f, 0.f, 0.f, 0.f};
; #pragma unroll
;             for (int ks = 0; ks < 2; ++ks) {
;                 const bf16x8 wa = *(const LAS bf16x8*)(lds + LR_WG + ((dir * 2 + 0) * 64 + 16 * ct + fr) * 144 + (32 * ks + 8 * fq) * 2);
;                 const bf16x8 wx = *(const LAS bf16x8*)(lds + LR_WG + ((dir * 2 + 1) * 64 + 16 * ct + fr) * 144 + (32 * ks + 8 * fq) * 2);
;                 ga = MFMA16(af[ks], wa, ga); gx = MFMA16(af[ks], wx, gx); }
;             const int ch = 16 * ct + fr; const float bav = GC[(dir * 3 + 0) * 64 + ch], bxv = GC[(dir * 3 + 1) * 64 + ch], c8 = GC[(dir * 3 + 2) * 64 + ch];
;             float Al = 1.f, Hl = 0.f;
; #pragma unroll
;             for (int ee = 0; ee < 4; ++ee) { const int e = dir ? 3 - ee : ee;
;                 const float r = __builtin_amdgcn_rcpf(1.f + __expf(-(ga[e] + bav))), ig = __builtin_amdgcn_rcpf(1.f + __expf(-(gx[e] + bxv)));
;                 const float la = -c8 * r; const float a = __expf(la); const float u = __builtin_amdgcn_sqrtf((1.f - a) * (1.f + a)) * (ig * xc[ct][e]);
;                 av[dir][ct][e] = a; uv[dir][ct][e] = u; Hl = a * Hl + u; Al *= a; }
;             const int o = dir ? 3 - fq : fq; const bool odd = (o & 1) != 0, hi2 = (o & 2) != 0;
;             const float A1 = __shfl_xor(Al, 16), H1 = __shfl_xor(Hl, 16);
;             const float pxA = odd ? A1 : 1.f, pxH = odd ? H1 : 0.f;
;             const float gA = Al * A1, gH = odd ? (Al * H1 + Hl) : (A1 * Hl + H1);
;             const float A2 = __shfl_xor(gA, 32), H2 = __shfl_xor(gH, 32);
	v_lshlrev_b32_e32 v70, 16, v51
	v_pk_mul_f32 v[106:107], v[66:67], v[70:71]
	v_pk_mov_b32 v[70:71], v[54:55], v[70:71] op_sel:[1,0]
	v_pk_mul_f32 v[68:69], v[66:67], v[54:55]
	v_pk_mul_f32 v[66:67], v[66:67], v[70:71]
	v_add_f32_e32 v49, v107, v34
	v_add_f32_e32 v51, v67, v34
	v_mov_b32_e32 v62, v40
	v_add_f32_e32 v40, v69, v34
	v_fma_f32 v108, v46, v54, v34
	v_add_f32_e32 v34, v106, v49
	v_add_f32_e32 v46, v66, v51
	v_lshlrev_b32_e32 v107, 16, v109
	v_lshlrev_b32_e32 v106, 16, v110
	v_mov_b32_e32 v66, v44
	v_mov_b32_e32 v67, v52
	v_pk_mul_f32 v[110:111], v[66:67], v[54:55]
	v_pk_mov_b32 v[54:55], v[106:107], v[54:55] op_sel:[1,0]
	v_add_f32_e32 v40, v68, v40
	v_pk_mul_f32 v[112:113], v[66:67], v[54:55]
	v_pk_mul_f32 v[114:115], v[66:67], v[106:107]
	v_add_f32_e32 v49, v113, v46
	v_lshlrev_b32_e32 v67, 16, v118
	v_lshlrev_b32_e32 v66, 16, v119
	v_mov_b32_e32 v46, v41
	v_lshlrev_b32_e32 v68, 16, v117
	v_lshlrev_b32_e32 v69, 16, v116
	v_pk_mul_f32 v[70:71], v[46:47], v[68:69]
	v_pk_mov_b32 v[68:69], v[66:67], v[68:69] op_sel:[1,0]
	v_mul_f32_e32 v57, v56, v130
	v_pk_mul_f32 v[68:69], v[46:47], v[68:69]
	v_mul_f32_e32 v57, v105, v57
	v_mul_f32_e32 v104, v52, v106
	v_pk_mul_f32 v[54:55], v[46:47], v[66:67]
	v_add_f32_e32 v52, v71, v35
	v_add_f32_e32 v46, v69, v35
	v_mov_b32_e32 v64, v44
	v_mul_f32_e32 v44, v59, v57
	v_add_f32_e32 v113, v115, v40
	v_add_f32_e32 v40, v55, v35
	v_fmac_f32_e32 v35, v47, v66
	v_add_f32_e32 v55, v70, v52
	v_add_f32_e32 v57, v68, v46
	v_lshlrev_b32_e32 v47, 16, v120
	v_lshlrev_b32_e32 v46, 16, v121
	v_mov_b32_e32 v52, v45
	v_add_f32_e32 v34, v111, v34
	v_pk_mul_f32 v[70:71], v[52:53], v[66:67]
	v_pk_mov_b32 v[66:67], v[46:47], v[66:67] op_sel:[1,0]
	v_add_f32_e32 v34, v110, v34
	v_pk_mul_f32 v[68:69], v[52:53], v[66:67]
	v_add_f32_e32 v40, v54, v40
	v_add_f32_e32 v69, v69, v57
	v_mul_f32_e32 v57, v34, v129
	v_mul_f32_e32 v54, v53, v46
	v_pk_mul_f32 v[66:67], v[52:53], v[46:47]
	v_pk_mul_f32 v[52:53], v[56:57], v[0:1]
	v_add_f32_e32 v67, v67, v40
	v_add_f32_e32 v1, v52, v53
	v_add_f32_e32 v40, v112, v49
	v_mul_f32_e32 v109, v130, v1
	v_mul_f32_e32 v53, v40, v131
	v_mov_b32_e32 v52, v107
	v_pk_fma_f32 v[52:53], v[62:63], v[52:53], v[108:109]
	v_add_f32_e32 v46, v114, v113
	v_pk_add_f32 v[56:57], v[104:105], v[52:53]
	v_pk_mul_f32 v[52:53], v[104:105], v[52:53]
	v_mul_f32_e32 v49, v46, v132
	v_mov_b32_e32 v57, v53
	v_pk_fma_f32 v[52:53], v[64:65], v[48:49], v[56:57]
	ds_bpermute_b32 v51, v83, v44
	v_pk_mul_f32 v[48:49], v[52:53], v[58:59]
	v_lshlrev_b32_e32 v121, 16, v124
	v_fmac_f32_e32 v49, v48, v133
	ds_bpermute_b32 v1, v83, v49
	s_waitcnt lgkmcnt(1)
	v_mul_f32_e32 v60, v44, v51
	ds_bpermute_b32 v111, v84, v60
	v_lshlrev_b32_e32 v120, 16, v125
	v_mov_b32_e32 v116, v30
	s_waitcnt lgkmcnt(1)
	v_fma_f32 v44, v44, v1, v49
	v_fmac_f32_e32 v1, v49, v51
	v_cndmask_b32_e64 v1, v44, v1, s[42:43]
	ds_bpermute_b32 v44, v84, v1
	v_mov_b32_e32 v117, v38
	v_pk_mul_f32 v[58:59], v[116:117], v[122:123]
	v_pk_mov_b32 v[56:57], v[120:121], v[122:123] op_sel:[1,0]
	v_pk_mul_f32 v[118:119], v[116:117], v[120:121]
	v_add_f32_e32 v48, v59, v26
	v_pk_mul_f32 v[62:63], v[116:117], v[56:57]
	v_add_f32_e32 v71, v71, v55
	v_add_f32_e32 v55, v119, v26
	v_add_f32_e32 v49, v63, v26
	v_fma_f32 v56, v38, v120, v26
	v_add_f32_e32 v26, v58, v48
	s_waitcnt lgkmcnt(0)
	v_fma_f32 v48, v60, v44, v1
	v_fmac_f32_e32 v44, v1, v111
	v_mul_f32_e32 v106, v60, v111
	v_cndmask_b32_e64 v107, v48, v44, s[44:45]
	ds_write_b64 v86, v[106:107] offset:58624
	v_add_f32_e32 v38, v62, v49
	s_waitcnt lgkmcnt(2)
	v_mfma_f32_16x16x32_bf16 v[112:115], v[14:17], v[198:201], 0
	v_mov_b32_e32 v122, v32
	v_mov_b32_e32 v123, v36
	v_lshlrev_b32_e32 v58, 16, v127
	v_pk_mul_f32 v[62:63], v[122:123], v[120:121]
	v_add_f32_e32 v53, v118, v55
	v_mul_f32_e32 v60, v36, v58
	v_add_f32_e32 v36, v63, v26
	ds_read_b32 v26, v93 offset:57152
	s_waitcnt lgkmcnt(2)
	v_mfma_f32_16x16x32_bf16 v[108:111], v[18:21], v[202:205], v[112:115]
	ds_read_b32 v51, v93 offset:57408
	ds_read_b32 v57, v93 offset:57664
	v_lshlrev_b32_e32 v59, 16, v126
	v_pk_mov_b32 v[48:49], v[58:59], v[120:121] op_sel:[1,0]
	v_mfma_f32_16x16x32_bf16 v[104:107], v[14:17], v[206:209], 0
	s_waitcnt lgkmcnt(2)
	s_nop 1
	v_add_f32_e32 v1, v108, v26
	v_mul_f32_e32 v1, 0xbfb8aa3b, v1
	v_exp_f32_e32 v1, v1
	v_mfma_f32_16x16x32_bf16 v[104:107], v[18:21], v[210:213], v[104:107]
	ds_read_b128 v[198:201], v23 offset:23552
	ds_read_b128 v[202:205], v23 offset:23616
	ds_read_b128 v[206:209], v23 offset:32768
	ds_read_b128 v[210:213], v23 offset:32832
	v_mul_f32_e64 v64, v122, v48
	v_mul_f32_e64 v65, v123, v49
	v_lshlrev_b32_e32 v117, 16, v103
	v_add_f32_e32 v1, 1.0, v1
	v_rcp_f32_e32 v1, v1
	v_lshlrev_b32_e32 v116, 16, v128
	s_waitcnt lgkmcnt(1)
	s_nop 0
	v_add_f32_e32 v44, v104, v51
	v_mul_f32_e32 v44, 0xbfb8aa3b, v44
	v_exp_f32_e32 v44, v44
	s_waitcnt lgkmcnt(0)
; #define LAS __attribute__((address_space(3)))
; #define MFMA16(a, b, c) __builtin_amdgcn_mfma_f32_16x16x32_bf16(a, b, c, 0, 0, 0)
; template <bool PHASE_B>
; __device__ __forceinline__ void lru_item(const Params& p, LAS unsigned char* lds, int ci, int ci_next, int jb, const int tid, v4u (&xvn)[3]) {
;     ...
;                 const bf16x8 wa = *(const LAS bf16x8*)(lds + LR_WG + ((dir * 2 + 0) * 64 + 16 * ct + fr) * 144 + (32 * ks + 8 * fq) * 2);
;                 const bf16x8 wx = *(const LAS bf16x8*)(lds + LR_WG + ((dir * 2 + 1) * 64 + 16 * ct + fr) * 144 + (32 * ks + 8 * fq) * 2);
;                 ga = MFMA16(af[ks], wa, ga); gx = MFMA16(af[ks], wx, gx); }
;             const int ch = 16 * ct + fr; const float bav = GC[(dir * 3 + 0) * 64 + ch], bxv = GC[(dir * 3 + 1) * 64 + ch], c8 = GC[(dir * 3 + 2) * 64 + ch];
;             float Al = 1.f, Hl = 0.f;
; #pragma unroll
;             for (int ee = 0; ee < 4; ++ee) { const int e = dir ? 3 - ee : ee;
;                 const float r = __builtin_amdgcn_rcpf(1.f + __expf(-(ga[e] + bav))), ig = __builtin_amdgcn_rcpf(1.f + __expf(-(gx[e] + bxv)));
;                 const float la = -c8 * r; const float a = __expf(la); const float u = __builtin_amdgcn_sqrtf((1.f - a) * (1.f + a)) * (ig * xc[ct][e]);
;                 av[dir][ct][e] = a; uv[dir][ct][e] = u; Hl = a * Hl + u; Al *= a; }
;             const int o = dir ? 3 - fq : fq; const bool odd = (o & 1) != 0, hi2 = (o & 2) != 0;
;             const float A1 = __shfl_xor(Al, 16), H1 = __shfl_xor(Hl, 16);
;             const float pxA = odd ? A1 : 1.f, pxH = odd ? H1 : 0.f;
;             const float gA = Al * A1, gH = odd ? (Al * H1 + Hl) : (A1 * Hl + H1);
;             const float A2 = __shfl_xor(gA, 32), H2 = __shfl_xor(gH, 32);
;             const float PA = hi2 ? pxA * A2 : pxA, PH = hi2 ? (pxA * H2 + pxH) : pxH;
;             const float TA = gA * A2, TH = hi2 ? (gA * H2 + gH) : (A2 * gH + H2);
;             pA[dir][ct] = PA; pH[dir][ct] = PH;
;             ((LAS f32x2*)(lds + LR_SEG))[(dir * 8 + rt) * 64 + ch] = (f32x2){TA, TH};
	v_mul_f32_e32 v1, v1, v57
	v_mul_f32_e32 v1, 0xbfb8aa3b, v1
	v_add_f32_e32 v44, 1.0, v44
	v_rcp_f32_e32 v63, v44
	v_exp_f32_e32 v44, v1
	v_add_f32_e32 v1, v109, v26
	v_mul_f32_e32 v1, 0xbfb8aa3b, v1
	v_exp_f32_e32 v1, v1
	v_sub_f32_e32 v48, 1.0, v44
	v_add_f32_e32 v49, 1.0, v44
	v_mul_f32_e32 v48, v48, v49
	v_add_f32_e32 v1, 1.0, v1
	v_rcp_f32_e32 v1, v1
	v_add_f32_e32 v49, v105, v51
	v_mul_f32_e32 v49, 0xbfb8aa3b, v49
	v_exp_f32_e32 v49, v49
	v_mul_f32_e32 v1, v1, v57
	v_mul_f32_e32 v1, 0xbfb8aa3b, v1
	v_exp_f32_e32 v108, v1
	v_sqrt_f32_e32 v1, v48
	v_add_f32_e32 v48, 1.0, v49
	v_add_f32_e32 v49, v110, v26
	v_mul_f32_e32 v49, 0xbfb8aa3b, v49
	v_add_f32_e32 v26, v111, v26
	v_exp_f32_e32 v55, v49
	v_mul_f32_e32 v26, 0xbfb8aa3b, v26
	v_exp_f32_e32 v26, v26
	v_rcp_f32_e32 v109, v48
	v_sub_f32_e32 v48, 1.0, v108
	v_add_f32_e32 v49, 1.0, v108
	v_mul_f32_e32 v48, v48, v49
	v_sqrt_f32_e32 v49, v48
	v_add_f32_e32 v48, 1.0, v55
	v_rcp_f32_e32 v48, v48
	v_add_f32_e32 v26, 1.0, v26
	v_rcp_f32_e32 v26, v26
	v_add_f32_e32 v55, v106, v51
	v_mul_f32_e32 v48, v48, v57
	v_add_f32_e32 v51, v107, v51
	v_mul_f32_e32 v55, 0xbfb8aa3b, v55
	v_mul_f32_e32 v48, 0xbfb8aa3b, v48
	v_mul_f32_e32 v51, 0xbfb8aa3b, v51
	v_mul_f32_e32 v26, v26, v57
	v_exp_f32_e32 v104, v55
	v_exp_f32_e32 v55, v48
	v_exp_f32_e32 v51, v51
	v_mul_f32_e32 v26, 0xbfb8aa3b, v26
	v_exp_f32_e32 v107, v26
	v_mul_f32_e32 v48, v44, v108
	v_mul_f32_e32 v26, v55, v48
	v_add_f32_e32 v48, 1.0, v51
	v_add_f32_e32 v104, 1.0, v104
	v_rcp_f32_e32 v106, v48
	v_sub_f32_e32 v48, 1.0, v107
	v_add_f32_e32 v51, 1.0, v107
	v_rcp_f32_e32 v110, v104
	v_sub_f32_e32 v104, 1.0, v55
	v_add_f32_e32 v105, 1.0, v55
	v_mul_f32_e32 v48, v48, v51
	v_mul_f32_e32 v104, v104, v105
	v_sqrt_f32_e32 v57, v48
	v_mov_b32_e32 v48, v41
	v_mul_f32_e32 v41, v107, v26
	v_add_f32_e32 v26, v70, v71
	v_sqrt_f32_e32 v105, v104
	v_mov_b32_e32 v104, v45
	v_mul_f32_e32 v45, v26, v63
	v_pk_mul_f32 v[44:45], v[44:45], v[0:1]
	v_mov_b32_e32 v70, v35
	v_add_f32_e32 v1, v44, v45
	v_add_f32_e32 v44, v68, v69
	v_mul_f32_e32 v71, v108, v1
	v_mul_f32_e32 v69, v44, v109
	v_mov_b32_e32 v68, v47
	v_pk_fma_f32 v[48:49], v[48:49], v[68:69], v[70:71]
	ds_bpermute_b32 v111, v83, v41
	v_pk_add_f32 v[68:69], v[54:55], v[48:49]
	v_pk_mul_f32 v[48:49], v[54:55], v[48:49]
	v_add_f32_e32 v35, v65, v38
	v_add_f32_e32 v48, v66, v67
	v_mov_b32_e32 v69, v49
	v_mul_f32_e32 v51, v48, v110
	v_pk_fma_f32 v[54:55], v[104:105], v[50:51], v[68:69]
	s_waitcnt lgkmcnt(0)
	v_mul_f32_e32 v38, v41, v111
	v_pk_mul_f32 v[50:51], v[54:55], v[106:107]
	ds_bpermute_b32 v45, v84, v38
	v_fmac_f32_e32 v51, v50, v57
	ds_bpermute_b32 v1, v83, v51
	v_pk_mul_f32 v[70:71], v[122:123], v[58:59]
	s_waitcnt lgkmcnt(1)
	v_mul_f32_e32 v50, v38, v45
	v_add_f32_e32 v47, v71, v53
	s_waitcnt lgkmcnt(0)
	v_fma_f32 v41, v41, v1, v51
	v_fmac_f32_e32 v1, v51, v111
	v_cndmask_b32_e64 v1, v41, v1, s[42:43]
	ds_bpermute_b32 v41, v84, v1
	s_waitcnt lgkmcnt(0)
	v_fma_f32 v38, v38, v41, v1
	v_fmac_f32_e32 v41, v1, v45
	v_cndmask_b32_e64 v51, v38, v41, s[44:45]
	ds_write_b64 v86, v[50:51] offset:58752
	s_waitcnt lgkmcnt(2)
	v_mfma_f32_16x16x32_bf16 v[66:69], v[14:17], v[198:201], 0
	v_lshlrev_b32_e32 v51, 16, v43
	ds_read_b32 v43, v93 offset:57216
	s_waitcnt lgkmcnt(2)
	v_mfma_f32_16x16x32_bf16 v[66:69], v[18:21], v[202:205], v[66:69]
	v_mov_b32_e32 v38, v31
	v_lshlrev_b32_e32 v50, 16, v61
	v_pk_mul_f32 v[120:121], v[38:39], v[50:51]
	v_mfma_f32_16x16x32_bf16 v[104:107], v[14:17], v[206:209], 0
	v_pk_mov_b32 v[50:51], v[116:117], v[50:51] op_sel:[1,0]
	s_waitcnt lgkmcnt(0)
	s_nop 1
	v_add_f32_e32 v1, v66, v43
	v_mul_f32_e32 v1, 0xbfb8aa3b, v1
	v_pk_mul_f32 v[118:119], v[38:39], v[116:117]
	v_pk_mul_f32 v[108:109], v[38:39], v[50:51]
	v_mfma_f32_16x16x32_bf16 v[104:107], v[18:21], v[210:213], v[104:107]
	ds_read_b128 v[198:201], v23 offset:25856
	ds_read_b128 v[202:205], v23 offset:25920
	ds_read_b128 v[206:209], v23 offset:35072
	ds_read_b128 v[210:213], v23 offset:35136
	ds_read_b32 v38, v93 offset:57472
	ds_read_b32 v49, v93 offset:57728
	v_exp_f32_e32 v1, v1
	v_add_f32_e32 v61, v68, v43
	v_mul_f32_e32 v61, 0xbfb8aa3b, v61
	s_waitcnt lgkmcnt(1)
	s_nop 1
	v_add_f32_e32 v50, v104, v38
	v_add_f32_e32 v1, 1.0, v1
	v_mul_f32_e32 v50, 0xbfb8aa3b, v50
	v_rcp_f32_e32 v1, v1
	v_exp_f32_e32 v50, v50
	v_exp_f32_e32 v61, v61
	v_mov_b32_e32 v68, v32
	s_waitcnt lgkmcnt(0)
	v_mul_f32_e32 v1, v1, v49
	v_add_f32_e32 v50, 1.0, v50
	v_mul_f32_e32 v1, 0xbfb8aa3b, v1
	v_rcp_f32_e32 v51, v50
	v_exp_f32_e32 v50, v1
	v_add_f32_e32 v1, v67, v43
	v_mul_f32_e32 v1, 0xbfb8aa3b, v1
	v_exp_f32_e32 v1, v1
	v_sub_f32_e32 v55, 1.0, v50
	v_add_f32_e32 v57, 1.0, v50
	v_mul_f32_e32 v55, v55, v57
	v_add_f32_e32 v1, 1.0, v1
	v_rcp_f32_e32 v1, v1
	v_add_f32_e32 v57, v105, v38
	v_mul_f32_e32 v57, 0xbfb8aa3b, v57
	v_exp_f32_e32 v57, v57
	v_mul_f32_e32 v1, v1, v49
	v_mul_f32_e32 v1, 0xbfb8aa3b, v1
	v_exp_f32_e32 v58, v1
	v_add_f32_e32 v43, v69, v43
	v_mul_f32_e32 v43, 0xbfb8aa3b, v43
	v_sqrt_f32_e32 v1, v55
	v_add_f32_e32 v55, 1.0, v57
	v_sub_f32_e32 v57, 1.0, v58
	v_add_f32_e32 v63, 1.0, v58
	v_exp_f32_e32 v43, v43
	v_mul_f32_e32 v57, v57, v63
	v_sqrt_f32_e32 v67, v57
	v_add_f32_e32 v57, 1.0, v61
	v_rcp_f32_e32 v57, v57
	v_add_f32_e32 v43, 1.0, v43
	v_rcp_f32_e32 v43, v43
	v_add_f32_e32 v61, v106, v38
	v_mul_f32_e32 v57, v57, v49
	v_mul_f32_e32 v61, 0xbfb8aa3b, v61
	v_mul_f32_e32 v57, 0xbfb8aa3b, v57
	v_add_f32_e32 v38, v107, v38
	v_exp_f32_e32 v63, v61
	v_exp_f32_e32 v61, v57
	v_mul_f32_e32 v38, 0xbfb8aa3b, v38
	v_mul_f32_e32 v43, v43, v49
	v_exp_f32_e32 v38, v38
	v_mul_f32_e32 v43, 0xbfb8aa3b, v43
	v_exp_f32_e32 v105, v43
	v_sub_f32_e32 v65, 1.0, v61
	v_add_f32_e32 v66, 1.0, v61
	v_rcp_f32_e32 v55, v55
	v_mul_f32_e32 v65, v65, v66
	v_add_f32_e32 v38, 1.0, v38
	v_mov_b32_e32 v66, v30
	v_add_f32_e32 v30, v62, v36
	v_rcp_f32_e32 v104, v38
	v_sub_f32_e32 v38, 1.0, v105
	v_add_f32_e32 v49, 1.0, v105
	v_mul_f32_e32 v51, v30, v51
	v_mul_f32_e32 v57, v50, v58
	v_mul_f32_e32 v38, v38, v49
	v_pk_mul_f32 v[50:51], v[50:51], v[0:1]
	v_add_f32_e32 v63, 1.0, v63
	v_sqrt_f32_e32 v49, v38
	v_add_f32_e32 v1, v50, v51
	v_add_f32_e32 v38, v64, v35
	v_rcp_f32_e32 v63, v63
	v_mul_f32_e32 v43, v61, v57
	v_mul_f32_e32 v57, v58, v1
	v_mul_f32_e32 v51, v38, v55
	v_mov_b32_e32 v50, v59
	v_sqrt_f32_e32 v69, v65
	v_pk_fma_f32 v[50:51], v[66:67], v[50:51], v[56:57]
	v_mul_f32_e32 v32, v105, v43
	v_pk_add_f32 v[56:57], v[60:61], v[50:51]
	v_pk_mul_f32 v[50:51], v[60:61], v[50:51]
	ds_bpermute_b32 v65, v83, v32
	v_add_f32_e32 v50, v70, v47
	v_mov_b32_e32 v57, v51
	v_mul_f32_e32 v43, v50, v63
	v_pk_fma_f32 v[56:57], v[68:69], v[42:43], v[56:57]
	s_waitcnt lgkmcnt(0)
; #define LAS __attribute__((address_space(3)))
; #define MFMA16(a, b, c) __builtin_amdgcn_mfma_f32_16x16x32_bf16(a, b, c, 0, 0, 0)
; template <bool PHASE_B>
; __device__ __forceinline__ void lru_item(const Params& p, LAS unsigned char* lds, int ci, int ci_next, int jb, const int tid, v4u (&xvn)[3]) {
;     ...
;                 const bf16x8 wa = *(const LAS bf16x8*)(lds + LR_WG + ((dir * 2 + 0) * 64 + 16 * ct + fr) * 144 + (32 * ks + 8 * fq) * 2);
;                 const bf16x8 wx = *(const LAS bf16x8*)(lds + LR_WG + ((dir * 2 + 1) * 64 + 16 * ct + fr) * 144 + (32 * ks + 8 * fq) * 2);
;                 ga = MFMA16(af[ks], wa, ga); gx = MFMA16(af[ks], wx, gx); }
;             const int ch = 16 * ct + fr; const float bav = GC[(dir * 3 + 0) * 64 + ch], bxv = GC[(dir * 3 + 1) * 64 + ch], c8 = GC[(dir * 3 + 2) * 64 + ch];
;             float Al = 1.f, Hl = 0.f;
; #pragma unroll
;             for (int ee = 0; ee < 4; ++ee) { const int e = dir ? 3 - ee : ee;
;                 const float r = __builtin_amdgcn_rcpf(1.f + __expf(-(ga[e] + bav))), ig = __builtin_amdgcn_rcpf(1.f + __expf(-(gx[e] + bxv)));
;                 const float la = -c8 * r; const float a = __expf(la); const float u = __builtin_amdgcn_sqrtf((1.f - a) * (1.f + a)) * (ig * xc[ct][e]);
;                 av[dir][ct][e] = a; uv[dir][ct][e] = u; Hl = a * Hl + u; Al *= a; }
;             const int o = dir ? 3 - fq : fq; const bool odd = (o & 1) != 0, hi2 = (o & 2) != 0;
;             const float A1 = __shfl_xor(Al, 16), H1 = __shfl_xor(Hl, 16);
;             const float pxA = odd ? A1 : 1.f, pxH = odd ? H1 : 0.f;
;             const float gA = Al * A1, gH = odd ? (Al * H1 + Hl) : (A1 * Hl + H1);
;             const float A2 = __shfl_xor(gA, 32), H2 = __shfl_xor(gH, 32);
;             const float PA = hi2 ? pxA * A2 : pxA, PH = hi2 ? (pxA * H2 + pxH) : pxH;
;             const float TA = gA * A2, TH = hi2 ? (gA * H2 + gH) : (A2 * gH + H2);
;             pA[dir][ct] = PA; pH[dir][ct] = PH;
;             ((LAS f32x2*)(lds + LR_SEG))[(dir * 8 + rt) * 64 + ch] = (f32x2){TA, TH};
	v_mul_f32_e32 v36, v32, v65
	v_pk_mul_f32 v[42:43], v[56:57], v[104:105]
	v_add_f32_e32 v41, v119, v27
	v_fmac_f32_e32 v43, v42, v49
	ds_bpermute_b32 v1, v83, v43
	v_add_f32_e32 v45, v121, v27
	v_add_f32_e32 v53, v109, v27
	v_fmac_f32_e32 v27, v39, v116
	ds_bpermute_b32 v39, v84, v36
	s_waitcnt lgkmcnt(1)
	v_fma_f32 v32, v32, v1, v43
	v_fmac_f32_e32 v1, v43, v65
	v_cndmask_b32_e64 v1, v32, v1, s[42:43]
	ds_bpermute_b32 v32, v84, v1
	s_waitcnt lgkmcnt(1)
	v_mul_f32_e32 v58, v36, v39
	v_lshlrev_b32_e32 v43, 16, v102
	v_lshlrev_b32_e32 v42, 16, v29
	v_add_f32_e32 v35, v120, v45
	s_waitcnt lgkmcnt(0)
	v_fma_f32 v36, v36, v32, v1
	v_fmac_f32_e32 v32, v1, v39
	v_cndmask_b32_e64 v59, v36, v32, s[44:45]
	ds_write_b64 v86, v[58:59] offset:58880
	s_waitcnt lgkmcnt(2)
	v_mfma_f32_16x16x32_bf16 v[58:61], v[14:17], v[198:201], 0
	ds_read_b32 v32, v93 offset:57280
	v_add_f32_e32 v45, v108, v53
	s_waitcnt lgkmcnt(2)
	v_mfma_f32_16x16x32_bf16 v[58:61], v[18:21], v[202:205], v[58:61]
	v_mov_b32_e32 v36, v33
	v_pk_mov_b32 v[108:109], v[42:43], v[116:117] op_sel:[1,0]
	v_mul_f32_e32 v70, v37, v42
	v_mfma_f32_16x16x32_bf16 v[62:65], v[14:17], v[206:209], 0
	v_mul_f32_e64 v106, v36, v116
	v_mul_f32_e64 v107, v37, v117
	s_waitcnt lgkmcnt(0)
	s_nop 0
	v_add_f32_e32 v1, v58, v32
	v_mul_f32_e32 v1, 0xbfb8aa3b, v1
	v_pk_mul_f32 v[108:109], v[36:37], v[108:109]
	v_pk_mul_f32 v[66:67], v[36:37], v[42:43]
	v_mfma_f32_16x16x32_bf16 v[62:65], v[18:21], v[210:213], v[62:65]
	ds_read_b128 v[198:201], v23 offset:37376
	ds_read_b128 v[202:205], v23 offset:37440
	ds_read_b128 v[206:209], v23 offset:46592
	ds_read_b128 v[210:213], v23 offset:46656
	ds_read_b32 v37, v93 offset:57536
	ds_read_b32 v39, v93 offset:57792
	v_exp_f32_e32 v1, v1
	v_add_f32_e32 v29, v107, v35
	v_add_f32_e32 v35, v109, v45
	s_waitcnt lgkmcnt(1)
	s_nop 1
	v_add_f32_e32 v36, v62, v37
	v_add_f32_e32 v1, 1.0, v1
	v_mul_f32_e32 v36, 0xbfb8aa3b, v36
	v_rcp_f32_e32 v1, v1
	v_exp_f32_e32 v36, v36
	v_add_f32_e32 v51, v60, v32
	v_mul_f32_e32 v51, 0xbfb8aa3b, v51
	s_waitcnt lgkmcnt(0)
	v_mul_f32_e32 v1, v1, v39
	v_add_f32_e32 v36, 1.0, v36
	v_mul_f32_e32 v1, 0xbfb8aa3b, v1
	v_rcp_f32_e32 v42, v36
	v_exp_f32_e32 v36, v1
	v_add_f32_e32 v1, v59, v32
	v_mul_f32_e32 v1, 0xbfb8aa3b, v1
	v_exp_f32_e32 v1, v1
	v_sub_f32_e32 v45, 1.0, v36
	v_add_f32_e32 v47, 1.0, v36
	v_mul_f32_e32 v45, v45, v47
	v_add_f32_e32 v1, 1.0, v1
	v_rcp_f32_e32 v1, v1
	v_add_f32_e32 v47, v63, v37
	v_mul_f32_e32 v47, 0xbfb8aa3b, v47
	v_exp_f32_e32 v47, v47
	v_mul_f32_e32 v1, v1, v39
	v_mul_f32_e32 v1, 0xbfb8aa3b, v1
	v_exp_f32_e32 v49, v1
	v_add_f32_e32 v32, v61, v32
	v_mul_f32_e32 v32, 0xbfb8aa3b, v32
	v_exp_f32_e32 v51, v51
	v_exp_f32_e32 v32, v32
	v_sqrt_f32_e32 v1, v45
	v_add_f32_e32 v45, 1.0, v47
	v_sub_f32_e32 v47, 1.0, v49
	v_add_f32_e32 v53, 1.0, v49
	v_mul_f32_e32 v47, v47, v53
	v_sqrt_f32_e32 v59, v47
	v_add_f32_e32 v47, 1.0, v51
	v_add_f32_e32 v32, 1.0, v32
	v_rcp_f32_e32 v47, v47
	v_rcp_f32_e32 v32, v32
	v_add_f32_e32 v51, v64, v37
	v_add_f32_e32 v37, v65, v37
	v_mul_f32_e32 v47, v47, v39
	v_mul_f32_e32 v37, 0xbfb8aa3b, v37
	v_mul_f32_e32 v32, v32, v39
	v_mul_f32_e32 v47, 0xbfb8aa3b, v47
	v_exp_f32_e32 v37, v37
	v_mul_f32_e32 v32, 0xbfb8aa3b, v32
	v_exp_f32_e32 v71, v47
	v_exp_f32_e32 v63, v32
	v_mul_f32_e32 v51, 0xbfb8aa3b, v51
	v_mul_f32_e32 v47, v36, v49
	v_add_f32_e32 v37, 1.0, v37
	v_exp_f32_e32 v51, v51
	v_mul_f32_e32 v32, v71, v47
	v_rcp_f32_e32 v62, v37
	v_sub_f32_e32 v37, 1.0, v63
	v_add_f32_e32 v39, 1.0, v63
	v_rcp_f32_e32 v45, v45
	v_mul_f32_e32 v37, v37, v39
	v_mov_b32_e32 v58, v31
	v_mul_f32_e32 v31, v63, v32
	v_add_f32_e32 v32, v106, v29
	v_sqrt_f32_e32 v39, v37
	v_mul_f32_e32 v37, v32, v42
	v_pk_mul_f32 v[36:37], v[36:37], v[0:1]
	v_add_f32_e32 v51, 1.0, v51
	v_sub_f32_e32 v53, 1.0, v71
	v_add_f32_e32 v55, 1.0, v71
	v_add_f32_e32 v1, v36, v37
	v_add_f32_e32 v36, v108, v35
	v_rcp_f32_e32 v51, v51
	v_mul_f32_e32 v53, v53, v55
	v_mul_f32_e32 v65, v49, v1
	v_mov_b32_e32 v64, v27
	v_mul_f32_e32 v69, v36, v45
	v_mov_b32_e32 v68, v43
	v_add_f32_e32 v41, v118, v41
	v_sqrt_f32_e32 v61, v53
	v_pk_fma_f32 v[42:43], v[58:59], v[68:69], v[64:65]
	v_add_f32_e32 v41, v67, v41
	v_pk_add_f32 v[58:59], v[70:71], v[42:43]
	v_pk_mul_f32 v[42:43], v[70:71], v[42:43]
	v_mov_b32_e32 v60, v33
	v_add_f32_e32 v42, v66, v41
	v_mov_b32_e32 v59, v43
	v_mul_f32_e32 v29, v42, v51
	v_pk_fma_f32 v[28:29], v[60:61], v[28:29], v[58:59]
	ds_bpermute_b32 v33, v83, v31
	v_pk_mul_f32 v[58:59], v[28:29], v[62:63]
	s_waitcnt lgkmcnt(0)
	v_mul_f32_e32 v27, v31, v33
	v_fmac_f32_e32 v59, v58, v39
	ds_bpermute_b32 v1, v83, v59
	ds_bpermute_b32 v29, v84, v27
	s_waitcnt lgkmcnt(1)
	v_fma_f32 v31, v31, v1, v59
	v_fmac_f32_e32 v1, v59, v33
	v_cndmask_b32_e64 v1, v31, v1, s[42:43]
	ds_bpermute_b32 v31, v84, v1
	s_waitcnt lgkmcnt(1)
	v_mul_f32_e32 v58, v27, v29
	s_waitcnt lgkmcnt(0)
	v_fma_f32 v27, v27, v31, v1
	v_fmac_f32_e32 v31, v1, v29
	v_cndmask_b32_e64 v59, v27, v31, s[44:45]
	ds_write_b64 v86, v[58:59] offset:59008
	s_waitcnt lgkmcnt(1)
	v_mfma_f32_16x16x32_bf16 v[58:61], v[14:17], v[198:201], 0
	ds_read_b32 v27, v93 offset:57856
	ds_read_b32 v29, v93 offset:58112
	ds_read_b32 v31, v93 offset:58368
	s_waitcnt lgkmcnt(5)
	v_mfma_f32_16x16x32_bf16 v[58:61], v[18:21], v[202:205], v[58:61]
	s_waitcnt lgkmcnt(4)
	v_mfma_f32_16x16x32_bf16 v[66:69], v[14:17], v[206:209], 0
	s_waitcnt lgkmcnt(3)
	v_mfma_f32_16x16x32_bf16 v[62:65], v[18:21], v[210:213], v[66:69]
	ds_read_b128 v[198:201], v23 offset:39680
	ds_read_b128 v[202:205], v23 offset:39744
	ds_read_b128 v[206:209], v23 offset:48896
	ds_read_b128 v[210:213], v23 offset:48960
	s_waitcnt lgkmcnt(2)
; #define LAS __attribute__((address_space(3)))
; #define MFMA16(a, b, c) __builtin_amdgcn_mfma_f32_16x16x32_bf16(a, b, c, 0, 0, 0)
; template <bool PHASE_B>
; __device__ __forceinline__ void lru_item(const Params& p, LAS unsigned char* lds, int ci, int ci_next, int jb, const int tid, v4u (&xvn)[3]) {
;     ...
;                 const bf16x8 wa = *(const LAS bf16x8*)(lds + LR_WG + ((dir * 2 + 0) * 64 + 16 * ct + fr) * 144 + (32 * ks + 8 * fq) * 2);
;                 const bf16x8 wx = *(const LAS bf16x8*)(lds + LR_WG + ((dir * 2 + 1) * 64 + 16 * ct + fr) * 144 + (32 * ks + 8 * fq) * 2);
;                 ga = MFMA16(af[ks], wa, ga); gx = MFMA16(af[ks], wx, gx); }
;             const int ch = 16 * ct + fr; const float bav = GC[(dir * 3 + 0) * 64 + ch], bxv = GC[(dir * 3 + 1) * 64 + ch], c8 = GC[(dir * 3 + 2) * 64 + ch];
;             float Al = 1.f, Hl = 0.f;
; #pragma unroll
;             for (int ee = 0; ee < 4; ++ee) { const int e = dir ? 3 - ee : ee;
;                 const float r = __builtin_amdgcn_rcpf(1.f + __expf(-(ga[e] + bav))), ig = __builtin_amdgcn_rcpf(1.f + __expf(-(gx[e] + bxv)));
;                 const float la = -c8 * r; const float a = __expf(la); const float u = __builtin_amdgcn_sqrtf((1.f - a) * (1.f + a)) * (ig * xc[ct][e]);
;                 av[dir][ct][e] = a; uv[dir][ct][e] = u; Hl = a * Hl + u; Al *= a; }
;             const int o = dir ? 3 - fq : fq; const bool odd = (o & 1) != 0, hi2 = (o & 2) != 0;
;             const float A1 = __shfl_xor(Al, 16), H1 = __shfl_xor(Hl, 16);
;             const float pxA = odd ? A1 : 1.f, pxH = odd ? H1 : 0.f;
;             const float gA = Al * A1, gH = odd ? (Al * H1 + Hl) : (A1 * Hl + H1);
;             const float A2 = __shfl_xor(gA, 32), H2 = __shfl_xor(gH, 32);
;             const float PA = hi2 ? pxA * A2 : pxA, PH = hi2 ? (pxA * H2 + pxH) : pxH;
;             const float TA = gA * A2, TH = hi2 ? (gA * H2 + gH) : (A2 * gH + H2);
;             pA[dir][ct] = PA; pH[dir][ct] = PH;
;             ((LAS f32x2*)(lds + LR_SEG))[(dir * 8 + rt) * 64 + ch] = (f32x2){TA, TH};
	s_nop 2
	v_add_f32_e32 v1, v61, v27
	v_mul_f32_e32 v1, 0xbfb8aa3b, v1
	v_exp_f32_e32 v1, v1
	s_nop 0
	v_add_f32_e32 v1, 1.0, v1
	v_rcp_f32_e32 v1, v1
	s_waitcnt lgkmcnt(1)
	v_add_f32_e32 v33, v65, v29
	v_mul_f32_e32 v33, 0xbfb8aa3b, v33
	v_exp_f32_e32 v33, v33
	s_waitcnt lgkmcnt(0)
	v_mul_f32_e32 v1, v1, v31
	v_mul_f32_e32 v1, 0xbfb8aa3b, v1
	v_exp_f32_e32 v66, v1
	v_add_f32_e32 v1, 1.0, v33
	v_rcp_f32_e32 v33, v1
	v_sub_f32_e32 v1, 1.0, v66
	v_add_f32_e32 v35, 1.0, v66
	v_mul_f32_e32 v1, v1, v35
	v_add_f32_e32 v35, v60, v27
	v_mul_f32_e32 v35, 0xbfb8aa3b, v35
	v_exp_f32_e32 v35, v35
	v_mul_f32_e32 v67, v52, v33
	v_sqrt_f32_e32 v1, v1
	v_mul_f32_e32 v52, 0, v66
	v_add_f32_e32 v33, 1.0, v35
	v_rcp_f32_e32 v33, v33
	v_add_f32_e32 v35, v64, v29
	v_mul_f32_e32 v35, 0xbfb8aa3b, v35
	v_exp_f32_e32 v35, v35
	v_mul_f32_e32 v33, v33, v31
	v_mul_f32_e32 v33, 0xbfb8aa3b, v33
	v_exp_f32_e32 v53, v33
	s_nop 0
	v_pk_fma_f32 v[60:61], v[66:67], v[0:1], v[52:53] op_sel_hi:[1,1,0]
	v_add_f32_e32 v1, 1.0, v35
	v_rcp_f32_e32 v52, v1
	v_sub_f32_e32 v1, 1.0, v53
	v_add_f32_e32 v33, 1.0, v53
	v_mul_f32_e32 v1, v1, v33
	v_add_f32_e32 v33, v59, v27
	v_mul_f32_e32 v33, 0xbfb8aa3b, v33
	v_sqrt_f32_e32 v1, v1
	v_exp_f32_e32 v33, v33
	v_add_f32_e32 v27, v58, v27
	v_mov_b32_e32 v47, v61
	v_mul_f32_e32 v27, 0xbfb8aa3b, v27
	v_pk_mul_f32 v[46:47], v[46:47], v[52:53]
	v_exp_f32_e32 v27, v27
	v_fmac_f32_e32 v47, v46, v1
	v_add_f32_e32 v1, 1.0, v33
	v_rcp_f32_e32 v1, v1
	v_add_f32_e32 v27, 1.0, v27
	v_add_f32_e32 v33, v63, v29
	v_rcp_f32_e32 v27, v27
	v_mul_f32_e32 v33, 0xbfb8aa3b, v33
	v_mul_f32_e32 v1, v1, v31
	v_exp_f32_e32 v33, v33
	v_mul_f32_e32 v1, 0xbfb8aa3b, v1
	v_exp_f32_e32 v61, v1
	v_add_f32_e32 v29, v62, v29
	v_mul_f32_e32 v29, 0xbfb8aa3b, v29
	v_mul_f32_e32 v27, v27, v31
	v_exp_f32_e32 v29, v29
	v_mul_f32_e32 v27, 0xbfb8aa3b, v27
	v_add_f32_e32 v33, 1.0, v33
	v_mov_b32_e32 v41, v47
	v_exp_f32_e32 v47, v27
	v_rcp_f32_e32 v60, v33
	v_sub_f32_e32 v33, 1.0, v61
	v_add_f32_e32 v35, 1.0, v61
	v_mul_f32_e32 v33, v33, v35
	v_sqrt_f32_e32 v33, v33
	v_add_f32_e32 v27, 1.0, v29
	v_rcp_f32_e32 v46, v27
	v_sub_f32_e32 v27, 1.0, v47
	v_add_f32_e32 v29, 1.0, v47
	v_mul_f32_e32 v27, v27, v29
	v_pk_mul_f32 v[40:41], v[40:41], v[60:61]
	v_sqrt_f32_e32 v27, v27
	v_fmac_f32_e32 v41, v40, v33
	v_mul_f32_e32 v1, v66, v53
	v_mov_b32_e32 v35, v41
	v_mul_f32_e32 v1, v61, v1
	v_pk_mul_f32 v[34:35], v[34:35], v[46:47]
	v_mul_f32_e32 v1, v47, v1
	v_fmac_f32_e32 v35, v34, v27
	ds_bpermute_b32 v27, v83, v1
	ds_bpermute_b32 v29, v83, v35
	s_waitcnt lgkmcnt(1)
	v_mul_f32_e32 v31, v1, v27
	s_waitcnt lgkmcnt(0)
	v_fma_f32 v1, v1, v29, v35
	v_fmac_f32_e32 v29, v35, v27
	v_cndmask_b32_e64 v1, v1, v29, s[46:47]
	ds_bpermute_b32 v27, v84, v31
	ds_bpermute_b32 v29, v84, v1
	s_waitcnt lgkmcnt(1)
	v_mul_f32_e32 v34, v31, v27
	s_waitcnt lgkmcnt(0)
	v_fma_f32 v31, v31, v29, v1
	v_fmac_f32_e32 v29, v1, v27
	v_cndmask_b32_e64 v35, v31, v29, s[48:49]
	ds_write_b64 v86, v[34:35] offset:62720
	s_waitcnt lgkmcnt(1)
	v_mfma_f32_16x16x32_bf16 v[58:61], v[14:17], v[198:201], 0
	ds_read_b32 v27, v93 offset:57920
	ds_read_b32 v29, v93 offset:58176
	ds_read_b32 v31, v93 offset:58432
	s_waitcnt lgkmcnt(5)
	v_mfma_f32_16x16x32_bf16 v[58:61], v[18:21], v[202:205], v[58:61]
	s_waitcnt lgkmcnt(4)
	v_mfma_f32_16x16x32_bf16 v[66:69], v[14:17], v[206:209], 0
	s_waitcnt lgkmcnt(3)
	v_mfma_f32_16x16x32_bf16 v[62:65], v[18:21], v[210:213], v[66:69]
	ds_read_b128 v[198:201], v23 offset:41984
	ds_read_b128 v[202:205], v23 offset:42048
	ds_read_b128 v[206:209], v23 offset:51200
	ds_read_b128 v[210:213], v23 offset:51264
	s_waitcnt lgkmcnt(2)
	s_nop 2
	v_add_f32_e32 v1, v61, v27
	v_mul_f32_e32 v1, 0xbfb8aa3b, v1
	v_exp_f32_e32 v1, v1
	s_nop 0
	v_add_f32_e32 v1, 1.0, v1
	v_rcp_f32_e32 v1, v1
	s_waitcnt lgkmcnt(1)
	v_add_f32_e32 v33, v65, v29
	v_mul_f32_e32 v33, 0xbfb8aa3b, v33
	v_exp_f32_e32 v33, v33
	s_waitcnt lgkmcnt(0)
	v_mul_f32_e32 v1, v1, v31
	v_mul_f32_e32 v1, 0xbfb8aa3b, v1
	v_exp_f32_e32 v34, v1
	v_add_f32_e32 v1, 1.0, v33
	v_rcp_f32_e32 v33, v1
	v_sub_f32_e32 v1, 1.0, v34
	v_add_f32_e32 v35, 1.0, v34
	v_mul_f32_e32 v1, v1, v35
	v_add_f32_e32 v35, v60, v27
	v_mul_f32_e32 v35, 0xbfb8aa3b, v35
	v_exp_f32_e32 v37, v35
	v_mul_f32_e32 v35, v54, v33
	v_sqrt_f32_e32 v1, v1
	v_mul_f32_e32 v40, 0, v34
	v_add_f32_e32 v33, 1.0, v37
	v_rcp_f32_e32 v33, v33
	v_add_f32_e32 v37, v64, v29
	v_mul_f32_e32 v37, 0xbfb8aa3b, v37
	v_exp_f32_e32 v37, v37
	v_mul_f32_e32 v33, v33, v31
	v_mul_f32_e32 v33, 0xbfb8aa3b, v33
	v_exp_f32_e32 v41, v33
	s_nop 0
	v_pk_fma_f32 v[46:47], v[34:35], v[0:1], v[40:41] op_sel_hi:[1,1,0]
	v_add_f32_e32 v1, 1.0, v37
	v_rcp_f32_e32 v40, v1
	v_sub_f32_e32 v1, 1.0, v41
	v_add_f32_e32 v33, 1.0, v41
	v_mul_f32_e32 v1, v1, v33
	v_add_f32_e32 v33, v59, v27
	v_mul_f32_e32 v33, 0xbfb8aa3b, v33
	v_sqrt_f32_e32 v1, v1
	v_exp_f32_e32 v33, v33
	v_mov_b32_e32 v49, v47
	v_add_f32_e32 v27, v58, v27
	v_pk_mul_f32 v[46:47], v[48:49], v[40:41]
	v_mul_f32_e32 v27, 0xbfb8aa3b, v27
	v_fmac_f32_e32 v47, v46, v1
	v_add_f32_e32 v1, 1.0, v33
	v_add_f32_e32 v33, v63, v29
	v_exp_f32_e32 v27, v27
	v_rcp_f32_e32 v1, v1
	v_mul_f32_e32 v33, 0xbfb8aa3b, v33
	v_exp_f32_e32 v33, v33
	v_add_f32_e32 v27, 1.0, v27
	v_mul_f32_e32 v1, v1, v31
	v_rcp_f32_e32 v27, v27
	v_mul_f32_e32 v1, 0xbfb8aa3b, v1
	v_add_f32_e32 v33, 1.0, v33
	v_exp_f32_e32 v35, v1
	v_mul_f32_e32 v1, v34, v41
	v_rcp_f32_e32 v34, v33
	v_add_f32_e32 v29, v62, v29
	v_mul_f32_e32 v29, 0xbfb8aa3b, v29
	v_mul_f32_e32 v27, v27, v31
	v_mov_b32_e32 v45, v47
	v_exp_f32_e32 v29, v29
	v_mul_f32_e32 v27, 0xbfb8aa3b, v27
	v_pk_mul_f32 v[40:41], v[44:45], v[34:35]
	v_exp_f32_e32 v45, v27
	v_sub_f32_e32 v33, 1.0, v35
	v_add_f32_e32 v37, 1.0, v35
	v_mul_f32_e32 v33, v33, v37
	v_sqrt_f32_e32 v33, v33
	v_add_f32_e32 v27, 1.0, v29
	v_rcp_f32_e32 v44, v27
	v_sub_f32_e32 v27, 1.0, v45
	v_add_f32_e32 v29, 1.0, v45
	v_mul_f32_e32 v27, v27, v29
	v_sqrt_f32_e32 v29, v27
	v_fmac_f32_e32 v41, v40, v33
	v_mov_b32_e32 v27, v41
	v_mul_f32_e32 v1, v35, v1
	v_pk_mul_f32 v[26:27], v[26:27], v[44:45]
	v_mul_f32_e32 v1, v45, v1
	v_fmac_f32_e32 v27, v26, v29
	ds_bpermute_b32 v26, v83, v1
	ds_bpermute_b32 v29, v83, v27
	s_waitcnt lgkmcnt(1)
; #define LAS __attribute__((address_space(3)))
; #define MFMA16(a, b, c) __builtin_amdgcn_mfma_f32_16x16x32_bf16(a, b, c, 0, 0, 0)
; template <bool PHASE_B>
; __device__ __forceinline__ void lru_item(const Params& p, LAS unsigned char* lds, int ci, int ci_next, int jb, const int tid, v4u (&xvn)[3]) {
;     ...
;                 const bf16x8 wa = *(const LAS bf16x8*)(lds + LR_WG + ((dir * 2 + 0) * 64 + 16 * ct + fr) * 144 + (32 * ks + 8 * fq) * 2);
;                 const bf16x8 wx = *(const LAS bf16x8*)(lds + LR_WG + ((dir * 2 + 1) * 64 + 16 * ct + fr) * 144 + (32 * ks + 8 * fq) * 2);
;                 ga = MFMA16(af[ks], wa, ga); gx = MFMA16(af[ks], wx, gx); }
;             const int ch = 16 * ct + fr; const float bav = GC[(dir * 3 + 0) * 64 + ch], bxv = GC[(dir * 3 + 1) * 64 + ch], c8 = GC[(dir * 3 + 2) * 64 + ch];
;             float Al = 1.f, Hl = 0.f;
; #pragma unroll
;             for (int ee = 0; ee < 4; ++ee) { const int e = dir ? 3 - ee : ee;
;                 const float r = __builtin_amdgcn_rcpf(1.f + __expf(-(ga[e] + bav))), ig = __builtin_amdgcn_rcpf(1.f + __expf(-(gx[e] + bxv)));
;                 const float la = -c8 * r; const float a = __expf(la); const float u = __builtin_amdgcn_sqrtf((1.f - a) * (1.f + a)) * (ig * xc[ct][e]);
;                 av[dir][ct][e] = a; uv[dir][ct][e] = u; Hl = a * Hl + u; Al *= a; }
;             const int o = dir ? 3 - fq : fq; const bool odd = (o & 1) != 0, hi2 = (o & 2) != 0;
;             const float A1 = __shfl_xor(Al, 16), H1 = __shfl_xor(Hl, 16);
;             const float pxA = odd ? A1 : 1.f, pxH = odd ? H1 : 0.f;
;             const float gA = Al * A1, gH = odd ? (Al * H1 + Hl) : (A1 * Hl + H1);
;             const float A2 = __shfl_xor(gA, 32), H2 = __shfl_xor(gH, 32);
;             const float PA = hi2 ? pxA * A2 : pxA, PH = hi2 ? (pxA * H2 + pxH) : pxH;
;             const float TA = gA * A2, TH = hi2 ? (gA * H2 + gH) : (A2 * gH + H2);
;             pA[dir][ct] = PA; pH[dir][ct] = PH;
;             ((LAS f32x2*)(lds + LR_SEG))[(dir * 8 + rt) * 64 + ch] = (f32x2){TA, TH};
	v_mul_f32_e32 v31, v1, v26
	s_waitcnt lgkmcnt(0)
	v_fma_f32 v1, v1, v29, v27
	v_fmac_f32_e32 v29, v27, v26
	v_cndmask_b32_e64 v1, v1, v29, s[46:47]
	ds_bpermute_b32 v27, v84, v31
	ds_bpermute_b32 v29, v84, v1
	s_waitcnt lgkmcnt(1)
	v_mul_f32_e32 v26, v31, v27
	s_waitcnt lgkmcnt(0)
	v_fma_f32 v31, v31, v29, v1
	v_fmac_f32_e32 v29, v1, v27
	v_cndmask_b32_e64 v27, v31, v29, s[48:49]
	ds_write_b64 v86, v[26:27] offset:62848
	s_waitcnt lgkmcnt(1)
	v_mfma_f32_16x16x32_bf16 v[44:47], v[14:17], v[198:201], 0
	ds_read_b32 v29, v93 offset:57984
	ds_read_b32 v31, v93 offset:58240
	ds_read_b32 v33, v93 offset:58496
	s_waitcnt lgkmcnt(5)
	v_mfma_f32_16x16x32_bf16 v[44:47], v[18:21], v[202:205], v[44:47]
	s_waitcnt lgkmcnt(4)
	v_mfma_f32_16x16x32_bf16 v[58:61], v[14:17], v[206:209], 0
	s_waitcnt lgkmcnt(3)
	v_mfma_f32_16x16x32_bf16 v[52:55], v[18:21], v[210:213], v[58:61]
	ds_read_b128 v[198:201], v23 offset:44288
	ds_read_b128 v[202:205], v23 offset:44352
	ds_read_b128 v[206:209], v23 offset:53504
	ds_read_b128 v[210:213], v23 offset:53568
	s_waitcnt lgkmcnt(2)
	s_nop 2
	v_add_f32_e32 v1, v47, v29
	v_mul_f32_e32 v1, 0xbfb8aa3b, v1
	v_exp_f32_e32 v1, v1
	s_nop 0
	v_add_f32_e32 v1, 1.0, v1
	v_rcp_f32_e32 v1, v1
	s_waitcnt lgkmcnt(1)
	v_add_f32_e32 v26, v55, v31
	v_mul_f32_e32 v26, 0xbfb8aa3b, v26
	v_exp_f32_e32 v27, v26
	s_waitcnt lgkmcnt(0)
	v_mul_f32_e32 v1, v1, v33
	v_mul_f32_e32 v1, 0xbfb8aa3b, v1
	v_exp_f32_e32 v26, v1
	v_add_f32_e32 v1, 1.0, v27
	v_rcp_f32_e32 v27, v1
	v_add_f32_e32 v37, v54, v31
	v_sub_f32_e32 v1, 1.0, v26
	v_add_f32_e32 v34, 1.0, v26
	v_mul_f32_e32 v1, v1, v34
	v_add_f32_e32 v34, v46, v29
	v_mul_f32_e32 v34, 0xbfb8aa3b, v34
	v_exp_f32_e32 v35, v34
	v_mul_f32_e32 v37, 0xbfb8aa3b, v37
	v_sqrt_f32_e32 v1, v1
	v_exp_f32_e32 v37, v37
	v_add_f32_e32 v35, 1.0, v35
	v_rcp_f32_e32 v35, v35
	v_mul_f32_e32 v27, v56, v27
	v_mul_f32_e32 v34, 0, v26
	v_mul_f32_e32 v35, v35, v33
	v_mul_f32_e32 v35, 0xbfb8aa3b, v35
	v_exp_f32_e32 v35, v35
	s_nop 0
	v_pk_fma_f32 v[40:41], v[26:27], v[0:1], v[34:35] op_sel_hi:[1,1,0]
	v_add_f32_e32 v1, 1.0, v37
	v_rcp_f32_e32 v34, v1
	v_sub_f32_e32 v1, 1.0, v35
	v_add_f32_e32 v27, 1.0, v35
	v_mul_f32_e32 v1, v1, v27
	v_add_f32_e32 v27, v45, v29
	v_mul_f32_e32 v27, 0xbfb8aa3b, v27
	v_sqrt_f32_e32 v1, v1
	v_exp_f32_e32 v27, v27
	v_mov_b32_e32 v51, v41
	v_pk_mul_f32 v[40:41], v[50:51], v[34:35]
	v_add_f32_e32 v29, v44, v29
	v_fmac_f32_e32 v41, v40, v1
	v_add_f32_e32 v1, 1.0, v27
	v_rcp_f32_e32 v1, v1
	v_add_f32_e32 v27, v53, v31
	v_mul_f32_e32 v27, 0xbfb8aa3b, v27
	v_exp_f32_e32 v34, v27
	v_mul_f32_e32 v1, v1, v33
	v_mul_f32_e32 v1, 0xbfb8aa3b, v1
	v_exp_f32_e32 v27, v1
	v_mul_f32_e32 v1, v26, v35
	v_add_f32_e32 v26, 1.0, v34
	v_mul_f32_e32 v29, 0xbfb8aa3b, v29
	v_rcp_f32_e32 v26, v26
	v_exp_f32_e32 v29, v29
	v_sub_f32_e32 v34, 1.0, v27
	v_add_f32_e32 v35, 1.0, v27
	v_mul_f32_e32 v34, v34, v35
	v_mov_b32_e32 v39, v41
	v_sqrt_f32_e32 v37, v34
	v_pk_mul_f32 v[34:35], v[38:39], v[26:27]
	v_add_f32_e32 v26, 1.0, v29
	v_rcp_f32_e32 v26, v26
	v_add_f32_e32 v29, v52, v31
	v_mul_f32_e32 v29, 0xbfb8aa3b, v29
	v_exp_f32_e32 v29, v29
	v_mul_f32_e32 v26, v26, v33
	v_mul_f32_e32 v26, 0xbfb8aa3b, v26
	v_exp_f32_e32 v39, v26
	v_add_f32_e32 v26, 1.0, v29
	v_rcp_f32_e32 v38, v26
	v_fmac_f32_e32 v35, v34, v37
	v_sub_f32_e32 v26, 1.0, v39
	v_add_f32_e32 v29, 1.0, v39
	v_mul_f32_e32 v26, v26, v29
	v_sqrt_f32_e32 v29, v26
	v_mov_b32_e32 v31, v35
	v_mul_f32_e32 v1, v27, v1
	v_pk_mul_f32 v[26:27], v[30:31], v[38:39]
	v_mul_f32_e32 v1, v39, v1
	v_fmac_f32_e32 v27, v26, v29
	ds_bpermute_b32 v26, v83, v1
	ds_bpermute_b32 v29, v83, v27
	s_waitcnt lgkmcnt(1)
	v_mul_f32_e32 v30, v1, v26
	s_waitcnt lgkmcnt(0)
	v_fma_f32 v1, v1, v29, v27
	v_fmac_f32_e32 v29, v27, v26
	v_cndmask_b32_e64 v1, v1, v29, s[46:47]
	ds_bpermute_b32 v27, v84, v30
	ds_bpermute_b32 v29, v84, v1
	s_waitcnt lgkmcnt(1)
	v_mul_f32_e32 v26, v30, v27
	s_waitcnt lgkmcnt(0)
	v_fma_f32 v30, v30, v29, v1
	v_fmac_f32_e32 v29, v1, v27
	v_cndmask_b32_e64 v27, v30, v29, s[48:49]
	ds_write_b64 v86, v[26:27] offset:62976
	s_waitcnt lgkmcnt(1)
	v_mfma_f32_16x16x32_bf16 v[38:41], v[14:17], v[198:201], 0
	ds_read_b32 v23, v93 offset:58048
	ds_read_b32 v26, v93 offset:58304
	ds_read_b32 v27, v93 offset:58560
	s_waitcnt lgkmcnt(5)
	v_mfma_f32_16x16x32_bf16 v[38:41], v[18:21], v[202:205], v[38:41]
	s_waitcnt lgkmcnt(4)
	v_mfma_f32_16x16x32_bf16 v[14:17], v[14:17], v[206:209], 0
	s_waitcnt lgkmcnt(3)
	v_mfma_f32_16x16x32_bf16 v[14:17], v[18:21], v[210:213], v[14:17]
	s_waitcnt lgkmcnt(2)
; #define LAS __attribute__((address_space(3)))
; template <bool PHASE_B>
; __device__ __forceinline__ void lru_item(const Params& p, LAS unsigned char* lds, int ci, int ci_next, int jb, const int tid, v4u (&xvn)[3]) {
;     ...
;                 const bf16x8 wa = *(const LAS bf16x8*)(lds + LR_WG + ((dir * 2 + 0) * 64 + 16 * ct + fr) * 144 + (32 * ks + 8 * fq) * 2);
;                 const bf16x8 wx = *(const LAS bf16x8*)(lds + LR_WG + ((dir * 2 + 1) * 64 + 16 * ct + fr) * 144 + (32 * ks + 8 * fq) * 2);
;                 ga = MFMA16(af[ks], wa, ga); gx = MFMA16(af[ks], wx, gx); }
;             const int ch = 16 * ct + fr; const float bav = GC[(dir * 3 + 0) * 64 + ch], bxv = GC[(dir * 3 + 1) * 64 + ch], c8 = GC[(dir * 3 + 2) * 64 + ch];
;             float Al = 1.f, Hl = 0.f;
; #pragma unroll
;             for (int ee = 0; ee < 4; ++ee) { const int e = dir ? 3 - ee : ee;
;                 const float r = __builtin_amdgcn_rcpf(1.f + __expf(-(ga[e] + bav))), ig = __builtin_amdgcn_rcpf(1.f + __expf(-(gx[e] + bxv)));
;                 const float la = -c8 * r; const float a = __expf(la); const float u = __builtin_amdgcn_sqrtf((1.f - a) * (1.f + a)) * (ig * xc[ct][e]);
;                 av[dir][ct][e] = a; uv[dir][ct][e] = u; Hl = a * Hl + u; Al *= a; }
;             const int o = dir ? 3 - fq : fq; const bool odd = (o & 1) != 0, hi2 = (o & 2) != 0;
;             const float A1 = __shfl_xor(Al, 16), H1 = __shfl_xor(Hl, 16);
;             const float pxA = odd ? A1 : 1.f, pxH = odd ? H1 : 0.f;
;             const float gA = Al * A1, gH = odd ? (Al * H1 + Hl) : (A1 * Hl + H1);
;             const float A2 = __shfl_xor(gA, 32), H2 = __shfl_xor(gH, 32);
;             const float PA = hi2 ? pxA * A2 : pxA, PH = hi2 ? (pxA * H2 + pxH) : pxH;
;             const float TA = gA * A2, TH = hi2 ? (gA * H2 + gH) : (A2 * gH + H2);
;             pA[dir][ct] = PA; pH[dir][ct] = PH;
;             ((LAS f32x2*)(lds + LR_SEG))[(dir * 8 + rt) * 64 + ch] = (f32x2){TA, TH};
;     ...
;         if (tid < 128) { const int dir = tid >> 6, ch = tid & 63; float A = 1.f, H = 0.f;
; #pragma unroll
;             for (int q = 0; q < 8; ++q) { const f32x2 sh = ((const LAS f32x2*)(lds + LR_SEG))[(dir * 8 + (dir ? 7 - q : q)) * 64 + ch]; H = sh.x * H + sh.y; A *= sh.x; }
;             ((f32x2*)(p.ws + WS_CAR))[(size_t)(ci * 2 + dir) * 768 + jb * 64 + ch] = (f32x2){A, H}; }
	s_nop 2
	v_add_f32_e32 v1, v41, v23
	v_mul_f32_e32 v1, 0xbfb8aa3b, v1
	v_exp_f32_e32 v1, v1
	s_nop 0
	v_add_f32_e32 v1, 1.0, v1
	v_rcp_f32_e32 v1, v1
	s_waitcnt lgkmcnt(1)
	v_add_f32_e32 v17, v17, v26
	v_mul_f32_e32 v17, 0xbfb8aa3b, v17
	v_exp_f32_e32 v17, v17
	s_waitcnt lgkmcnt(0)
	v_mul_f32_e32 v1, v1, v27
	v_mul_f32_e32 v1, 0xbfb8aa3b, v1
	v_exp_f32_e32 v18, v1
	v_add_f32_e32 v1, 1.0, v17
	v_rcp_f32_e32 v17, v1
	v_add_f32_e32 v16, v16, v26
	v_sub_f32_e32 v1, 1.0, v18
	v_add_f32_e32 v19, 1.0, v18
	v_mul_f32_e32 v1, v1, v19
	v_add_f32_e32 v19, v40, v23
	v_mul_f32_e32 v19, 0xbfb8aa3b, v19
	v_exp_f32_e32 v21, v19
	v_mul_f32_e32 v19, v28, v17
	v_mul_f32_e32 v16, 0xbfb8aa3b, v16
	v_sqrt_f32_e32 v1, v1
	v_add_f32_e32 v17, 1.0, v21
	v_rcp_f32_e32 v17, v17
	v_exp_f32_e32 v16, v16
	v_mul_f32_e32 v20, 0, v18
	v_pk_fma_f32 v[20:21], v[18:19], v[0:1], v[20:21] op_sel_hi:[1,1,0]
	v_mul_f32_e32 v17, v17, v27
	v_mul_f32_e32 v17, 0xbfb8aa3b, v17
	v_exp_f32_e32 v17, v17
	v_add_f32_e32 v1, 1.0, v16
	v_rcp_f32_e32 v16, v1
	v_mov_b32_e32 v43, v21
	v_sub_f32_e32 v1, 1.0, v17
	v_add_f32_e32 v19, 1.0, v17
	v_mul_f32_e32 v1, v1, v19
	v_add_f32_e32 v19, v39, v23
	v_mul_f32_e32 v19, 0xbfb8aa3b, v19
	v_sqrt_f32_e32 v1, v1
	v_exp_f32_e32 v19, v19
	v_pk_mul_f32 v[20:21], v[42:43], v[16:17]
	v_add_f32_e32 v15, v15, v26
	v_fmac_f32_e32 v21, v20, v1
	v_add_f32_e32 v1, 1.0, v19
	v_rcp_f32_e32 v1, v1
	v_mul_f32_e32 v15, 0xbfb8aa3b, v15
	v_exp_f32_e32 v15, v15
	v_add_f32_e32 v14, v14, v26
	v_mul_f32_e32 v1, v1, v27
	v_mul_f32_e32 v1, 0xbfb8aa3b, v1
	v_exp_f32_e32 v19, v1
	v_add_f32_e32 v15, 1.0, v15
	v_mul_f32_e32 v1, v18, v17
	v_rcp_f32_e32 v18, v15
	v_sub_f32_e32 v15, 1.0, v19
	v_add_f32_e32 v16, 1.0, v19
	v_mul_f32_e32 v15, v15, v16
	v_add_f32_e32 v16, v38, v23
	v_mul_f32_e32 v16, 0xbfb8aa3b, v16
	v_exp_f32_e32 v20, v16
	v_sqrt_f32_e32 v23, v15
	v_mul_f32_e32 v14, 0xbfb8aa3b, v14
	v_exp_f32_e32 v14, v14
	v_add_f32_e32 v15, 1.0, v20
	v_rcp_f32_e32 v15, v15
	v_mov_b32_e32 v37, v21
	v_pk_mul_f32 v[16:17], v[36:37], v[18:19]
	v_add_f32_e32 v14, 1.0, v14
	v_mul_f32_e32 v15, v15, v27
	v_mul_f32_e32 v15, 0xbfb8aa3b, v15
	v_exp_f32_e32 v15, v15
	v_fmac_f32_e32 v17, v16, v23
	v_rcp_f32_e32 v14, v14
	v_mov_b32_e32 v33, v17
	v_sub_f32_e32 v16, 1.0, v15
	v_add_f32_e32 v18, 1.0, v15
	v_mul_f32_e32 v16, v16, v18
	v_sqrt_f32_e32 v18, v16
	v_mul_f32_e32 v1, v19, v1
	v_pk_mul_f32 v[16:17], v[32:33], v[14:15]
	v_mul_f32_e32 v1, v15, v1
	v_fmac_f32_e32 v17, v16, v18
	ds_bpermute_b32 v14, v83, v1
	ds_bpermute_b32 v15, v83, v17
	s_waitcnt lgkmcnt(1)
	v_mul_f32_e32 v16, v1, v14
	s_waitcnt lgkmcnt(0)
	v_fma_f32 v1, v1, v15, v17
	v_fmac_f32_e32 v15, v17, v14
	v_cndmask_b32_e64 v1, v1, v15, s[46:47]
	ds_bpermute_b32 v15, v84, v16
	ds_bpermute_b32 v17, v84, v1
	s_waitcnt lgkmcnt(1)
	v_mul_f32_e32 v14, v16, v15
	s_waitcnt lgkmcnt(0)
	v_fma_f32 v16, v16, v17, v1
	v_fmac_f32_e32 v17, v1, v15
	v_cndmask_b32_e64 v15, v16, v17, s[48:49]
	ds_write_b64 v86, v[14:15] offset:63104
	s_waitcnt vmcnt(0) lgkmcnt(0)
	s_barrier
	s_and_saveexec_b64 s[12:13], s[50:51]
	s_cbranch_execz .LBB0_528
	ds_read_b64 v[14:15], v94 offset:58624
	ds_read_b64 v[16:17], v95 offset:58624
	ds_read_b64 v[18:19], v96 offset:58624
	ds_read_b64 v[20:21], v97 offset:58624
	s_waitcnt lgkmcnt(3)
	v_fma_f32 v1, 0, v14, v15
	s_waitcnt lgkmcnt(2)
	v_pk_mul_f32 v[14:15], v[14:15], v[16:17]
	v_fmac_f32_e32 v17, v16, v1
	s_waitcnt lgkmcnt(1)
	v_fma_f32 v1, v18, v17, v19
	ds_read_b64 v[16:17], v98 offset:58624
	ds_read_b64 v[26:27], v99 offset:58624
	ds_read_b64 v[28:29], v100 offset:58624
	ds_read_b64 v[30:31], v101 offset:58624
	s_waitcnt lgkmcnt(4)
	v_fma_f32 v1, v20, v1, v21
	v_mov_b32_e32 v32, v14
	v_mov_b32_e32 v34, v18
	s_waitcnt lgkmcnt(3)
	v_fma_f32 v33, v16, v1, v17
	s_waitcnt lgkmcnt(2)
	v_mov_b32_e32 v35, v26
	v_pk_mul_f32 v[14:15], v[14:15], v[18:19]
	v_pk_fma_f32 v[18:19], v[32:33], v[34:35], v[26:27]
	v_pk_mul_f32 v[14:15], v[14:15], v[20:21]
	s_waitcnt lgkmcnt(1)
	v_mov_b32_e32 v17, v28
	v_mov_b32_e32 v15, v19
	v_pk_mul_f32 v[18:19], v[14:15], v[16:17]
	v_pk_fma_f32 v[14:15], v[14:15], v[16:17], v[28:29]
	v_pk_mul_f32 v[18:19], v[18:19], v[26:27]
	v_mov_b32_e32 v16, v28
	v_mov_b32_e32 v14, v18
	s_waitcnt lgkmcnt(0)
	v_mov_b32_e32 v17, v30
	v_pk_mul_f32 v[18:19], v[18:19], v[28:29]
	v_pk_fma_f32 v[14:15], v[14:15], v[16:17], v[30:31]
	v_pk_mul_f32 v[18:19], v[18:19], v[30:31]
	s_nop 0
	v_mov_b32_e32 v19, v15
	v_mad_i64_i32 v[14:15], s[60:61], v87, s64, v[24:25]
	global_store_dwordx2 v[14:15], v[18:19], off
	s_branch .LBB0_528
